# final RMSNorm fused into the last down-GEMM epilogue (row sums exchanged by f32 atomics among the 4 column-tile workgroups); static ctx SG units; resid epilogues batched; attn stagger
# speedup vs baseline: 1.0154x; 1.0117x over previous
; __device__ __forceinline__ int wq_next(unsigned* cnt, int lane) { unsigned v = 0u; if (lane == 0) v = atomicAdd(cnt, 1u); return (int)__builtin_amdgcn_readfirstlane(v); }
; #define KIN(i) KPTR(const float, i)
; template <int L> __device__ __forceinline__ void layer_fwd(cg::grid_group& grid, LAS unsigned char* lds) {
;     ...
;         unsigned* cnt_sg = (unsigned*)(ws + CTL_CNT) + 64 * (2 * L + 1);
;         const bf16_t* VSTp = (const bf16_t*)(ws + WS_VST); const bf16_t* QUp = (const bf16_t*)(ws + WS_QU); bf16_t* OBp = (bf16_t*)(ws + WS_H); const float* stp = (const float*)(ws + STL); const bf16_t* wsb = (const bf16_t*)(ws + WL + W_S);
;         for (int u = gw; u < 2048; u += NGW) sg_unit<4>(u >> 3, (u >> 1) & 3, (u & 1) * 64, VSTp, QUp, OBp, stp, KIN(12) + L * 512, KIN(13) + L * 512, wsb, KIN(15) + L * 512, lane);
;         if (L == 0)
;             for (;;) { const int u = wq_next(cnt_sg, lane); if (u >= 64) break; sg_unit<2>(256 + (u >> 4), (u >> 2) & 3, (u & 3) * 32, VSTp, QUp, OBp, stp, KIN(12) + L * 512, KIN(13) + L * 512, wsb, KIN(15) + L * 512, lane); }
.LBB0_964:
	v_readfirstlane_b32 s100, v206
	s_nop 0
	s_cmp_eq_u32 s100, 0
	s_cselect_b32 s100, s2, 64
	s_min_u32 s100, s100, 64
	v_mbcnt_hi_u32_b32 v202, -1, v212
	s_add_u32 s40, s40, 0xc2100
	v_and_b32_e32 v205, 64, v202
	s_addc_u32 s41, s41, 0
	s_mov_b32 s43, 0
	v_cmp_eq_u32_e64 s[4:5], 0, v161
	v_mov_b32_e32 v113, 0
	s_mov_b32 s51, 0x8000
	s_mov_b64 s[44:45], 0x8000
	s_mov_b64 s[46:47], 0x10000
	s_mov_b32 s55, 0x10000
	s_mov_b64 s[48:49], 0x18000
	s_mov_b32 s56, 0x18000
	s_mov_b32 s50, 0x3b000000
	s_mov_b32 s57, 0xf800000
	v_mov_b32_e32 v125, 0x260
	s_movk_i32 s58, 0x1000
	s_movk_i32 s59, 0x2000
	v_mov_b32_e32 v114, 0x3b000000
	v_xor_b32_e32 v204, 16, v202
	v_add_u32_e32 v203, 64, v205
	s_branch .LBB0_967

; template <int NMT> __device__ __forceinline__ void sg_unit(int chunk, int g, int cofs, const bf16_t* VST, const bf16_t* QU, bf16_t* OB, const float* stats, const float* lng, const float* lnb, const bf16_t* WSb, const float* bs, int lane_) {
;     int lane = lane_; asm volatile("" : "+v"(lane));
;     const int fr = lane & 15, fq = lane >> 4;
;     const int R0 = chunk < 256 ? chunk * 128 : MX + (chunk - 256) * 128;
;     const int ch0 = g * 128 + cofs;
;     u32x4 raw[NMT][4]; pg8::f32x2 sv[4][8];
; #pragma unroll
;     for (int ks = 0; ks < 4; ++ks) {
; #pragma unroll
;         for (int j = 0; j < 8; ++j) sv[ks][j] = *(const pg8::f32x2*)(stats + 2 * (size_t)(R0 + ks * 32 + 8 * fq + j));
; #pragma unroll
;         for (int mt = 0; mt < NMT; ++mt) raw[mt][ks] = *(const u32x4*)(VST + ((size_t)((R0 >> 3) + ks * 4 + fq) * 512 + ch0 + mt * 16 + fr) * 8);
;     }
;     float lg[NMT], lb[NMT];
; #pragma unroll
;     for (int mt = 0; mt < NMT; ++mt) { lg[mt] = lng[ch0 + mt * 16 + fr]; lb[mt] = lnb[ch0 + mt * 16 + fr]; }
;     const bf16_t* wp0 = WSb + (size_t)(g * 128 + fr) * 128 + 8 * fq;
;     bf16x8 wf[2][4]; u32x2 uu[2][NMT]; float bsv[2];
; #pragma unroll
;     for (int ks = 0; ks < 4; ++ks) wf[0][ks] = *(const bf16x8*)(wp0 + ks * 32);
; #pragma unroll
;     for (int mt = 0; mt < NMT; ++mt) uu[0][mt] = *(const u32x2*)(QU + (size_t)(R0 + fr) * 1024 + 512 + ch0 + mt * 16 + 4 * fq);
;     bsv[0] = bs[g * 128 + fr];
;     __builtin_amdgcn_sched_barrier(0);
;     bf16x8 af[NMT][4];
; #pragma unroll
;     for (int ks = 0; ks < 4; ++ks) {
;         float mu[8], rs[8];
; #pragma unroll
;         for (int j = 0; j < 8; ++j) { const float mean = sv[ks][j][0] * (1.0f / 512.0f); const float var = fmaxf(sv[ks][j][1] * (1.0f / 512.0f) - mean * mean, 0.f); mu[j] = mean; rs[j] = 1.0f / sqrtf(var + EPS); }
.LBB0_967:
	s_mov_b32 s6, s100
	s_mov_b32 s100, 64
	s_cmp_gt_i32 s6, 63
	s_mov_b64 s[10:11], -1
	s_cbranch_scc1 .LBB0_966
	s_lshl_b32 s7, s6, 5
	s_lshl_b32 s6, s6, 3
	s_and_b32 s6, s6, 0xffffff80
	v_mov_b32_e32 v129, v161
	s_add_i32 s6, s6, 0x8000
	s_load_dwordx4 s[12:15], s[20:21], 0x60
	s_load_dwordx2 s[52:53], s[20:21], 0x78
	s_ashr_i32 s9, s6, 3
	v_ashrrev_i32_e32 v116, 4, v129
	v_lshlrev_b32_e32 v0, 3, v116
	v_add_u32_e32 v2, s9, v116
	v_and_b32_e32 v115, 15, v129
	s_and_b32 s8, s7, 0x180
	s_and_b32 s7, s7, 0x1e0
	v_add_u32_e32 v6, s6, v0
	v_ashrrev_i32_e32 v3, 31, v2
	v_or_b32_e32 v1, s7, v115
	v_lshlrev_b64 v[2:3], 13, v[2:3]
	v_add_u32_e32 v8, 32, v6
	v_ashrrev_i32_e32 v7, 31, v6
	v_lshlrev_b32_e32 v112, 4, v1
	v_lshl_add_u64 v[2:3], s[22:23], 0, v[2:3]
	v_ashrrev_i32_e32 v9, 31, v8
	v_lshl_add_u64 v[4:5], v[6:7], 3, s[36:37]
	v_lshl_add_u64 v[12:13], v[2:3], 0, v[112:113]
	v_lshl_add_u64 v[8:9], v[8:9], 3, s[36:37]
	global_load_dwordx4 v[100:103], v[4:5], off offset:48
	global_load_dwordx4 v[104:107], v[4:5], off offset:32
	global_load_dwordx4 v[108:111], v[4:5], off offset:16
	global_load_dwordx4 v[140:143], v[4:5], off
	global_load_dwordx4 v[96:99], v[12:13], off
	s_nop 0
	global_load_dwordx4 v[2:5], v[12:13], off offset:256
	global_load_dwordx4 v[80:83], v[8:9], off offset:48
	global_load_dwordx4 v[84:87], v[8:9], off offset:32
	global_load_dwordx4 v[88:91], v[8:9], off offset:16
	global_load_dwordx4 v[92:95], v[8:9], off
	v_add_co_u32_e32 v8, vcc, s51, v12
	v_lshl_add_u64 v[14:15], v[12:13], 0, s[44:45]
	s_nop 0
	v_addc_co_u32_e32 v9, vcc, 0, v13, vcc
	global_load_dwordx4 v[8:11], v[8:9], off
	s_nop 0
	global_load_dwordx4 v[36:39], v[14:15], off offset:256
	v_add_u32_e32 v14, 64, v6
	v_add_u32_e32 v6, 0x60, v6
	v_ashrrev_i32_e32 v15, 31, v14
	v_add_co_u32_e32 v16, vcc, s55, v12
	v_ashrrev_i32_e32 v7, 31, v6
	v_lshl_add_u64 v[14:15], v[14:15], 3, s[36:37]
	v_addc_co_u32_e32 v17, vcc, 0, v13, vcc
	v_lshl_add_u64 v[6:7], v[6:7], 3, s[36:37]
	global_load_dwordx4 v[64:67], v[14:15], off offset:48
	global_load_dwordx4 v[68:71], v[14:15], off offset:32
	global_load_dwordx4 v[72:75], v[14:15], off offset:16
	global_load_dwordx4 v[76:79], v[14:15], off
	v_lshl_add_u64 v[14:15], v[12:13], 0, s[46:47]
	global_load_dwordx4 v[44:47], v[16:17], off
	global_load_dwordx4 v[60:63], v[14:15], off offset:256
	global_load_dwordx4 v[40:43], v[6:7], off offset:48
	global_load_dwordx4 v[48:51], v[6:7], off offset:32
	global_load_dwordx4 v[52:55], v[6:7], off offset:16
	global_load_dwordx4 v[56:59], v[6:7], off
	v_lshl_add_u64 v[6:7], v[12:13], 0, s[48:49]
	v_add_co_u32_e32 v12, vcc, s56, v12
	v_or_b32_e32 v124, s8, v115
	v_or_b32_e32 v118, s6, v115
	v_addc_co_u32_e32 v13, vcc, 0, v13, vcc
	v_lshlrev_b32_e32 v1, 2, v1
	v_lshlrev_b32_e32 v112, 8, v124
	v_ashrrev_i32_e32 v119, 31, v118
	global_load_dwordx4 v[20:23], v[12:13], off
	s_nop 0
	global_load_dwordx4 v[12:15], v[6:7], off offset:256
	s_waitcnt lgkmcnt(0)
	global_load_dword v132, v1, s[12:13]
	global_load_dword v134, v1, s[14:15]
	global_load_dword v128, v1, s[12:13] offset:64
	global_load_dword v130, v1, s[14:15] offset:64
	v_lshl_add_u64 v[6:7], s[38:39], 0, v[112:113]
	v_ashrrev_i32_e32 v1, 31, v0
	v_lshlrev_b64 v[122:123], 11, v[118:119]
	v_lshlrev_b32_e32 v116, 2, v116
	v_lshl_add_u64 v[120:121], v[0:1], 1, v[6:7]
	v_lshl_add_u64 v[0:1], s[26:27], 0, v[122:123]
	s_lshl_b32 s42, s7, 1
	v_ashrrev_i32_e32 v117, 31, v116
	global_load_dwordx4 v[32:35], v[120:121], off
	global_load_dwordx4 v[28:31], v[120:121], off offset:64
	global_load_dwordx4 v[24:27], v[120:121], off offset:128
	global_load_dwordx4 v[16:19], v[120:121], off offset:192
	v_lshl_add_u64 v[0:1], v[0:1], 0, s[42:43]
	v_lshlrev_b64 v[138:139], 1, v[116:117]
	v_lshl_add_u64 v[0:1], v[0:1], 0, v[138:139]
	global_load_dwordx2 v[136:137], v[0:1], off offset:1024
	global_load_dwordx2 v[126:127], v[0:1], off offset:1056
	v_lshlrev_b32_e32 v112, 2, v124
	global_load_dword v124, v112, s[52:53]
	s_waitcnt vmcnt(31)
	v_mov_b32_e32 v6, v140
	v_mov_b32_e32 v7, v142
	v_pk_mul_f32 v[0:1], v[6:7], s[50:51] op_sel_hi:[1,0]
	v_mov_b32_e32 v144, v108
	v_pk_mov_b32 v[140:141], v[140:141], v[0:1] op_sel:[1,0]
	v_mov_b32_e32 v115, v0
	v_pk_mul_f32 v[140:141], v[140:141], v[114:115]
	v_mov_b32_e32 v145, v110
	v_sub_f32_e32 v0, v140, v141
	v_max_f32_e32 v0, 0, v0
	v_add_f32_e32 v0, 0x358637bd, v0
	v_mul_f32_e32 v115, 0x4f800000, v0
	v_cmp_gt_f32_e32 vcc, s57, v0
	v_pk_mul_f32 v[146:147], v[144:145], s[50:51] op_sel_hi:[1,0]
	s_waitcnt vmcnt(29)
; __device__ __forceinline__ float bflo(unsigned w) { return __uint_as_float(w << 16); }
; __device__ __forceinline__ float bfhi(unsigned w) { return __uint_as_float(w & 0xffff0000u); }
; __device__ __forceinline__ unsigned cvtpk_s(float lo, float hi) { f32x2_t v = {lo, hi}; bf16x2_t b = __builtin_convertvector(v, bf16x2_t); return __builtin_bit_cast(unsigned, b); }
; template <int NMT> __device__ __forceinline__ void sg_unit(int chunk, int g, int cofs, const bf16_t* VST, const bf16_t* QU, bf16_t* OB, const float* stats, const float* lng, const float* lnb, const bf16_t* WSb, const float* bs, int lane_) {
;     ...
;     for (int ks = 0; ks < 4; ++ks) {
;         float mu[8], rs[8];
; #pragma unroll
;         for (int j = 0; j < 8; ++j) { const float mean = sv[ks][j][0] * (1.0f / 512.0f); const float var = fmaxf(sv[ks][j][1] * (1.0f / 512.0f) - mean * mean, 0.f); mu[j] = mean; rs[j] = 1.0f / sqrtf(var + EPS); }
; #pragma unroll
;         for (int mt = 0; mt < NMT; ++mt) {
;             const u32x4 rw = raw[mt][ks];
;             float v[8]; v[0] = pg8::bflo(rw.x); v[1] = pg8::bfhi(rw.x); v[2] = pg8::bflo(rw.y); v[3] = pg8::bfhi(rw.y); v[4] = pg8::bflo(rw.z); v[5] = pg8::bfhi(rw.z); v[6] = pg8::bflo(rw.w); v[7] = pg8::bfhi(rw.w);
; #pragma unroll
;             for (int j = 0; j < 8; ++j) v[j] = (v[j] - mu[j]) * rs[j] * lg[mt] + lb[mt];
;             u32x4 pw; pw.x = cvtpk_s(v[0], v[1]); pw.y = cvtpk_s(v[2], v[3]); pw.z = cvtpk_s(v[4], v[5]); pw.w = cvtpk_s(v[6], v[7]);
;             af[mt][ks] = __builtin_bit_cast(bf16x8, pw);
;         }
	v_lshlrev_b32_e32 v142, 16, v2
	v_cndmask_b32_e32 v119, v0, v115, vcc
	v_sqrt_f32_e32 v0, v119
	v_pk_mov_b32 v[108:109], v[108:109], v[146:147] op_sel:[1,0]
	v_add_u32_e32 v115, -1, v0
	v_fma_f32 v131, -v115, v0, v119
	v_cmp_ge_f32_e64 s[10:11], 0, v131
	v_add_u32_e32 v133, 1, v0
	v_fma_f32 v135, -v133, v0, v119
	v_cndmask_b32_e64 v131, v0, v115, s[10:11]
	v_mov_b32_e32 v0, v143
	v_mov_b32_e32 v115, v1
	v_pk_mul_f32 v[0:1], v[0:1], v[114:115]
	v_cmp_lt_f32_e64 s[12:13], 0, v135
	v_sub_f32_e32 v0, v0, v1
	v_max_f32_e32 v0, 0, v0
	v_add_f32_e32 v0, 0x358637bd, v0
	v_mul_f32_e32 v1, 0x4f800000, v0
	v_cmp_gt_f32_e64 s[10:11], s57, v0
	v_cndmask_b32_e64 v115, v131, v133, s[12:13]
	v_mul_f32_e32 v131, 0x37800000, v115
	v_cndmask_b32_e64 v0, v0, v1, s[10:11]
	v_sqrt_f32_e32 v1, v0
	v_cndmask_b32_e32 v115, v115, v131, vcc
	v_cmp_class_f32_e32 vcc, v119, v125
	v_and_b32_e32 v143, 0xffff0000, v2
	v_add_u32_e32 v133, -1, v1
	v_fma_f32 v135, -v133, v1, v0
	v_cmp_ge_f32_e64 s[12:13], 0, v135
	v_add_u32_e32 v135, 1, v1
	v_cndmask_b32_e32 v115, v115, v119, vcc
	v_cndmask_b32_e64 v133, v1, v133, s[12:13]
	v_fma_f32 v1, -v135, v1, v0
	v_cmp_lt_f32_e64 s[12:13], 0, v1
	s_nop 1
	v_cndmask_b32_e64 v1, v133, v135, s[12:13]
	v_mul_f32_e32 v133, 0x37800000, v1
	v_cndmask_b32_e64 v1, v1, v133, s[10:11]
	v_cmp_class_f32_e64 s[10:11], v0, v125
	s_nop 1
	v_cndmask_b32_e64 v0, v1, v0, s[10:11]
	v_div_scale_f32 v1, s[6:7], v0, v0, 1.0
	v_rcp_f32_e32 v133, v1
	s_nop 0
	v_fma_f32 v119, -v1, v133, 1.0
	v_fmac_f32_e32 v133, v119, v133
	v_div_scale_f32 v119, vcc, 1.0, v0, 1.0
	v_mul_f32_e32 v131, v119, v133
	v_fma_f32 v135, -v1, v131, v119
	v_fmac_f32_e32 v131, v135, v133
	v_fma_f32 v1, -v1, v131, v119
	v_div_scale_f32 v119, s[6:7], v115, v115, 1.0
	v_rcp_f32_e32 v135, v119
	v_div_fmas_f32 v1, v1, v133, v131
	v_div_fixup_f32 v141, v1, v0, 1.0
	v_fma_f32 v0, -v119, v135, 1.0
	v_fmac_f32_e32 v135, v0, v135
	v_div_scale_f32 v0, vcc, 1.0, v115, 1.0
	v_mul_f32_e32 v1, v0, v135
	v_fma_f32 v131, -v119, v1, v0
	v_fmac_f32_e32 v1, v131, v135
	v_fma_f32 v0, -v119, v1, v0
	v_div_fmas_f32 v0, v0, v135, v1
	v_div_fixup_f32 v140, v0, v115, 1.0
	v_lshlrev_b32_e32 v0, 16, v96
	v_and_b32_e32 v1, 0xffff0000, v96
	v_pk_fma_f32 v[0:1], v[6:7], s[50:51], v[0:1] op_sel_hi:[1,0,1] neg_lo:[1,0,0] neg_hi:[1,0,0]
	v_mov_b32_e32 v115, v146
	v_pk_mul_f32 v[0:1], v[140:141], v[0:1]
	v_pk_mul_f32 v[108:109], v[108:109], v[114:115]
	s_waitcnt vmcnt(9)
	v_pk_fma_f32 v[0:1], v[0:1], v[132:133], v[134:135] op_sel_hi:[1,0,0]
	v_mov_b32_e32 v146, v111
	v_cvt_pk_bf16_f32 v0, v0, v1
	v_sub_f32_e32 v1, v108, v109
	v_max_f32_e32 v1, 0, v1
	v_add_f32_e32 v1, 0x358637bd, v1
	v_mul_f32_e32 v2, 0x4f800000, v1
	v_cmp_gt_f32_e32 vcc, s57, v1
	v_mov_b32_e32 v115, v147
	v_pk_fma_f32 v[6:7], v[6:7], s[50:51], v[142:143] op_sel_hi:[1,0,1] neg_lo:[1,0,0] neg_hi:[1,0,0]
	v_cndmask_b32_e32 v1, v1, v2, vcc
	v_sqrt_f32_e32 v2, v1
	v_pk_mul_f32 v[6:7], v[140:141], v[6:7]
	v_add_u32_e32 v96, -1, v2
	v_fma_f32 v108, -v96, v2, v1
	v_cmp_ge_f32_e64 s[10:11], 0, v108
	v_pk_mul_f32 v[108:109], v[146:147], v[114:115]
	v_add_u32_e32 v110, 1, v2
	v_sub_f32_e32 v108, v108, v109
	v_max_f32_e32 v108, 0, v108
	v_add_f32_e32 v108, 0x358637bd, v108
	v_cndmask_b32_e64 v96, v2, v96, s[10:11]
	v_mul_f32_e32 v109, 0x4f800000, v108
	v_cmp_gt_f32_e64 s[10:11], s57, v108
	v_fma_f32 v2, -v110, v2, v1
	v_cmp_lt_f32_e64 s[12:13], 0, v2
	v_cndmask_b32_e64 v108, v108, v109, s[10:11]
	v_sqrt_f32_e32 v109, v108
	v_cndmask_b32_e64 v2, v96, v110, s[12:13]
	v_mul_f32_e32 v96, 0x37800000, v2
	v_cndmask_b32_e32 v2, v2, v96, vcc
	v_add_u32_e32 v110, -1, v109
	v_fma_f32 v111, -v110, v109, v108
	v_cmp_ge_f32_e64 s[12:13], 0, v111
	v_add_u32_e32 v111, 1, v109
	v_cmp_class_f32_e32 vcc, v1, v125
	v_cndmask_b32_e64 v110, v109, v110, s[12:13]
	v_fma_f32 v109, -v111, v109, v108
	v_cmp_lt_f32_e64 s[12:13], 0, v109
	v_cndmask_b32_e32 v1, v2, v1, vcc
	s_waitcnt vmcnt(7)
	v_pk_fma_f32 v[6:7], v[6:7], v[128:129], v[130:131] op_sel_hi:[1,0,0]
	v_cndmask_b32_e64 v109, v110, v111, s[12:13]
	v_mul_f32_e32 v110, 0x37800000, v109
	v_cndmask_b32_e64 v109, v109, v110, s[10:11]
	v_cmp_class_f32_e64 s[10:11], v108, v125
	s_nop 1
	v_cndmask_b32_e64 v108, v109, v108, s[10:11]
	v_div_scale_f32 v109, s[6:7], v108, v108, 1.0
	v_rcp_f32_e32 v110, v109
	s_nop 0
	v_fma_f32 v2, -v109, v110, 1.0
	v_fmac_f32_e32 v110, v2, v110
	v_div_scale_f32 v2, vcc, 1.0, v108, 1.0
	v_mul_f32_e32 v96, v2, v110
	v_fma_f32 v111, -v109, v96, v2
	v_fmac_f32_e32 v96, v111, v110
	v_div_scale_f32 v111, s[6:7], v1, v1, 1.0
	v_rcp_f32_e32 v115, v111
	v_fma_f32 v2, -v109, v96, v2
	v_div_fmas_f32 v2, v2, v110, v96
	v_div_fixup_f32 v109, v2, v108, 1.0
	v_fma_f32 v2, -v111, v115, 1.0
	v_fmac_f32_e32 v115, v2, v115
	v_div_scale_f32 v2, vcc, 1.0, v1, 1.0
	v_mul_f32_e32 v96, v2, v115
	v_fma_f32 v108, -v111, v96, v2
	v_fmac_f32_e32 v96, v108, v115
	v_fma_f32 v2, -v111, v96, v2
	v_div_fmas_f32 v2, v2, v115, v96
	v_lshlrev_b32_e32 v96, 16, v97
	v_and_b32_e32 v97, 0xffff0000, v97
	v_div_fixup_f32 v108, v2, v1, 1.0
	v_pk_fma_f32 v[96:97], v[144:145], s[50:51], v[96:97] op_sel_hi:[1,0,1] neg_lo:[1,0,0] neg_hi:[1,0,0]
	v_lshlrev_b32_e32 v2, 16, v3
	v_pk_mul_f32 v[96:97], v[108:109], v[96:97]
	v_and_b32_e32 v3, 0xffff0000, v3
	v_pk_fma_f32 v[96:97], v[96:97], v[132:133], v[134:135] op_sel_hi:[1,0,0]
	v_pk_fma_f32 v[2:3], v[144:145], s[50:51], v[2:3] op_sel_hi:[1,0,1] neg_lo:[1,0,0] neg_hi:[1,0,0]
	v_cvt_pk_bf16_f32 v1, v96, v97
	v_mov_b32_e32 v96, v104
	v_mov_b32_e32 v97, v106
	v_pk_mul_f32 v[110:111], v[96:97], s[50:51] op_sel_hi:[1,0]
	v_pk_mul_f32 v[2:3], v[108:109], v[2:3]
	v_pk_mov_b32 v[104:105], v[104:105], v[110:111] op_sel:[1,0]
; __device__ __forceinline__ float bflo(unsigned w) { return __uint_as_float(w << 16); }
; __device__ __forceinline__ float bfhi(unsigned w) { return __uint_as_float(w & 0xffff0000u); }
; __device__ __forceinline__ unsigned cvtpk_s(float lo, float hi) { f32x2_t v = {lo, hi}; bf16x2_t b = __builtin_convertvector(v, bf16x2_t); return __builtin_bit_cast(unsigned, b); }
; template <int NMT> __device__ __forceinline__ void sg_unit(int chunk, int g, int cofs, const bf16_t* VST, const bf16_t* QU, bf16_t* OB, const float* stats, const float* lng, const float* lnb, const bf16_t* WSb, const float* bs, int lane_) {
;     ...
;     for (int ks = 0; ks < 4; ++ks) {
;         float mu[8], rs[8];
; #pragma unroll
;         for (int j = 0; j < 8; ++j) { const float mean = sv[ks][j][0] * (1.0f / 512.0f); const float var = fmaxf(sv[ks][j][1] * (1.0f / 512.0f) - mean * mean, 0.f); mu[j] = mean; rs[j] = 1.0f / sqrtf(var + EPS); }
; #pragma unroll
;         for (int mt = 0; mt < NMT; ++mt) {
;             const u32x4 rw = raw[mt][ks];
;             float v[8]; v[0] = pg8::bflo(rw.x); v[1] = pg8::bfhi(rw.x); v[2] = pg8::bflo(rw.y); v[3] = pg8::bfhi(rw.y); v[4] = pg8::bflo(rw.z); v[5] = pg8::bfhi(rw.z); v[6] = pg8::bflo(rw.w); v[7] = pg8::bfhi(rw.w);
; #pragma unroll
;             for (int j = 0; j < 8; ++j) v[j] = (v[j] - mu[j]) * rs[j] * lg[mt] + lb[mt];
;             u32x4 pw; pw.x = cvtpk_s(v[0], v[1]); pw.y = cvtpk_s(v[2], v[3]); pw.z = cvtpk_s(v[4], v[5]); pw.w = cvtpk_s(v[6], v[7]);
;             af[mt][ks] = __builtin_bit_cast(bf16x8, pw);
;         }
	v_mov_b32_e32 v115, v110
	v_pk_mul_f32 v[104:105], v[104:105], v[114:115]
	v_mov_b32_e32 v115, v111
	v_sub_f32_e32 v104, v104, v105
	v_max_f32_e32 v104, 0, v104
	v_add_f32_e32 v104, 0x358637bd, v104
	v_mul_f32_e32 v105, 0x4f800000, v104
	v_cmp_gt_f32_e32 vcc, s57, v104
	s_nop 1
	v_cndmask_b32_e32 v106, v104, v105, vcc
	v_sqrt_f32_e32 v110, v106
	v_pk_fma_f32 v[104:105], v[2:3], v[128:129], v[130:131] op_sel_hi:[1,0,0]
	v_add_u32_e32 v2, -1, v110
	v_fma_f32 v3, -v2, v110, v106
	v_cmp_ge_f32_e64 s[10:11], 0, v3
	v_add_u32_e32 v109, 1, v110
	v_fma_f32 v119, -v109, v110, v106
	v_cndmask_b32_e64 v108, v110, v2, s[10:11]
	v_mov_b32_e32 v110, v107
	v_pk_mul_f32 v[2:3], v[110:111], v[114:115]
	v_cmp_lt_f32_e64 s[12:13], 0, v119
	v_sub_f32_e32 v2, v2, v3
	v_max_f32_e32 v2, 0, v2
	v_add_f32_e32 v2, 0x358637bd, v2
	v_mul_f32_e32 v3, 0x4f800000, v2
	v_cmp_gt_f32_e64 s[10:11], s57, v2
	v_cndmask_b32_e64 v107, v108, v109, s[12:13]
	v_mul_f32_e32 v108, 0x37800000, v107
	v_cndmask_b32_e64 v2, v2, v3, s[10:11]
	v_sqrt_f32_e32 v3, v2
	v_cndmask_b32_e32 v107, v107, v108, vcc
	v_cmp_class_f32_e32 vcc, v106, v125
	v_add_u32_e32 v109, -1, v3
	v_fma_f32 v110, -v109, v3, v2
	v_cmp_ge_f32_e64 s[12:13], 0, v110
	v_add_u32_e32 v110, 1, v3
	v_cndmask_b32_e32 v106, v107, v106, vcc
	v_cndmask_b32_e64 v109, v3, v109, s[12:13]
	v_fma_f32 v3, -v110, v3, v2
	v_cmp_lt_f32_e64 s[12:13], 0, v3
	s_nop 1
	v_cndmask_b32_e64 v3, v109, v110, s[12:13]
	v_mul_f32_e32 v109, 0x37800000, v3
	v_cndmask_b32_e64 v3, v3, v109, s[10:11]
	v_cmp_class_f32_e64 s[10:11], v2, v125
	s_nop 1
	v_cndmask_b32_e64 v2, v3, v2, s[10:11]
	v_div_scale_f32 v3, s[6:7], v2, v2, 1.0
	v_rcp_f32_e32 v109, v3
	s_nop 0
	v_fma_f32 v107, -v3, v109, 1.0
	v_fmac_f32_e32 v109, v107, v109
	v_div_scale_f32 v107, vcc, 1.0, v2, 1.0
	v_mul_f32_e32 v108, v107, v109
	v_fma_f32 v110, -v3, v108, v107
	v_fmac_f32_e32 v108, v110, v109
	v_div_scale_f32 v110, s[6:7], v106, v106, 1.0
	v_rcp_f32_e32 v111, v110
	v_fma_f32 v3, -v3, v108, v107
	v_div_fmas_f32 v3, v3, v109, v108
	v_div_fixup_f32 v107, v3, v2, 1.0
	v_fma_f32 v2, -v110, v111, 1.0
	v_fmac_f32_e32 v111, v2, v111
	v_div_scale_f32 v2, vcc, 1.0, v106, 1.0
	v_mul_f32_e32 v3, v2, v111
	v_fma_f32 v108, -v110, v3, v2
	v_fmac_f32_e32 v3, v108, v111
	v_fma_f32 v2, -v110, v3, v2
	v_div_fmas_f32 v2, v2, v111, v3
	v_div_fixup_f32 v106, v2, v106, 1.0
	v_lshlrev_b32_e32 v2, 16, v98
	v_and_b32_e32 v3, 0xffff0000, v98
	v_mov_b32_e32 v110, v100
	v_mov_b32_e32 v111, v102
	v_pk_fma_f32 v[2:3], v[96:97], s[50:51], v[2:3] op_sel_hi:[1,0,1] neg_lo:[1,0,0] neg_hi:[1,0,0]
	v_pk_mul_f32 v[140:141], v[110:111], s[50:51] op_sel_hi:[1,0]
	v_pk_mul_f32 v[2:3], v[2:3], v[106:107]
	v_pk_mov_b32 v[100:101], v[100:101], v[140:141] op_sel:[1,0]
	v_mov_b32_e32 v115, v140
	v_pk_fma_f32 v[2:3], v[2:3], v[132:133], v[134:135] op_sel_hi:[1,0,0]
	v_pk_mul_f32 v[100:101], v[100:101], v[114:115]
	v_cvt_pk_bf16_f32 v2, v2, v3
	v_sub_f32_e32 v3, v100, v101
	v_max_f32_e32 v3, 0, v3
	v_add_f32_e32 v3, 0x358637bd, v3
	v_lshlrev_b32_e32 v108, 16, v4
	v_and_b32_e32 v109, 0xffff0000, v4
	v_mul_f32_e32 v4, 0x4f800000, v3
	v_cmp_gt_f32_e32 vcc, s57, v3
	v_mov_b32_e32 v140, v103
	v_mov_b32_e32 v115, v141
	v_cndmask_b32_e32 v3, v3, v4, vcc
	v_sqrt_f32_e32 v4, v3
	v_pk_fma_f32 v[96:97], v[96:97], s[50:51], v[108:109] op_sel_hi:[1,0,1] neg_lo:[1,0,0] neg_hi:[1,0,0]
	v_add_u32_e32 v98, -1, v4
	v_fma_f32 v100, -v98, v4, v3
	v_cmp_ge_f32_e64 s[10:11], 0, v100
	v_pk_mul_f32 v[100:101], v[140:141], v[114:115]
	v_add_u32_e32 v102, 1, v4
	v_sub_f32_e32 v100, v100, v101
	v_max_f32_e32 v100, 0, v100
	v_add_f32_e32 v100, 0x358637bd, v100
	v_cndmask_b32_e64 v98, v4, v98, s[10:11]
	v_mul_f32_e32 v101, 0x4f800000, v100
	v_cmp_gt_f32_e64 s[10:11], s57, v100
	v_fma_f32 v4, -v102, v4, v3
	v_cmp_lt_f32_e64 s[12:13], 0, v4
	v_cndmask_b32_e64 v100, v100, v101, s[10:11]
	v_sqrt_f32_e32 v101, v100
	v_cndmask_b32_e64 v4, v98, v102, s[12:13]
	v_mul_f32_e32 v98, 0x37800000, v4
	v_cndmask_b32_e32 v4, v4, v98, vcc
	v_add_u32_e32 v102, -1, v101
	v_fma_f32 v103, -v102, v101, v100
	v_cmp_ge_f32_e64 s[12:13], 0, v103
	v_add_u32_e32 v103, 1, v101
	v_cmp_class_f32_e32 vcc, v3, v125
	v_cndmask_b32_e64 v102, v101, v102, s[12:13]
	v_fma_f32 v101, -v103, v101, v100
	v_cmp_lt_f32_e64 s[12:13], 0, v101
	v_cndmask_b32_e32 v3, v4, v3, vcc
	v_pk_mul_f32 v[96:97], v[106:107], v[96:97]
	v_cndmask_b32_e64 v101, v102, v103, s[12:13]
	v_mul_f32_e32 v102, 0x37800000, v101
	v_cndmask_b32_e64 v101, v101, v102, s[10:11]
	v_cmp_class_f32_e64 s[10:11], v100, v125
	v_pk_fma_f32 v[96:97], v[96:97], v[128:129], v[130:131] op_sel_hi:[1,0,0]
	s_nop 0
	v_cndmask_b32_e64 v100, v101, v100, s[10:11]
	v_div_scale_f32 v101, s[6:7], v100, v100, 1.0
	v_rcp_f32_e32 v102, v101
	s_nop 0
	v_fma_f32 v4, -v101, v102, 1.0
	v_fmac_f32_e32 v102, v4, v102
	v_div_scale_f32 v4, vcc, 1.0, v100, 1.0
	v_mul_f32_e32 v98, v4, v102
	v_fma_f32 v103, -v101, v98, v4
	v_fmac_f32_e32 v98, v103, v102
	v_div_scale_f32 v103, s[6:7], v3, v3, 1.0
	v_rcp_f32_e32 v106, v103
	v_fma_f32 v4, -v101, v98, v4
	v_div_fmas_f32 v4, v4, v102, v98
	v_div_fixup_f32 v101, v4, v100, 1.0
	v_fma_f32 v4, -v103, v106, 1.0
	v_fmac_f32_e32 v106, v4, v106
	v_div_scale_f32 v4, vcc, 1.0, v3, 1.0
	v_mul_f32_e32 v98, v4, v106
	v_fma_f32 v100, -v103, v98, v4
	v_fmac_f32_e32 v98, v100, v106
	v_fma_f32 v4, -v103, v98, v4
	v_div_fmas_f32 v4, v4, v106, v98
	v_div_fixup_f32 v100, v4, v3, 1.0
	v_lshlrev_b32_e32 v98, 16, v99
	v_and_b32_e32 v99, 0xffff0000, v99
	v_lshlrev_b32_e32 v4, 16, v5
	v_and_b32_e32 v5, 0xffff0000, v5
	v_pk_fma_f32 v[98:99], v[110:111], s[50:51], v[98:99] op_sel_hi:[1,0,1] neg_lo:[1,0,0] neg_hi:[1,0,0]
; __device__ __forceinline__ float bflo(unsigned w) { return __uint_as_float(w << 16); }
; __device__ __forceinline__ float bfhi(unsigned w) { return __uint_as_float(w & 0xffff0000u); }
; __device__ __forceinline__ unsigned cvtpk_s(float lo, float hi) { f32x2_t v = {lo, hi}; bf16x2_t b = __builtin_convertvector(v, bf16x2_t); return __builtin_bit_cast(unsigned, b); }
; template <int NMT> __device__ __forceinline__ void sg_unit(int chunk, int g, int cofs, const bf16_t* VST, const bf16_t* QU, bf16_t* OB, const float* stats, const float* lng, const float* lnb, const bf16_t* WSb, const float* bs, int lane_) {
;     ...
;     for (int ks = 0; ks < 4; ++ks) {
;         float mu[8], rs[8];
; #pragma unroll
;         for (int j = 0; j < 8; ++j) { const float mean = sv[ks][j][0] * (1.0f / 512.0f); const float var = fmaxf(sv[ks][j][1] * (1.0f / 512.0f) - mean * mean, 0.f); mu[j] = mean; rs[j] = 1.0f / sqrtf(var + EPS); }
; #pragma unroll
;         for (int mt = 0; mt < NMT; ++mt) {
;             const u32x4 rw = raw[mt][ks];
;             float v[8]; v[0] = pg8::bflo(rw.x); v[1] = pg8::bfhi(rw.x); v[2] = pg8::bflo(rw.y); v[3] = pg8::bfhi(rw.y); v[4] = pg8::bflo(rw.z); v[5] = pg8::bfhi(rw.z); v[6] = pg8::bflo(rw.w); v[7] = pg8::bfhi(rw.w);
; #pragma unroll
;             for (int j = 0; j < 8; ++j) v[j] = (v[j] - mu[j]) * rs[j] * lg[mt] + lb[mt];
;             u32x4 pw; pw.x = cvtpk_s(v[0], v[1]); pw.y = cvtpk_s(v[2], v[3]); pw.z = cvtpk_s(v[4], v[5]); pw.w = cvtpk_s(v[6], v[7]);
;             af[mt][ks] = __builtin_bit_cast(bf16x8, pw);
;         }
	v_pk_fma_f32 v[4:5], v[110:111], s[50:51], v[4:5] op_sel_hi:[1,0,1] neg_lo:[1,0,0] neg_hi:[1,0,0]
	v_pk_mul_f32 v[98:99], v[98:99], v[100:101]
	v_pk_mul_f32 v[4:5], v[4:5], v[100:101]
	v_mov_b32_e32 v100, v92
	v_mov_b32_e32 v101, v94
	v_pk_fma_f32 v[98:99], v[98:99], v[132:133], v[134:135] op_sel_hi:[1,0,0]
	v_pk_mul_f32 v[102:103], v[100:101], s[50:51] op_sel_hi:[1,0]
	v_cvt_pk_bf16_f32 v3, v98, v99
	v_pk_fma_f32 v[98:99], v[4:5], v[128:129], v[130:131] op_sel_hi:[1,0,0]
	v_cvt_pk_bf16_f32 v4, v6, v7
	v_pk_mov_b32 v[6:7], v[92:93], v[102:103] op_sel:[1,0]
	v_mov_b32_e32 v115, v102
	v_pk_mul_f32 v[6:7], v[6:7], v[114:115]
	v_mov_b32_e32 v102, v95
	v_sub_f32_e32 v5, v6, v7
	v_max_f32_e32 v5, 0, v5
	v_add_f32_e32 v5, 0x358637bd, v5
	v_mul_f32_e32 v6, 0x4f800000, v5
	v_cmp_gt_f32_e32 vcc, s57, v5
	v_mov_b32_e32 v115, v103
	v_cvt_pk_bf16_f32 v7, v98, v99
	v_cndmask_b32_e32 v94, v5, v6, vcc
	v_sqrt_f32_e32 v92, v94
	v_cvt_pk_bf16_f32 v6, v96, v97
	v_cvt_pk_bf16_f32 v5, v104, v105
	v_add_u32_e32 v93, -1, v92
	v_fma_f32 v96, -v93, v92, v94
	v_cmp_ge_f32_e64 s[10:11], 0, v96
	v_add_u32_e32 v97, 1, v92
	v_fma_f32 v98, -v97, v92, v94
	v_cndmask_b32_e64 v96, v92, v93, s[10:11]
	v_pk_mul_f32 v[92:93], v[102:103], v[114:115]
	v_cmp_lt_f32_e64 s[12:13], 0, v98
	v_sub_f32_e32 v92, v92, v93
	v_max_f32_e32 v92, 0, v92
	v_add_f32_e32 v92, 0x358637bd, v92
	v_mul_f32_e32 v93, 0x4f800000, v92
	v_cmp_gt_f32_e64 s[10:11], s57, v92
	v_cndmask_b32_e64 v95, v96, v97, s[12:13]
	v_mul_f32_e32 v96, 0x37800000, v95
	v_cndmask_b32_e64 v92, v92, v93, s[10:11]
	v_sqrt_f32_e32 v93, v92
	v_cndmask_b32_e32 v95, v95, v96, vcc
	v_cmp_class_f32_e32 vcc, v94, v125
	v_add_u32_e32 v97, -1, v93
	v_fma_f32 v98, -v97, v93, v92
	v_cmp_ge_f32_e64 s[12:13], 0, v98
	v_add_u32_e32 v98, 1, v93
	v_cndmask_b32_e32 v94, v95, v94, vcc
	v_cndmask_b32_e64 v97, v93, v97, s[12:13]
	v_fma_f32 v93, -v98, v93, v92
	v_cmp_lt_f32_e64 s[12:13], 0, v93
	s_nop 1
	v_cndmask_b32_e64 v93, v97, v98, s[12:13]
	v_mul_f32_e32 v97, 0x37800000, v93
	v_cndmask_b32_e64 v93, v93, v97, s[10:11]
	v_cmp_class_f32_e64 s[10:11], v92, v125
	s_nop 1
	v_cndmask_b32_e64 v92, v93, v92, s[10:11]
	v_div_scale_f32 v93, s[6:7], v92, v92, 1.0
	v_rcp_f32_e32 v97, v93
	s_nop 0
	v_fma_f32 v95, -v93, v97, 1.0
	v_fmac_f32_e32 v97, v95, v97
	v_div_scale_f32 v95, vcc, 1.0, v92, 1.0
	v_mul_f32_e32 v96, v95, v97
	v_fma_f32 v98, -v93, v96, v95
	v_fmac_f32_e32 v96, v98, v97
	v_fma_f32 v93, -v93, v96, v95
	v_div_scale_f32 v95, s[6:7], v94, v94, 1.0
	v_rcp_f32_e32 v98, v95
	v_div_fmas_f32 v93, v93, v97, v96
	v_div_fixup_f32 v93, v93, v92, 1.0
	v_fma_f32 v92, -v95, v98, 1.0
	v_fmac_f32_e32 v98, v92, v98
	v_div_scale_f32 v92, vcc, 1.0, v94, 1.0
	v_mul_f32_e32 v96, v92, v98
	v_fma_f32 v97, -v95, v96, v92
	v_fmac_f32_e32 v96, v97, v98
	v_fma_f32 v92, -v95, v96, v92
	v_div_fmas_f32 v92, v92, v98, v96
	v_div_fixup_f32 v92, v92, v94, 1.0
	v_lshlrev_b32_e32 v94, 16, v8
	v_and_b32_e32 v95, 0xffff0000, v8
	v_mov_b32_e32 v96, v88
	v_mov_b32_e32 v97, v90
	v_pk_fma_f32 v[94:95], v[100:101], s[50:51], v[94:95] op_sel_hi:[1,0,1] neg_lo:[1,0,0] neg_hi:[1,0,0]
	v_pk_mul_f32 v[98:99], v[96:97], s[50:51] op_sel_hi:[1,0]
	v_pk_mul_f32 v[94:95], v[92:93], v[94:95]
	v_pk_mov_b32 v[88:89], v[88:89], v[98:99] op_sel:[1,0]
	v_mov_b32_e32 v115, v98
	v_pk_fma_f32 v[94:95], v[94:95], v[132:133], v[134:135] op_sel_hi:[1,0,0]
	v_pk_mul_f32 v[88:89], v[88:89], v[114:115]
	v_cvt_pk_bf16_f32 v8, v94, v95
	v_lshlrev_b32_e32 v94, 16, v36
	v_and_b32_e32 v95, 0xffff0000, v36
	v_sub_f32_e32 v36, v88, v89
	v_max_f32_e32 v36, 0, v36
	v_add_f32_e32 v36, 0x358637bd, v36
	v_mul_f32_e32 v88, 0x4f800000, v36
	v_cmp_gt_f32_e32 vcc, s57, v36
	v_mov_b32_e32 v98, v91
	v_mov_b32_e32 v115, v99
	v_cndmask_b32_e32 v36, v36, v88, vcc
	v_sqrt_f32_e32 v90, v36
	v_pk_fma_f32 v[88:89], v[100:101], s[50:51], v[94:95] op_sel_hi:[1,0,1] neg_lo:[1,0,0] neg_hi:[1,0,0]
	s_nop 0
	v_pk_mul_f32 v[88:89], v[92:93], v[88:89]
	v_add_u32_e32 v92, -1, v90
	v_fma_f32 v93, -v92, v90, v36
	v_cmp_ge_f32_e64 s[10:11], 0, v93
	v_add_u32_e32 v93, 1, v90
	v_fma_f32 v94, -v93, v90, v36
	v_cndmask_b32_e64 v92, v90, v92, s[10:11]
	v_pk_mul_f32 v[90:91], v[98:99], v[114:115]
	v_cmp_lt_f32_e64 s[12:13], 0, v94
	v_sub_f32_e32 v90, v90, v91
	v_max_f32_e32 v90, 0, v90
	v_add_f32_e32 v90, 0x358637bd, v90
	v_mul_f32_e32 v91, 0x4f800000, v90
	v_cmp_gt_f32_e64 s[10:11], s57, v90
	v_cndmask_b32_e64 v92, v92, v93, s[12:13]
	v_mul_f32_e32 v93, 0x37800000, v92
	v_cndmask_b32_e64 v90, v90, v91, s[10:11]
	v_sqrt_f32_e32 v91, v90
	v_cndmask_b32_e32 v92, v92, v93, vcc
	v_cmp_class_f32_e32 vcc, v36, v125
	v_pk_fma_f32 v[88:89], v[88:89], v[128:129], v[130:131] op_sel_hi:[1,0,0]
	v_add_u32_e32 v94, -1, v91
	v_fma_f32 v95, -v94, v91, v90
	v_cmp_ge_f32_e64 s[12:13], 0, v95
	v_add_u32_e32 v95, 1, v91
	v_cndmask_b32_e32 v36, v92, v36, vcc
	v_cndmask_b32_e64 v94, v91, v94, s[12:13]
	v_fma_f32 v91, -v95, v91, v90
	v_cmp_lt_f32_e64 s[12:13], 0, v91
	s_nop 1
	v_cndmask_b32_e64 v91, v94, v95, s[12:13]
	v_mul_f32_e32 v94, 0x37800000, v91
	v_cndmask_b32_e64 v91, v91, v94, s[10:11]
	v_cmp_class_f32_e64 s[10:11], v90, v125
	s_nop 1
	v_cndmask_b32_e64 v90, v91, v90, s[10:11]
	v_div_scale_f32 v91, s[6:7], v90, v90, 1.0
	v_rcp_f32_e32 v94, v91
	s_nop 0
	v_fma_f32 v92, -v91, v94, 1.0
	v_fmac_f32_e32 v94, v92, v94
	v_div_scale_f32 v92, vcc, 1.0, v90, 1.0
	v_mul_f32_e32 v93, v92, v94
	v_fma_f32 v95, -v91, v93, v92
	v_fmac_f32_e32 v93, v95, v94
	v_fma_f32 v91, -v91, v93, v92
	v_div_scale_f32 v92, s[6:7], v36, v36, 1.0
	v_rcp_f32_e32 v95, v92
	v_div_fmas_f32 v91, v91, v94, v93
	v_div_fixup_f32 v91, v91, v90, 1.0
	v_fma_f32 v90, -v92, v95, 1.0
	v_fmac_f32_e32 v95, v90, v95
; __device__ __forceinline__ float bflo(unsigned w) { return __uint_as_float(w << 16); }
; __device__ __forceinline__ float bfhi(unsigned w) { return __uint_as_float(w & 0xffff0000u); }
; __device__ __forceinline__ unsigned cvtpk_s(float lo, float hi) { f32x2_t v = {lo, hi}; bf16x2_t b = __builtin_convertvector(v, bf16x2_t); return __builtin_bit_cast(unsigned, b); }
; template <int NMT> __device__ __forceinline__ void sg_unit(int chunk, int g, int cofs, const bf16_t* VST, const bf16_t* QU, bf16_t* OB, const float* stats, const float* lng, const float* lnb, const bf16_t* WSb, const float* bs, int lane_) {
;     ...
;     for (int ks = 0; ks < 4; ++ks) {
;         float mu[8], rs[8];
; #pragma unroll
;         for (int j = 0; j < 8; ++j) { const float mean = sv[ks][j][0] * (1.0f / 512.0f); const float var = fmaxf(sv[ks][j][1] * (1.0f / 512.0f) - mean * mean, 0.f); mu[j] = mean; rs[j] = 1.0f / sqrtf(var + EPS); }
; #pragma unroll
;         for (int mt = 0; mt < NMT; ++mt) {
;             const u32x4 rw = raw[mt][ks];
;             float v[8]; v[0] = pg8::bflo(rw.x); v[1] = pg8::bfhi(rw.x); v[2] = pg8::bflo(rw.y); v[3] = pg8::bfhi(rw.y); v[4] = pg8::bflo(rw.z); v[5] = pg8::bfhi(rw.z); v[6] = pg8::bflo(rw.w); v[7] = pg8::bfhi(rw.w);
; #pragma unroll
;             for (int j = 0; j < 8; ++j) v[j] = (v[j] - mu[j]) * rs[j] * lg[mt] + lb[mt];
;             u32x4 pw; pw.x = cvtpk_s(v[0], v[1]); pw.y = cvtpk_s(v[2], v[3]); pw.z = cvtpk_s(v[4], v[5]); pw.w = cvtpk_s(v[6], v[7]);
;             af[mt][ks] = __builtin_bit_cast(bf16x8, pw);
;         }
	v_div_scale_f32 v90, vcc, 1.0, v36, 1.0
	v_mul_f32_e32 v93, v90, v95
	v_fma_f32 v94, -v92, v93, v90
	v_fmac_f32_e32 v93, v94, v95
	v_fma_f32 v90, -v92, v93, v90
	v_div_fmas_f32 v90, v90, v95, v93
	v_lshlrev_b32_e32 v92, 16, v9
	v_and_b32_e32 v93, 0xffff0000, v9
	v_div_fixup_f32 v90, v90, v36, 1.0
	v_pk_fma_f32 v[92:93], v[96:97], s[50:51], v[92:93] op_sel_hi:[1,0,1] neg_lo:[1,0,0] neg_hi:[1,0,0]
	v_lshlrev_b32_e32 v36, 16, v37
	v_pk_mul_f32 v[92:93], v[90:91], v[92:93]
	v_and_b32_e32 v37, 0xffff0000, v37
	v_pk_fma_f32 v[92:93], v[92:93], v[132:133], v[134:135] op_sel_hi:[1,0,0]
	v_pk_fma_f32 v[36:37], v[96:97], s[50:51], v[36:37] op_sel_hi:[1,0,1] neg_lo:[1,0,0] neg_hi:[1,0,0]
	v_cvt_pk_bf16_f32 v9, v92, v93
	v_mov_b32_e32 v92, v84
	v_mov_b32_e32 v93, v86
	v_pk_mul_f32 v[94:95], v[92:93], s[50:51] op_sel_hi:[1,0]
	v_pk_mul_f32 v[36:37], v[90:91], v[36:37]
	v_pk_mov_b32 v[84:85], v[84:85], v[94:95] op_sel:[1,0]
	v_mov_b32_e32 v115, v94
	v_pk_mul_f32 v[84:85], v[84:85], v[114:115]
	v_mov_b32_e32 v115, v95
	v_sub_f32_e32 v84, v84, v85
	v_max_f32_e32 v84, 0, v84
	v_add_f32_e32 v84, 0x358637bd, v84
	v_mul_f32_e32 v85, 0x4f800000, v84
	v_cmp_gt_f32_e32 vcc, s57, v84
	s_nop 1
	v_cndmask_b32_e32 v86, v84, v85, vcc
	v_sqrt_f32_e32 v94, v86
	v_pk_fma_f32 v[84:85], v[36:37], v[128:129], v[130:131] op_sel_hi:[1,0,0]
	v_add_u32_e32 v36, -1, v94
	v_fma_f32 v37, -v36, v94, v86
	v_cmp_ge_f32_e64 s[10:11], 0, v37
	v_add_u32_e32 v91, 1, v94
	v_fma_f32 v96, -v91, v94, v86
	v_cndmask_b32_e64 v90, v94, v36, s[10:11]
	v_mov_b32_e32 v94, v87
	v_pk_mul_f32 v[36:37], v[94:95], v[114:115]
	v_cmp_lt_f32_e64 s[12:13], 0, v96
	v_sub_f32_e32 v36, v36, v37
	v_max_f32_e32 v36, 0, v36
	v_add_f32_e32 v36, 0x358637bd, v36
	v_mul_f32_e32 v37, 0x4f800000, v36
	v_cmp_gt_f32_e64 s[10:11], s57, v36
	v_cndmask_b32_e64 v87, v90, v91, s[12:13]
	v_mul_f32_e32 v90, 0x37800000, v87
	v_cndmask_b32_e64 v36, v36, v37, s[10:11]
	v_sqrt_f32_e32 v37, v36
	v_cndmask_b32_e32 v87, v87, v90, vcc
	v_cmp_class_f32_e32 vcc, v86, v125
	v_add_u32_e32 v91, -1, v37
	v_fma_f32 v94, -v91, v37, v36
	v_cmp_ge_f32_e64 s[12:13], 0, v94
	v_add_u32_e32 v94, 1, v37
	v_cndmask_b32_e32 v86, v87, v86, vcc
	v_cndmask_b32_e64 v91, v37, v91, s[12:13]
	v_fma_f32 v37, -v94, v37, v36
	v_cmp_lt_f32_e64 s[12:13], 0, v37
	s_nop 1
	v_cndmask_b32_e64 v37, v91, v94, s[12:13]
	v_mul_f32_e32 v91, 0x37800000, v37
	v_cndmask_b32_e64 v37, v37, v91, s[10:11]
	v_cmp_class_f32_e64 s[10:11], v36, v125
	s_nop 1
	v_cndmask_b32_e64 v36, v37, v36, s[10:11]
	v_div_scale_f32 v37, s[6:7], v36, v36, 1.0
	v_rcp_f32_e32 v91, v37
	s_nop 0
	v_fma_f32 v87, -v37, v91, 1.0
	v_fmac_f32_e32 v91, v87, v91
	v_div_scale_f32 v87, vcc, 1.0, v36, 1.0
	v_mul_f32_e32 v90, v87, v91
	v_fma_f32 v94, -v37, v90, v87
	v_fmac_f32_e32 v90, v94, v91
	v_fma_f32 v37, -v37, v90, v87
	v_div_scale_f32 v87, s[6:7], v86, v86, 1.0
	v_rcp_f32_e32 v94, v87
	v_div_fmas_f32 v37, v37, v91, v90
	v_div_fixup_f32 v37, v37, v36, 1.0
	v_fma_f32 v36, -v87, v94, 1.0
	v_fmac_f32_e32 v94, v36, v94
	v_div_scale_f32 v36, vcc, 1.0, v86, 1.0
	v_mul_f32_e32 v90, v36, v94
	v_fma_f32 v91, -v87, v90, v36
	v_fmac_f32_e32 v90, v91, v94
	v_fma_f32 v36, -v87, v90, v36
	v_div_fmas_f32 v36, v36, v94, v90
	v_div_fixup_f32 v36, v36, v86, 1.0
	v_lshlrev_b32_e32 v86, 16, v10
	v_and_b32_e32 v87, 0xffff0000, v10
	v_mov_b32_e32 v90, v80
	v_mov_b32_e32 v91, v82
	v_pk_fma_f32 v[86:87], v[92:93], s[50:51], v[86:87] op_sel_hi:[1,0,1] neg_lo:[1,0,0] neg_hi:[1,0,0]
	v_pk_mul_f32 v[94:95], v[90:91], s[50:51] op_sel_hi:[1,0]
	v_pk_mul_f32 v[86:87], v[86:87], v[36:37]
	v_pk_mov_b32 v[80:81], v[80:81], v[94:95] op_sel:[1,0]
	v_mov_b32_e32 v115, v94
	v_pk_fma_f32 v[86:87], v[86:87], v[132:133], v[134:135] op_sel_hi:[1,0,0]
	v_pk_mul_f32 v[80:81], v[80:81], v[114:115]
	v_cvt_pk_bf16_f32 v10, v86, v87
	v_lshlrev_b32_e32 v86, 16, v38
	v_and_b32_e32 v87, 0xffff0000, v38
	v_sub_f32_e32 v38, v80, v81
	v_max_f32_e32 v38, 0, v38
	v_add_f32_e32 v38, 0x358637bd, v38
	v_mul_f32_e32 v80, 0x4f800000, v38
	v_cmp_gt_f32_e32 vcc, s57, v38
	v_mov_b32_e32 v94, v83
	v_mov_b32_e32 v115, v95
	v_cndmask_b32_e32 v38, v38, v80, vcc
	v_sqrt_f32_e32 v82, v38
	v_pk_fma_f32 v[80:81], v[92:93], s[50:51], v[86:87] op_sel_hi:[1,0,1] neg_lo:[1,0,0] neg_hi:[1,0,0]
	v_add_u32_e32 v87, 1, v82
	v_pk_mul_f32 v[36:37], v[36:37], v[80:81]
	s_nop 0
	v_pk_fma_f32 v[80:81], v[36:37], v[128:129], v[130:131] op_sel_hi:[1,0,0]
	v_add_u32_e32 v36, -1, v82
	v_fma_f32 v37, -v36, v82, v38
	v_cmp_ge_f32_e64 s[10:11], 0, v37
	s_nop 1
	v_cndmask_b32_e64 v86, v82, v36, s[10:11]
	v_pk_mul_f32 v[36:37], v[94:95], v[114:115]
	v_fma_f32 v82, -v87, v82, v38
	v_sub_f32_e32 v36, v36, v37
	v_max_f32_e32 v36, 0, v36
	v_add_f32_e32 v36, 0x358637bd, v36
	v_mul_f32_e32 v37, 0x4f800000, v36
	v_cmp_gt_f32_e64 s[10:11], s57, v36
	v_cmp_lt_f32_e64 s[12:13], 0, v82
	s_nop 0
	v_cndmask_b32_e64 v36, v36, v37, s[10:11]
	v_sqrt_f32_e32 v37, v36
	v_cndmask_b32_e64 v82, v86, v87, s[12:13]
	v_mul_f32_e32 v83, 0x37800000, v82
	v_cndmask_b32_e32 v82, v82, v83, vcc
	v_add_u32_e32 v86, -1, v37
	v_fma_f32 v87, -v86, v37, v36
	v_cmp_ge_f32_e64 s[12:13], 0, v87
	v_add_u32_e32 v87, 1, v37
	v_cmp_class_f32_e32 vcc, v38, v125
	v_cndmask_b32_e64 v86, v37, v86, s[12:13]
	v_fma_f32 v37, -v87, v37, v36
	v_cmp_lt_f32_e64 s[12:13], 0, v37
	v_cndmask_b32_e32 v38, v82, v38, vcc
	s_nop 0
	v_cndmask_b32_e64 v37, v86, v87, s[12:13]
	v_mul_f32_e32 v86, 0x37800000, v37
	v_cndmask_b32_e64 v37, v37, v86, s[10:11]
	v_cmp_class_f32_e64 s[10:11], v36, v125
	s_nop 1
	v_cndmask_b32_e64 v36, v37, v36, s[10:11]
	v_div_scale_f32 v37, s[6:7], v36, v36, 1.0
	v_rcp_f32_e32 v86, v37
	s_nop 0
	v_fma_f32 v82, -v37, v86, 1.0
; __device__ __forceinline__ float bflo(unsigned w) { return __uint_as_float(w << 16); }
; __device__ __forceinline__ float bfhi(unsigned w) { return __uint_as_float(w & 0xffff0000u); }
; __device__ __forceinline__ unsigned cvtpk_s(float lo, float hi) { f32x2_t v = {lo, hi}; bf16x2_t b = __builtin_convertvector(v, bf16x2_t); return __builtin_bit_cast(unsigned, b); }
; template <int NMT> __device__ __forceinline__ void sg_unit(int chunk, int g, int cofs, const bf16_t* VST, const bf16_t* QU, bf16_t* OB, const float* stats, const float* lng, const float* lnb, const bf16_t* WSb, const float* bs, int lane_) {
;     ...
;     for (int ks = 0; ks < 4; ++ks) {
;         float mu[8], rs[8];
; #pragma unroll
;         for (int j = 0; j < 8; ++j) { const float mean = sv[ks][j][0] * (1.0f / 512.0f); const float var = fmaxf(sv[ks][j][1] * (1.0f / 512.0f) - mean * mean, 0.f); mu[j] = mean; rs[j] = 1.0f / sqrtf(var + EPS); }
; #pragma unroll
;         for (int mt = 0; mt < NMT; ++mt) {
;             const u32x4 rw = raw[mt][ks];
;             float v[8]; v[0] = pg8::bflo(rw.x); v[1] = pg8::bfhi(rw.x); v[2] = pg8::bflo(rw.y); v[3] = pg8::bfhi(rw.y); v[4] = pg8::bflo(rw.z); v[5] = pg8::bfhi(rw.z); v[6] = pg8::bflo(rw.w); v[7] = pg8::bfhi(rw.w);
; #pragma unroll
;             for (int j = 0; j < 8; ++j) v[j] = (v[j] - mu[j]) * rs[j] * lg[mt] + lb[mt];
;             u32x4 pw; pw.x = cvtpk_s(v[0], v[1]); pw.y = cvtpk_s(v[2], v[3]); pw.z = cvtpk_s(v[4], v[5]); pw.w = cvtpk_s(v[6], v[7]);
;             af[mt][ks] = __builtin_bit_cast(bf16x8, pw);
;         }
	v_fmac_f32_e32 v86, v82, v86
	v_div_scale_f32 v82, vcc, 1.0, v36, 1.0
	v_mul_f32_e32 v83, v82, v86
	v_fma_f32 v87, -v37, v83, v82
	v_fmac_f32_e32 v83, v87, v86
	v_fma_f32 v37, -v37, v83, v82
	v_div_scale_f32 v82, s[6:7], v38, v38, 1.0
	v_rcp_f32_e32 v87, v82
	v_div_fmas_f32 v37, v37, v86, v83
	v_div_fixup_f32 v37, v37, v36, 1.0
	v_fma_f32 v36, -v82, v87, 1.0
	v_fmac_f32_e32 v87, v36, v87
	v_div_scale_f32 v36, vcc, 1.0, v38, 1.0
	v_mul_f32_e32 v83, v36, v87
	v_fma_f32 v86, -v82, v83, v36
	v_fmac_f32_e32 v83, v86, v87
	v_fma_f32 v36, -v82, v83, v36
	v_div_fmas_f32 v36, v36, v87, v83
	v_lshlrev_b32_e32 v82, 16, v11
	v_and_b32_e32 v83, 0xffff0000, v11
	v_div_fixup_f32 v36, v36, v38, 1.0
	v_pk_fma_f32 v[82:83], v[90:91], s[50:51], v[82:83] op_sel_hi:[1,0,1] neg_lo:[1,0,0] neg_hi:[1,0,0]
	v_lshlrev_b32_e32 v38, 16, v39
	v_and_b32_e32 v39, 0xffff0000, v39
	v_pk_mul_f32 v[82:83], v[82:83], v[36:37]
	v_pk_fma_f32 v[38:39], v[90:91], s[50:51], v[38:39] op_sel_hi:[1,0,1] neg_lo:[1,0,0] neg_hi:[1,0,0]
	v_pk_fma_f32 v[82:83], v[82:83], v[132:133], v[134:135] op_sel_hi:[1,0,0]
	v_pk_mul_f32 v[36:37], v[38:39], v[36:37]
	v_mov_b32_e32 v86, v76
	v_mov_b32_e32 v87, v78
	v_cvt_pk_bf16_f32 v11, v82, v83
	v_pk_fma_f32 v[82:83], v[36:37], v[128:129], v[130:131] op_sel_hi:[1,0,0]
	v_cvt_pk_bf16_f32 v36, v88, v89
	v_pk_mul_f32 v[88:89], v[86:87], s[50:51] op_sel_hi:[1,0]
	s_nop 0
	v_pk_mov_b32 v[38:39], v[76:77], v[88:89] op_sel:[1,0]
	v_mov_b32_e32 v115, v88
	v_pk_mul_f32 v[38:39], v[38:39], v[114:115]
	v_mov_b32_e32 v88, v79
	v_sub_f32_e32 v37, v38, v39
	v_max_f32_e32 v37, 0, v37
	v_add_f32_e32 v37, 0x358637bd, v37
	v_mul_f32_e32 v38, 0x4f800000, v37
	v_cmp_gt_f32_e32 vcc, s57, v37
	v_mov_b32_e32 v115, v89
	v_cvt_pk_bf16_f32 v39, v82, v83
	v_cndmask_b32_e32 v78, v37, v38, vcc
	v_sqrt_f32_e32 v76, v78
	v_cvt_pk_bf16_f32 v38, v80, v81
	v_cvt_pk_bf16_f32 v37, v84, v85
	v_lshlrev_b32_e32 v84, 16, v23
	v_add_u32_e32 v77, -1, v76
	v_fma_f32 v80, -v77, v76, v78
	v_cmp_ge_f32_e64 s[10:11], 0, v80
	v_add_u32_e32 v81, 1, v76
	v_fma_f32 v82, -v81, v76, v78
	v_cndmask_b32_e64 v80, v76, v77, s[10:11]
	v_pk_mul_f32 v[76:77], v[88:89], v[114:115]
	v_cmp_lt_f32_e64 s[12:13], 0, v82
	v_sub_f32_e32 v76, v76, v77
	v_max_f32_e32 v76, 0, v76
	v_add_f32_e32 v76, 0x358637bd, v76
	v_mul_f32_e32 v77, 0x4f800000, v76
	v_cmp_gt_f32_e64 s[10:11], s57, v76
	v_cndmask_b32_e64 v79, v80, v81, s[12:13]
	v_mul_f32_e32 v80, 0x37800000, v79
	v_cndmask_b32_e64 v76, v76, v77, s[10:11]
	v_sqrt_f32_e32 v77, v76
	v_cndmask_b32_e32 v79, v79, v80, vcc
	v_cmp_class_f32_e32 vcc, v78, v125
	v_and_b32_e32 v85, 0xffff0000, v23
	v_add_u32_e32 v81, -1, v77
	v_fma_f32 v82, -v81, v77, v76
	v_cmp_ge_f32_e64 s[12:13], 0, v82
	v_add_u32_e32 v82, 1, v77
	v_cndmask_b32_e32 v78, v79, v78, vcc
	v_cndmask_b32_e64 v81, v77, v81, s[12:13]
	v_fma_f32 v77, -v82, v77, v76
	v_cmp_lt_f32_e64 s[12:13], 0, v77
	s_nop 1
	v_cndmask_b32_e64 v77, v81, v82, s[12:13]
	v_mul_f32_e32 v81, 0x37800000, v77
	v_cndmask_b32_e64 v77, v77, v81, s[10:11]
	v_cmp_class_f32_e64 s[10:11], v76, v125
	s_nop 1
	v_cndmask_b32_e64 v76, v77, v76, s[10:11]
	v_div_scale_f32 v77, s[6:7], v76, v76, 1.0
	v_rcp_f32_e32 v81, v77
	s_nop 0
	v_fma_f32 v79, -v77, v81, 1.0
	v_fmac_f32_e32 v81, v79, v81
	v_div_scale_f32 v79, vcc, 1.0, v76, 1.0
	v_mul_f32_e32 v80, v79, v81
	v_fma_f32 v82, -v77, v80, v79
	v_fmac_f32_e32 v80, v82, v81
	v_fma_f32 v77, -v77, v80, v79
	v_div_scale_f32 v79, s[6:7], v78, v78, 1.0
	v_rcp_f32_e32 v82, v79
	v_div_fmas_f32 v77, v77, v81, v80
	v_div_fixup_f32 v77, v77, v76, 1.0
	v_fma_f32 v76, -v79, v82, 1.0
	v_fmac_f32_e32 v82, v76, v82
	v_div_scale_f32 v76, vcc, 1.0, v78, 1.0
	v_mul_f32_e32 v80, v76, v82
	v_fma_f32 v81, -v79, v80, v76
	v_fmac_f32_e32 v80, v81, v82
	v_fma_f32 v76, -v79, v80, v76
	v_div_fmas_f32 v76, v76, v82, v80
	v_div_fixup_f32 v76, v76, v78, 1.0
	v_lshlrev_b32_e32 v78, 16, v44
	v_and_b32_e32 v79, 0xffff0000, v44
	v_mov_b32_e32 v80, v72
	v_mov_b32_e32 v81, v74
	v_pk_fma_f32 v[78:79], v[86:87], s[50:51], v[78:79] op_sel_hi:[1,0,1] neg_lo:[1,0,0] neg_hi:[1,0,0]
	v_pk_mul_f32 v[82:83], v[80:81], s[50:51] op_sel_hi:[1,0]
	v_pk_mul_f32 v[78:79], v[76:77], v[78:79]
	v_pk_mov_b32 v[72:73], v[72:73], v[82:83] op_sel:[1,0]
	v_mov_b32_e32 v115, v82
	v_pk_fma_f32 v[78:79], v[78:79], v[132:133], v[134:135] op_sel_hi:[1,0,0]
	v_pk_mul_f32 v[72:73], v[72:73], v[114:115]
	v_cvt_pk_bf16_f32 v44, v78, v79
	v_lshlrev_b32_e32 v78, 16, v60
	v_and_b32_e32 v79, 0xffff0000, v60
	v_sub_f32_e32 v60, v72, v73
	v_max_f32_e32 v60, 0, v60
	v_add_f32_e32 v60, 0x358637bd, v60
	v_mul_f32_e32 v72, 0x4f800000, v60
	v_cmp_gt_f32_e32 vcc, s57, v60
	v_mov_b32_e32 v82, v75
	v_mov_b32_e32 v115, v83
	v_cndmask_b32_e32 v60, v60, v72, vcc
	v_sqrt_f32_e32 v74, v60
	v_pk_fma_f32 v[72:73], v[86:87], s[50:51], v[78:79] op_sel_hi:[1,0,1] neg_lo:[1,0,0] neg_hi:[1,0,0]
	s_nop 0
	v_pk_mul_f32 v[72:73], v[76:77], v[72:73]
	v_add_u32_e32 v76, -1, v74
	v_fma_f32 v77, -v76, v74, v60
	v_cmp_ge_f32_e64 s[10:11], 0, v77
	v_add_u32_e32 v77, 1, v74
	v_fma_f32 v78, -v77, v74, v60
	v_cndmask_b32_e64 v76, v74, v76, s[10:11]
	v_pk_mul_f32 v[74:75], v[82:83], v[114:115]
	v_cmp_lt_f32_e64 s[12:13], 0, v78
	v_sub_f32_e32 v74, v74, v75
	v_max_f32_e32 v74, 0, v74
	v_add_f32_e32 v74, 0x358637bd, v74
	v_mul_f32_e32 v75, 0x4f800000, v74
	v_cmp_gt_f32_e64 s[10:11], s57, v74
	v_cndmask_b32_e64 v76, v76, v77, s[12:13]
	v_mul_f32_e32 v77, 0x37800000, v76
	v_cndmask_b32_e64 v74, v74, v75, s[10:11]
	v_sqrt_f32_e32 v75, v74
	v_cndmask_b32_e32 v76, v76, v77, vcc
	v_cmp_class_f32_e32 vcc, v60, v125
	v_pk_fma_f32 v[72:73], v[72:73], v[128:129], v[130:131] op_sel_hi:[1,0,0]
	v_add_u32_e32 v78, -1, v75
; __device__ __forceinline__ float bflo(unsigned w) { return __uint_as_float(w << 16); }
; __device__ __forceinline__ float bfhi(unsigned w) { return __uint_as_float(w & 0xffff0000u); }
; __device__ __forceinline__ unsigned cvtpk_s(float lo, float hi) { f32x2_t v = {lo, hi}; bf16x2_t b = __builtin_convertvector(v, bf16x2_t); return __builtin_bit_cast(unsigned, b); }
; template <int NMT> __device__ __forceinline__ void sg_unit(int chunk, int g, int cofs, const bf16_t* VST, const bf16_t* QU, bf16_t* OB, const float* stats, const float* lng, const float* lnb, const bf16_t* WSb, const float* bs, int lane_) {
;     ...
;     for (int ks = 0; ks < 4; ++ks) {
;         float mu[8], rs[8];
; #pragma unroll
;         for (int j = 0; j < 8; ++j) { const float mean = sv[ks][j][0] * (1.0f / 512.0f); const float var = fmaxf(sv[ks][j][1] * (1.0f / 512.0f) - mean * mean, 0.f); mu[j] = mean; rs[j] = 1.0f / sqrtf(var + EPS); }
; #pragma unroll
;         for (int mt = 0; mt < NMT; ++mt) {
;             const u32x4 rw = raw[mt][ks];
;             float v[8]; v[0] = pg8::bflo(rw.x); v[1] = pg8::bfhi(rw.x); v[2] = pg8::bflo(rw.y); v[3] = pg8::bfhi(rw.y); v[4] = pg8::bflo(rw.z); v[5] = pg8::bfhi(rw.z); v[6] = pg8::bflo(rw.w); v[7] = pg8::bfhi(rw.w);
; #pragma unroll
;             for (int j = 0; j < 8; ++j) v[j] = (v[j] - mu[j]) * rs[j] * lg[mt] + lb[mt];
;             u32x4 pw; pw.x = cvtpk_s(v[0], v[1]); pw.y = cvtpk_s(v[2], v[3]); pw.z = cvtpk_s(v[4], v[5]); pw.w = cvtpk_s(v[6], v[7]);
;             af[mt][ks] = __builtin_bit_cast(bf16x8, pw);
;         }
	v_fma_f32 v79, -v78, v75, v74
	v_cmp_ge_f32_e64 s[12:13], 0, v79
	v_add_u32_e32 v79, 1, v75
	v_cndmask_b32_e32 v60, v76, v60, vcc
	v_cndmask_b32_e64 v78, v75, v78, s[12:13]
	v_fma_f32 v75, -v79, v75, v74
	v_cmp_lt_f32_e64 s[12:13], 0, v75
	s_nop 1
	v_cndmask_b32_e64 v75, v78, v79, s[12:13]
	v_mul_f32_e32 v78, 0x37800000, v75
	v_cndmask_b32_e64 v75, v75, v78, s[10:11]
	v_cmp_class_f32_e64 s[10:11], v74, v125
	s_nop 1
	v_cndmask_b32_e64 v74, v75, v74, s[10:11]
	v_div_scale_f32 v75, s[6:7], v74, v74, 1.0
	v_rcp_f32_e32 v78, v75
	s_nop 0
	v_fma_f32 v76, -v75, v78, 1.0
	v_fmac_f32_e32 v78, v76, v78
	v_div_scale_f32 v76, vcc, 1.0, v74, 1.0
	v_mul_f32_e32 v77, v76, v78
	v_fma_f32 v79, -v75, v77, v76
	v_fmac_f32_e32 v77, v79, v78
	v_fma_f32 v75, -v75, v77, v76
	v_div_scale_f32 v76, s[6:7], v60, v60, 1.0
	v_rcp_f32_e32 v79, v76
	v_div_fmas_f32 v75, v75, v78, v77
	v_div_fixup_f32 v75, v75, v74, 1.0
	v_fma_f32 v74, -v76, v79, 1.0
	v_fmac_f32_e32 v79, v74, v79
	v_div_scale_f32 v74, vcc, 1.0, v60, 1.0
	v_mul_f32_e32 v77, v74, v79
	v_fma_f32 v78, -v76, v77, v74
	v_fmac_f32_e32 v77, v78, v79
	v_fma_f32 v74, -v76, v77, v74
	v_div_fmas_f32 v74, v74, v79, v77
	v_lshlrev_b32_e32 v76, 16, v45
	v_and_b32_e32 v77, 0xffff0000, v45
	v_div_fixup_f32 v74, v74, v60, 1.0
	v_pk_fma_f32 v[76:77], v[80:81], s[50:51], v[76:77] op_sel_hi:[1,0,1] neg_lo:[1,0,0] neg_hi:[1,0,0]
	v_lshlrev_b32_e32 v60, 16, v61
	v_pk_mul_f32 v[76:77], v[74:75], v[76:77]
	v_and_b32_e32 v61, 0xffff0000, v61
	v_pk_fma_f32 v[76:77], v[76:77], v[132:133], v[134:135] op_sel_hi:[1,0,0]
	v_pk_fma_f32 v[60:61], v[80:81], s[50:51], v[60:61] op_sel_hi:[1,0,1] neg_lo:[1,0,0] neg_hi:[1,0,0]
	v_cvt_pk_bf16_f32 v45, v76, v77
	v_mov_b32_e32 v76, v68
	v_mov_b32_e32 v77, v70
	v_pk_mul_f32 v[78:79], v[76:77], s[50:51] op_sel_hi:[1,0]
	v_pk_mul_f32 v[60:61], v[74:75], v[60:61]
	v_pk_mov_b32 v[68:69], v[68:69], v[78:79] op_sel:[1,0]
	v_mov_b32_e32 v115, v78
	v_pk_mul_f32 v[68:69], v[68:69], v[114:115]
	v_mov_b32_e32 v115, v79
	v_sub_f32_e32 v68, v68, v69
	v_max_f32_e32 v68, 0, v68
	v_add_f32_e32 v68, 0x358637bd, v68
	v_mul_f32_e32 v69, 0x4f800000, v68
	v_cmp_gt_f32_e32 vcc, s57, v68
	v_mov_b32_e32 v81, v42
	s_nop 0
	v_cndmask_b32_e32 v70, v68, v69, vcc
	v_sqrt_f32_e32 v78, v70
	v_pk_fma_f32 v[68:69], v[60:61], v[128:129], v[130:131] op_sel_hi:[1,0,0]
	v_add_u32_e32 v60, -1, v78
	v_fma_f32 v61, -v60, v78, v70
	v_cmp_ge_f32_e64 s[10:11], 0, v61
	v_add_u32_e32 v75, 1, v78
	v_fma_f32 v80, -v75, v78, v70
	v_cndmask_b32_e64 v74, v78, v60, s[10:11]
	v_mov_b32_e32 v78, v71
	v_pk_mul_f32 v[60:61], v[78:79], v[114:115]
	v_cmp_lt_f32_e64 s[12:13], 0, v80
	v_sub_f32_e32 v60, v60, v61
	v_max_f32_e32 v60, 0, v60
	v_add_f32_e32 v60, 0x358637bd, v60
	v_mul_f32_e32 v61, 0x4f800000, v60
	v_cmp_gt_f32_e64 s[10:11], s57, v60
	v_cndmask_b32_e64 v71, v74, v75, s[12:13]
	v_mul_f32_e32 v74, 0x37800000, v71
	v_cndmask_b32_e64 v60, v60, v61, s[10:11]
	v_sqrt_f32_e32 v61, v60
	v_cndmask_b32_e32 v71, v71, v74, vcc
	v_cmp_class_f32_e32 vcc, v70, v125
	v_mov_b32_e32 v80, v40
	v_add_u32_e32 v75, -1, v61
	v_fma_f32 v78, -v75, v61, v60
	v_cmp_ge_f32_e64 s[12:13], 0, v78
	v_add_u32_e32 v78, 1, v61
	v_cndmask_b32_e32 v70, v71, v70, vcc
	v_cndmask_b32_e64 v75, v61, v75, s[12:13]
	v_fma_f32 v61, -v78, v61, v60
	v_cmp_lt_f32_e64 s[12:13], 0, v61
	v_pk_fma_f32 v[84:85], v[80:81], s[50:51], v[84:85] op_sel_hi:[1,0,1] neg_lo:[1,0,0] neg_hi:[1,0,0]
	s_nop 0
	v_cndmask_b32_e64 v61, v75, v78, s[12:13]
	v_mul_f32_e32 v75, 0x37800000, v61
	v_cndmask_b32_e64 v61, v61, v75, s[10:11]
	v_cmp_class_f32_e64 s[10:11], v60, v125
	s_nop 1
	v_cndmask_b32_e64 v60, v61, v60, s[10:11]
	v_div_scale_f32 v61, s[6:7], v60, v60, 1.0
	v_rcp_f32_e32 v75, v61
	s_nop 0
	v_fma_f32 v71, -v61, v75, 1.0
	v_fmac_f32_e32 v75, v71, v75
	v_div_scale_f32 v71, vcc, 1.0, v60, 1.0
	v_mul_f32_e32 v74, v71, v75
	v_fma_f32 v78, -v61, v74, v71
	v_fmac_f32_e32 v74, v78, v75
	v_fma_f32 v61, -v61, v74, v71
	v_div_scale_f32 v71, s[6:7], v70, v70, 1.0
	v_rcp_f32_e32 v78, v71
	v_div_fmas_f32 v61, v61, v75, v74
	v_div_fixup_f32 v61, v61, v60, 1.0
	v_fma_f32 v60, -v71, v78, 1.0
	v_fmac_f32_e32 v78, v60, v78
	v_div_scale_f32 v60, vcc, 1.0, v70, 1.0
	v_mul_f32_e32 v74, v60, v78
	v_fma_f32 v75, -v71, v74, v60
	v_fmac_f32_e32 v74, v75, v78
	v_fma_f32 v60, -v71, v74, v60
	v_div_fmas_f32 v60, v60, v78, v74
	v_div_fixup_f32 v60, v60, v70, 1.0
	v_lshlrev_b32_e32 v70, 16, v46
	v_and_b32_e32 v71, 0xffff0000, v46
	v_mov_b32_e32 v74, v64
	v_mov_b32_e32 v75, v66
	v_pk_fma_f32 v[70:71], v[76:77], s[50:51], v[70:71] op_sel_hi:[1,0,1] neg_lo:[1,0,0] neg_hi:[1,0,0]
	v_pk_mul_f32 v[78:79], v[74:75], s[50:51] op_sel_hi:[1,0]
	v_pk_mul_f32 v[70:71], v[70:71], v[60:61]
	v_pk_mov_b32 v[64:65], v[64:65], v[78:79] op_sel:[1,0]
	v_mov_b32_e32 v115, v78
	v_pk_fma_f32 v[70:71], v[70:71], v[132:133], v[134:135] op_sel_hi:[1,0,0]
	v_pk_mul_f32 v[64:65], v[64:65], v[114:115]
	v_cvt_pk_bf16_f32 v46, v70, v71
	v_lshlrev_b32_e32 v70, 16, v62
	v_and_b32_e32 v71, 0xffff0000, v62
	v_sub_f32_e32 v62, v64, v65
	v_max_f32_e32 v62, 0, v62
	v_add_f32_e32 v62, 0x358637bd, v62
	v_mul_f32_e32 v64, 0x4f800000, v62
	v_cmp_gt_f32_e32 vcc, s57, v62
	v_mov_b32_e32 v78, v67
	v_mov_b32_e32 v115, v79
	v_cndmask_b32_e32 v62, v62, v64, vcc
	v_sqrt_f32_e32 v66, v62
	v_pk_fma_f32 v[64:65], v[76:77], s[50:51], v[70:71] op_sel_hi:[1,0,1] neg_lo:[1,0,0] neg_hi:[1,0,0]
	v_add_u32_e32 v71, 1, v66
	v_pk_mul_f32 v[60:61], v[60:61], v[64:65]
	s_nop 0
	v_pk_fma_f32 v[64:65], v[60:61], v[128:129], v[130:131] op_sel_hi:[1,0,0]
	v_add_u32_e32 v60, -1, v66
	v_fma_f32 v61, -v60, v66, v62
	v_cmp_ge_f32_e64 s[10:11], 0, v61
	s_nop 1
	v_cndmask_b32_e64 v70, v66, v60, s[10:11]
; __device__ __forceinline__ float bflo(unsigned w) { return __uint_as_float(w << 16); }
; __device__ __forceinline__ float bfhi(unsigned w) { return __uint_as_float(w & 0xffff0000u); }
; __device__ __forceinline__ unsigned cvtpk_s(float lo, float hi) { f32x2_t v = {lo, hi}; bf16x2_t b = __builtin_convertvector(v, bf16x2_t); return __builtin_bit_cast(unsigned, b); }
; template <int NMT> __device__ __forceinline__ void sg_unit(int chunk, int g, int cofs, const bf16_t* VST, const bf16_t* QU, bf16_t* OB, const float* stats, const float* lng, const float* lnb, const bf16_t* WSb, const float* bs, int lane_) {
;     ...
;     for (int ks = 0; ks < 4; ++ks) {
;         float mu[8], rs[8];
; #pragma unroll
;         for (int j = 0; j < 8; ++j) { const float mean = sv[ks][j][0] * (1.0f / 512.0f); const float var = fmaxf(sv[ks][j][1] * (1.0f / 512.0f) - mean * mean, 0.f); mu[j] = mean; rs[j] = 1.0f / sqrtf(var + EPS); }
; #pragma unroll
;         for (int mt = 0; mt < NMT; ++mt) {
;             const u32x4 rw = raw[mt][ks];
;             float v[8]; v[0] = pg8::bflo(rw.x); v[1] = pg8::bfhi(rw.x); v[2] = pg8::bflo(rw.y); v[3] = pg8::bfhi(rw.y); v[4] = pg8::bflo(rw.z); v[5] = pg8::bfhi(rw.z); v[6] = pg8::bflo(rw.w); v[7] = pg8::bfhi(rw.w);
; #pragma unroll
;             for (int j = 0; j < 8; ++j) v[j] = (v[j] - mu[j]) * rs[j] * lg[mt] + lb[mt];
;             u32x4 pw; pw.x = cvtpk_s(v[0], v[1]); pw.y = cvtpk_s(v[2], v[3]); pw.z = cvtpk_s(v[4], v[5]); pw.w = cvtpk_s(v[6], v[7]);
;             af[mt][ks] = __builtin_bit_cast(bf16x8, pw);
;         }
	v_pk_mul_f32 v[60:61], v[78:79], v[114:115]
	v_fma_f32 v66, -v71, v66, v62
	v_sub_f32_e32 v60, v60, v61
	v_max_f32_e32 v60, 0, v60
	v_add_f32_e32 v60, 0x358637bd, v60
	v_mul_f32_e32 v61, 0x4f800000, v60
	v_cmp_gt_f32_e64 s[10:11], s57, v60
	v_cmp_lt_f32_e64 s[12:13], 0, v66
	s_nop 0
	v_cndmask_b32_e64 v60, v60, v61, s[10:11]
	v_sqrt_f32_e32 v61, v60
	v_cndmask_b32_e64 v66, v70, v71, s[12:13]
	v_mul_f32_e32 v67, 0x37800000, v66
	v_cndmask_b32_e32 v66, v66, v67, vcc
	v_add_u32_e32 v70, -1, v61
	v_fma_f32 v71, -v70, v61, v60
	v_cmp_ge_f32_e64 s[12:13], 0, v71
	v_add_u32_e32 v71, 1, v61
	v_cmp_class_f32_e32 vcc, v62, v125
	v_cndmask_b32_e64 v70, v61, v70, s[12:13]
	v_fma_f32 v61, -v71, v61, v60
	v_cmp_lt_f32_e64 s[12:13], 0, v61
	v_cndmask_b32_e32 v62, v66, v62, vcc
	s_nop 0
	v_cndmask_b32_e64 v61, v70, v71, s[12:13]
	v_mul_f32_e32 v70, 0x37800000, v61
	v_cndmask_b32_e64 v61, v61, v70, s[10:11]
	v_cmp_class_f32_e64 s[10:11], v60, v125
	s_nop 1
	v_cndmask_b32_e64 v60, v61, v60, s[10:11]
	v_div_scale_f32 v61, s[6:7], v60, v60, 1.0
	v_rcp_f32_e32 v70, v61
	s_nop 0
	v_fma_f32 v66, -v61, v70, 1.0
	v_fmac_f32_e32 v70, v66, v70
	v_div_scale_f32 v66, vcc, 1.0, v60, 1.0
	v_mul_f32_e32 v67, v66, v70
	v_fma_f32 v71, -v61, v67, v66
	v_fmac_f32_e32 v67, v71, v70
	v_fma_f32 v61, -v61, v67, v66
	v_div_scale_f32 v66, s[6:7], v62, v62, 1.0
	v_rcp_f32_e32 v71, v66
	v_div_fmas_f32 v61, v61, v70, v67
	v_div_fixup_f32 v61, v61, v60, 1.0
	v_fma_f32 v60, -v66, v71, 1.0
	v_fmac_f32_e32 v71, v60, v71
	v_div_scale_f32 v60, vcc, 1.0, v62, 1.0
	v_mul_f32_e32 v67, v60, v71
	v_fma_f32 v70, -v66, v67, v60
	v_fmac_f32_e32 v67, v70, v71
	v_fma_f32 v60, -v66, v67, v60
	v_div_fmas_f32 v60, v60, v71, v67
	v_lshlrev_b32_e32 v66, 16, v47
	v_and_b32_e32 v67, 0xffff0000, v47
	v_div_fixup_f32 v60, v60, v62, 1.0
	v_pk_fma_f32 v[66:67], v[74:75], s[50:51], v[66:67] op_sel_hi:[1,0,1] neg_lo:[1,0,0] neg_hi:[1,0,0]
	v_lshlrev_b32_e32 v62, 16, v63
	v_and_b32_e32 v63, 0xffff0000, v63
	v_pk_mul_f32 v[66:67], v[66:67], v[60:61]
	v_pk_fma_f32 v[62:63], v[74:75], s[50:51], v[62:63] op_sel_hi:[1,0,1] neg_lo:[1,0,0] neg_hi:[1,0,0]
	v_pk_fma_f32 v[66:67], v[66:67], v[132:133], v[134:135] op_sel_hi:[1,0,0]
	v_pk_mul_f32 v[60:61], v[62:63], v[60:61]
	v_mov_b32_e32 v70, v56
	v_mov_b32_e32 v71, v58
	v_cvt_pk_bf16_f32 v47, v66, v67
	v_pk_fma_f32 v[66:67], v[60:61], v[128:129], v[130:131] op_sel_hi:[1,0,0]
	v_cvt_pk_bf16_f32 v60, v72, v73
	v_pk_mul_f32 v[72:73], v[70:71], s[50:51] op_sel_hi:[1,0]
	v_cvt_pk_bf16_f32 v62, v64, v65
	v_pk_mov_b32 v[56:57], v[56:57], v[72:73] op_sel:[1,0]
	v_mov_b32_e32 v115, v72
	v_pk_mul_f32 v[56:57], v[56:57], v[114:115]
	v_mov_b32_e32 v72, v59
	v_sub_f32_e32 v56, v56, v57
	v_max_f32_e32 v56, 0, v56
	v_add_f32_e32 v56, 0x358637bd, v56
	v_mul_f32_e32 v57, 0x4f800000, v56
	v_cmp_gt_f32_e32 vcc, s57, v56
	v_mov_b32_e32 v115, v73
	v_cvt_pk_bf16_f32 v63, v66, v67
	v_cndmask_b32_e32 v58, v56, v57, vcc
	v_sqrt_f32_e32 v56, v58
	v_mov_b32_e32 v67, v54
	v_cvt_pk_bf16_f32 v61, v68, v69
	v_add_u32_e32 v57, -1, v56
	v_fma_f32 v64, -v57, v56, v58
	v_cmp_ge_f32_e64 s[10:11], 0, v64
	v_add_u32_e32 v65, 1, v56
	v_fma_f32 v66, -v65, v56, v58
	v_cndmask_b32_e64 v64, v56, v57, s[10:11]
	v_pk_mul_f32 v[56:57], v[72:73], v[114:115]
	v_cmp_lt_f32_e64 s[12:13], 0, v66
	v_sub_f32_e32 v56, v56, v57
	v_max_f32_e32 v56, 0, v56
	v_add_f32_e32 v56, 0x358637bd, v56
	v_mul_f32_e32 v57, 0x4f800000, v56
	v_cmp_gt_f32_e64 s[10:11], s57, v56
	v_cndmask_b32_e64 v59, v64, v65, s[12:13]
	v_mul_f32_e32 v64, 0x37800000, v59
	v_cndmask_b32_e64 v56, v56, v57, s[10:11]
	v_sqrt_f32_e32 v57, v56
	v_cndmask_b32_e32 v59, v59, v64, vcc
	v_cmp_class_f32_e32 vcc, v58, v125
	v_add_u32_e32 v65, -1, v57
	v_fma_f32 v66, -v65, v57, v56
	v_cmp_ge_f32_e64 s[12:13], 0, v66
	v_add_u32_e32 v66, 1, v57
	v_cndmask_b32_e32 v58, v59, v58, vcc
	v_cndmask_b32_e64 v65, v57, v65, s[12:13]
	v_fma_f32 v57, -v66, v57, v56
	v_cmp_lt_f32_e64 s[12:13], 0, v57
	s_nop 1
	v_cndmask_b32_e64 v57, v65, v66, s[12:13]
	v_mul_f32_e32 v65, 0x37800000, v57
	v_cndmask_b32_e64 v57, v57, v65, s[10:11]
	v_cmp_class_f32_e64 s[10:11], v56, v125
	s_nop 1
	v_cndmask_b32_e64 v56, v57, v56, s[10:11]
	v_div_scale_f32 v57, s[6:7], v56, v56, 1.0
	v_rcp_f32_e32 v65, v57
	s_nop 0
	v_fma_f32 v59, -v57, v65, 1.0
	v_fmac_f32_e32 v65, v59, v65
	v_div_scale_f32 v59, vcc, 1.0, v56, 1.0
	v_mul_f32_e32 v64, v59, v65
	v_fma_f32 v66, -v57, v64, v59
	v_fmac_f32_e32 v64, v66, v65
	v_fma_f32 v57, -v57, v64, v59
	v_div_scale_f32 v59, s[6:7], v58, v58, 1.0
	v_rcp_f32_e32 v66, v59
	v_div_fmas_f32 v57, v57, v65, v64
	v_div_fixup_f32 v57, v57, v56, 1.0
	v_fma_f32 v56, -v59, v66, 1.0
	v_fmac_f32_e32 v66, v56, v66
	v_div_scale_f32 v56, vcc, 1.0, v58, 1.0
	v_mul_f32_e32 v64, v56, v66
	v_fma_f32 v65, -v59, v64, v56
	v_fmac_f32_e32 v64, v65, v66
	v_fma_f32 v56, -v59, v64, v56
	v_div_fmas_f32 v56, v56, v66, v64
	v_div_fixup_f32 v56, v56, v58, 1.0
	v_lshlrev_b32_e32 v58, 16, v20
	v_and_b32_e32 v59, 0xffff0000, v20
	v_mov_b32_e32 v66, v52
	v_pk_fma_f32 v[58:59], v[70:71], s[50:51], v[58:59] op_sel_hi:[1,0,1] neg_lo:[1,0,0] neg_hi:[1,0,0]
	v_pk_mul_f32 v[68:69], v[66:67], s[50:51] op_sel_hi:[1,0]
	v_pk_mul_f32 v[58:59], v[56:57], v[58:59]
	v_pk_mov_b32 v[52:53], v[52:53], v[68:69] op_sel:[1,0]
	v_mov_b32_e32 v115, v68
	v_pk_fma_f32 v[58:59], v[132:133], v[58:59], v[134:135] op_sel_hi:[0,1,0]
	v_pk_mul_f32 v[52:53], v[52:53], v[114:115]
	v_cvt_pk_bf16_f32 v20, v58, v59
	v_lshlrev_b32_e32 v58, 16, v12
	v_and_b32_e32 v59, 0xffff0000, v12
	v_sub_f32_e32 v12, v52, v53
	v_max_f32_e32 v12, 0, v12
	v_add_f32_e32 v12, 0x358637bd, v12
	v_mul_f32_e32 v52, 0x4f800000, v12
	v_cmp_gt_f32_e32 vcc, s57, v12
; __device__ __forceinline__ float bflo(unsigned w) { return __uint_as_float(w << 16); }
; __device__ __forceinline__ float bfhi(unsigned w) { return __uint_as_float(w & 0xffff0000u); }
; __device__ __forceinline__ unsigned cvtpk_s(float lo, float hi) { f32x2_t v = {lo, hi}; bf16x2_t b = __builtin_convertvector(v, bf16x2_t); return __builtin_bit_cast(unsigned, b); }
; template <int NMT> __device__ __forceinline__ void sg_unit(int chunk, int g, int cofs, const bf16_t* VST, const bf16_t* QU, bf16_t* OB, const float* stats, const float* lng, const float* lnb, const bf16_t* WSb, const float* bs, int lane_) {
;     ...
;     for (int ks = 0; ks < 4; ++ks) {
;         float mu[8], rs[8];
; #pragma unroll
;         for (int j = 0; j < 8; ++j) { const float mean = sv[ks][j][0] * (1.0f / 512.0f); const float var = fmaxf(sv[ks][j][1] * (1.0f / 512.0f) - mean * mean, 0.f); mu[j] = mean; rs[j] = 1.0f / sqrtf(var + EPS); }
; #pragma unroll
;         for (int mt = 0; mt < NMT; ++mt) {
;             const u32x4 rw = raw[mt][ks];
;             float v[8]; v[0] = pg8::bflo(rw.x); v[1] = pg8::bfhi(rw.x); v[2] = pg8::bflo(rw.y); v[3] = pg8::bfhi(rw.y); v[4] = pg8::bflo(rw.z); v[5] = pg8::bfhi(rw.z); v[6] = pg8::bflo(rw.w); v[7] = pg8::bfhi(rw.w);
; #pragma unroll
;             for (int j = 0; j < 8; ++j) v[j] = (v[j] - mu[j]) * rs[j] * lg[mt] + lb[mt];
;             u32x4 pw; pw.x = cvtpk_s(v[0], v[1]); pw.y = cvtpk_s(v[2], v[3]); pw.z = cvtpk_s(v[4], v[5]); pw.w = cvtpk_s(v[6], v[7]);
;             af[mt][ks] = __builtin_bit_cast(bf16x8, pw);
;         }
	v_mov_b32_e32 v68, v55
	v_mov_b32_e32 v115, v69
	v_cndmask_b32_e32 v12, v12, v52, vcc
	v_sqrt_f32_e32 v54, v12
	v_pk_fma_f32 v[52:53], v[70:71], s[50:51], v[58:59] op_sel_hi:[1,0,1] neg_lo:[1,0,0] neg_hi:[1,0,0]
	s_nop 0
	v_pk_mul_f32 v[52:53], v[56:57], v[52:53]
	v_add_u32_e32 v57, 1, v54
	v_pk_fma_f32 v[64:65], v[128:129], v[52:53], v[130:131] op_sel_hi:[0,1,0]
	v_add_u32_e32 v52, -1, v54
	v_fma_f32 v53, -v52, v54, v12
	v_cmp_ge_f32_e64 s[10:11], 0, v53
	s_nop 1
	v_cndmask_b32_e64 v56, v54, v52, s[10:11]
	v_pk_mul_f32 v[52:53], v[68:69], v[114:115]
	v_fma_f32 v54, -v57, v54, v12
	v_sub_f32_e32 v52, v52, v53
	v_max_f32_e32 v52, 0, v52
	v_add_f32_e32 v52, 0x358637bd, v52
	v_mul_f32_e32 v53, 0x4f800000, v52
	v_cmp_gt_f32_e64 s[10:11], s57, v52
	v_cmp_lt_f32_e64 s[12:13], 0, v54
	s_nop 0
	v_cndmask_b32_e64 v52, v52, v53, s[10:11]
	v_sqrt_f32_e32 v53, v52
	v_cndmask_b32_e64 v54, v56, v57, s[12:13]
	v_mul_f32_e32 v55, 0x37800000, v54
	v_cndmask_b32_e32 v54, v54, v55, vcc
	v_add_u32_e32 v56, -1, v53
	v_fma_f32 v57, -v56, v53, v52
	v_cmp_ge_f32_e64 s[12:13], 0, v57
	v_add_u32_e32 v57, 1, v53
	v_cmp_class_f32_e32 vcc, v12, v125
	v_cndmask_b32_e64 v56, v53, v56, s[12:13]
	v_fma_f32 v53, -v57, v53, v52
	v_cmp_lt_f32_e64 s[12:13], 0, v53
	v_cndmask_b32_e32 v12, v54, v12, vcc
	s_nop 0
	v_cndmask_b32_e64 v53, v56, v57, s[12:13]
	v_mul_f32_e32 v56, 0x37800000, v53
	v_cndmask_b32_e64 v53, v53, v56, s[10:11]
	v_cmp_class_f32_e64 s[10:11], v52, v125
	s_nop 1
	v_cndmask_b32_e64 v52, v53, v52, s[10:11]
	v_div_scale_f32 v53, s[6:7], v52, v52, 1.0
	v_rcp_f32_e32 v56, v53
	s_nop 0
	v_fma_f32 v54, -v53, v56, 1.0
	v_fmac_f32_e32 v56, v54, v56
	v_div_scale_f32 v54, vcc, 1.0, v52, 1.0
	v_mul_f32_e32 v55, v54, v56
	v_fma_f32 v57, -v53, v55, v54
	v_fmac_f32_e32 v55, v57, v56
	v_fma_f32 v53, -v53, v55, v54
	v_div_scale_f32 v54, s[6:7], v12, v12, 1.0
	v_rcp_f32_e32 v57, v54
	v_div_fmas_f32 v53, v53, v56, v55
	v_div_fixup_f32 v53, v53, v52, 1.0
	v_fma_f32 v52, -v54, v57, 1.0
	v_fmac_f32_e32 v57, v52, v57
	v_div_scale_f32 v52, vcc, 1.0, v12, 1.0
	v_mul_f32_e32 v55, v52, v57
	v_fma_f32 v56, -v54, v55, v52
	v_fmac_f32_e32 v55, v56, v57
	v_fma_f32 v52, -v54, v55, v52
	v_div_fmas_f32 v52, v52, v57, v55
	v_lshlrev_b32_e32 v54, 16, v21
	v_and_b32_e32 v55, 0xffff0000, v21
	v_div_fixup_f32 v52, v52, v12, 1.0
	v_pk_fma_f32 v[54:55], v[66:67], s[50:51], v[54:55] op_sel_hi:[1,0,1] neg_lo:[1,0,0] neg_hi:[1,0,0]
	v_lshlrev_b32_e32 v12, 16, v13
	v_pk_mul_f32 v[54:55], v[52:53], v[54:55]
	v_and_b32_e32 v13, 0xffff0000, v13
	v_pk_fma_f32 v[54:55], v[132:133], v[54:55], v[134:135] op_sel_hi:[0,1,0]
	v_cvt_pk_bf16_f32 v21, v54, v55
	v_mov_b32_e32 v54, v48
	v_mov_b32_e32 v55, v50
	v_pk_mul_f32 v[56:57], v[54:55], s[50:51] op_sel_hi:[1,0]
	v_pk_fma_f32 v[12:13], v[66:67], s[50:51], v[12:13] op_sel_hi:[1,0,1] neg_lo:[1,0,0] neg_hi:[1,0,0]
	v_pk_mov_b32 v[48:49], v[48:49], v[56:57] op_sel:[1,0]
	v_mov_b32_e32 v115, v56
	v_pk_mul_f32 v[48:49], v[48:49], v[114:115]
	v_pk_mul_f32 v[12:13], v[52:53], v[12:13]
	v_sub_f32_e32 v48, v48, v49
	v_max_f32_e32 v48, 0, v48
	v_add_f32_e32 v48, 0x358637bd, v48
	v_mul_f32_e32 v49, 0x4f800000, v48
	v_cmp_gt_f32_e32 vcc, s57, v48
	v_pk_fma_f32 v[66:67], v[128:129], v[12:13], v[130:131] op_sel_hi:[0,1,0]
	v_mov_b32_e32 v56, v51
	v_cndmask_b32_e32 v48, v48, v49, vcc
	v_sqrt_f32_e32 v49, v48
	v_mov_b32_e32 v115, v57
	v_add_u32_e32 v12, -1, v49
	v_fma_f32 v13, -v12, v49, v48
	v_cmp_ge_f32_e64 s[10:11], 0, v13
	v_add_u32_e32 v52, 1, v49
	s_nop 0
	v_cndmask_b32_e64 v50, v49, v12, s[10:11]
	v_pk_mul_f32 v[12:13], v[56:57], v[114:115]
	v_fma_f32 v49, -v52, v49, v48
	v_sub_f32_e32 v12, v12, v13
	v_max_f32_e32 v12, 0, v12
	v_add_f32_e32 v12, 0x358637bd, v12
	v_mul_f32_e32 v13, 0x4f800000, v12
	v_cmp_gt_f32_e64 s[10:11], s57, v12
	v_cmp_lt_f32_e64 s[12:13], 0, v49
	s_nop 0
	v_cndmask_b32_e64 v12, v12, v13, s[10:11]
	v_sqrt_f32_e32 v13, v12
	v_cndmask_b32_e64 v49, v50, v52, s[12:13]
	v_mul_f32_e32 v50, 0x37800000, v49
	v_cndmask_b32_e32 v49, v49, v50, vcc
	v_add_u32_e32 v51, -1, v13
	v_fma_f32 v52, -v51, v13, v12
	v_cmp_ge_f32_e64 s[12:13], 0, v52
	v_add_u32_e32 v52, 1, v13
	v_cmp_class_f32_e32 vcc, v48, v125
	v_cndmask_b32_e64 v51, v13, v51, s[12:13]
	v_fma_f32 v13, -v52, v13, v12
	v_cmp_lt_f32_e64 s[12:13], 0, v13
	v_cndmask_b32_e32 v48, v49, v48, vcc
	s_nop 0
	v_cndmask_b32_e64 v13, v51, v52, s[12:13]
	v_mul_f32_e32 v51, 0x37800000, v13
	v_cndmask_b32_e64 v13, v13, v51, s[10:11]
	v_cmp_class_f32_e64 s[10:11], v12, v125
	s_nop 1
	v_cndmask_b32_e64 v12, v13, v12, s[10:11]
	v_div_scale_f32 v13, s[6:7], v12, v12, 1.0
	v_rcp_f32_e32 v51, v13
	s_nop 0
	v_fma_f32 v49, -v13, v51, 1.0
	v_fmac_f32_e32 v51, v49, v51
	v_div_scale_f32 v49, vcc, 1.0, v12, 1.0
	v_mul_f32_e32 v50, v49, v51
	v_fma_f32 v52, -v13, v50, v49
	v_fmac_f32_e32 v50, v52, v51
	v_fma_f32 v13, -v13, v50, v49
	v_div_scale_f32 v49, s[6:7], v48, v48, 1.0
	v_rcp_f32_e32 v52, v49
	v_div_fmas_f32 v13, v13, v51, v50
	v_div_fixup_f32 v13, v13, v12, 1.0
	v_fma_f32 v12, -v49, v52, 1.0
	v_fmac_f32_e32 v52, v12, v52
	v_div_scale_f32 v12, vcc, 1.0, v48, 1.0
	v_mul_f32_e32 v50, v12, v52
	v_fma_f32 v51, -v49, v50, v12
	v_fmac_f32_e32 v50, v51, v52
	v_fma_f32 v12, -v49, v50, v12
	v_div_fmas_f32 v12, v12, v52, v50
	v_div_fixup_f32 v12, v12, v48, 1.0
	v_lshlrev_b32_e32 v48, 16, v22
	v_and_b32_e32 v49, 0xffff0000, v22
	v_pk_fma_f32 v[48:49], v[54:55], s[50:51], v[48:49] op_sel_hi:[1,0,1] neg_lo:[1,0,0] neg_hi:[1,0,0]
	v_pk_mul_f32 v[50:51], v[80:81], s[50:51] op_sel_hi:[1,0]
	v_pk_mul_f32 v[48:49], v[48:49], v[12:13]
	v_pk_mov_b32 v[40:41], v[40:41], v[50:51] op_sel:[1,0]
	v_mov_b32_e32 v115, v50
; template <int NMT> __device__ __forceinline__ void sg_unit(int chunk, int g, int cofs, const bf16_t* VST, const bf16_t* QU, bf16_t* OB, const float* stats, const float* lng, const float* lnb, const bf16_t* WSb, const float* bs, int lane_) {
;     ...
;         for (int j = 0; j < 8; ++j) { const float mean = sv[ks][j][0] * (1.0f / 512.0f); const float var = fmaxf(sv[ks][j][1] * (1.0f / 512.0f) - mean * mean, 0.f); mu[j] = mean; rs[j] = 1.0f / sqrtf(var + EPS); }
; #pragma unroll
;         for (int mt = 0; mt < NMT; ++mt) {
;             const u32x4 rw = raw[mt][ks];
;             float v[8]; v[0] = pg8::bflo(rw.x); v[1] = pg8::bfhi(rw.x); v[2] = pg8::bflo(rw.y); v[3] = pg8::bfhi(rw.y); v[4] = pg8::bflo(rw.z); v[5] = pg8::bfhi(rw.z); v[6] = pg8::bflo(rw.w); v[7] = pg8::bfhi(rw.w);
; #pragma unroll
;             for (int j = 0; j < 8; ++j) v[j] = (v[j] - mu[j]) * rs[j] * lg[mt] + lb[mt];
;             u32x4 pw; pw.x = cvtpk_s(v[0], v[1]); pw.y = cvtpk_s(v[2], v[3]); pw.z = cvtpk_s(v[4], v[5]); pw.w = cvtpk_s(v[6], v[7]);
;             af[mt][ks] = __builtin_bit_cast(bf16x8, pw);
;         }
;     }
;     const f32x4 z4 = {0.f, 0.f, 0.f, 0.f};
; #pragma unroll
;     for (int nt = 0; nt < 8; ++nt) {
;         const int cur = nt & 1, nxt = cur ^ 1;
;         if (nt < 7) {
; #pragma unroll
;             for (int ks = 0; ks < 4; ++ks) wf[nxt][ks] = *(const bf16x8*)(wp0 + (size_t)(nt + 1) * 16 * 128 + ks * 32);
; #pragma unroll
;             for (int mt = 0; mt < NMT; ++mt) uu[nxt][mt] = *(const u32x2*)(QU + (size_t)(R0 + (nt + 1) * 16 + fr) * 1024 + 512 + ch0 + mt * 16 + 4 * fq);
;             bsv[nxt] = bs[g * 128 + (nt + 1) * 16 + fr];
;         }
;         f32x4 a[NMT];
; #pragma unroll
;         for (int mt = 0; mt < NMT; ++mt) a[mt] = z4;
; #pragma unroll
;         for (int ks = 0; ks < 4; ++ks)
; #pragma unroll
;             for (int mt = 0; mt < NMT; ++mt) a[mt] = MFMA16(af[mt][ks], wf[cur][ks], a[mt]);
;         const float bv = bsv[cur];
;         unsigned q[NMT][2];
; #pragma unroll
;         for (int mt = 0; mt < NMT; ++mt) { const u32x2 u0 = uu[cur][mt];
;             q[mt][0] = cvtpk_s(pg8::bflo(u0.x) * (a[mt][0] + bv), pg8::bfhi(u0.x) * (a[mt][1] + bv)); q[mt][1] = cvtpk_s(pg8::bflo(u0.y) * (a[mt][2] + bv), pg8::bfhi(u0.y) * (a[mt][3] + bv)); }
;         const size_t uo = (size_t)(R0 + nt * 16 + fr) * 1024 + 512 + ch0;
; #pragma unroll
	v_pk_fma_f32 v[48:49], v[132:133], v[48:49], v[134:135] op_sel_hi:[0,1,0]
	v_pk_mul_f32 v[40:41], v[40:41], v[114:115]
	v_cvt_pk_bf16_f32 v22, v48, v49
	v_lshlrev_b32_e32 v48, 16, v14
	v_and_b32_e32 v49, 0xffff0000, v14
	v_sub_f32_e32 v14, v40, v41
	v_max_f32_e32 v14, 0, v14
	v_add_f32_e32 v14, 0x358637bd, v14
	v_mul_f32_e32 v40, 0x4f800000, v14
	v_cmp_gt_f32_e32 vcc, s57, v14
	v_mov_b32_e32 v50, v43
	v_mov_b32_e32 v115, v51
	v_cndmask_b32_e32 v14, v14, v40, vcc
	v_sqrt_f32_e32 v42, v14
	v_pk_fma_f32 v[40:41], v[54:55], s[50:51], v[48:49] op_sel_hi:[1,0,1] neg_lo:[1,0,0] neg_hi:[1,0,0]
	s_nop 0
	v_pk_mul_f32 v[12:13], v[12:13], v[40:41]
	v_add_u32_e32 v41, 1, v42
	v_pk_fma_f32 v[82:83], v[128:129], v[12:13], v[130:131] op_sel_hi:[0,1,0]
	v_add_u32_e32 v12, -1, v42
	v_fma_f32 v13, -v12, v42, v14
	v_cmp_ge_f32_e64 s[10:11], 0, v13
	s_nop 1
	v_cndmask_b32_e64 v40, v42, v12, s[10:11]
	v_pk_mul_f32 v[12:13], v[50:51], v[114:115]
	v_fma_f32 v42, -v41, v42, v14
	v_sub_f32_e32 v12, v12, v13
	v_max_f32_e32 v12, 0, v12
	v_add_f32_e32 v12, 0x358637bd, v12
	v_mul_f32_e32 v13, 0x4f800000, v12
	v_cmp_gt_f32_e64 s[10:11], s57, v12
	v_cmp_lt_f32_e64 s[12:13], 0, v42
	s_nop 0
	v_cndmask_b32_e64 v12, v12, v13, s[10:11]
	v_sqrt_f32_e32 v13, v12
	v_cndmask_b32_e64 v40, v40, v41, s[12:13]
	v_mul_f32_e32 v41, 0x37800000, v40
	v_add_u32_e32 v42, -1, v13
	v_fma_f32 v43, -v42, v13, v12
	v_cmp_ge_f32_e64 s[12:13], 0, v43
	v_add_u32_e32 v43, 1, v13
	s_nop 0
	v_cndmask_b32_e64 v42, v13, v42, s[12:13]
	v_fma_f32 v13, -v43, v13, v12
	v_cmp_lt_f32_e64 s[12:13], 0, v13
	s_nop 1
	v_cndmask_b32_e64 v13, v42, v43, s[12:13]
	v_mul_f32_e32 v42, 0x37800000, v13
	v_cndmask_b32_e64 v13, v13, v42, s[10:11]
	v_cmp_class_f32_e64 s[10:11], v12, v125
	s_nop 1
	v_cndmask_b32_e64 v71, v13, v12, s[10:11]
	v_div_scale_f32 v76, s[6:7], v71, v71, 1.0
	v_rcp_f32_e32 v77, v76
	v_cndmask_b32_e32 v12, v40, v41, vcc
	v_cmp_class_f32_e32 vcc, v14, v125
	v_add_co_u32_e64 v40, s[10:11], s58, v120
	s_nop 0
	v_cndmask_b32_e32 v14, v12, v14, vcc
	v_fma_f32 v12, -v76, v77, 1.0
	v_fmac_f32_e32 v77, v12, v77
	v_or_b32_e32 v12, 16, v118
	v_ashrrev_i32_e32 v13, 31, v12
	v_lshlrev_b64 v[68:69], 11, v[12:13]
	v_lshl_add_u64 v[12:13], s[26:27], 0, v[68:69]
	v_addc_co_u32_e64 v41, s[10:11], 0, v121, s[10:11]
	v_lshl_add_u64 v[12:13], v[12:13], 0, s[42:43]
	global_load_dwordx4 v[56:59], v[40:41], off
	global_load_dwordx4 v[52:55], v[40:41], off offset:64
	global_load_dwordx4 v[48:51], v[40:41], off offset:128
	s_nop 0
	global_load_dwordx4 v[40:43], v[40:41], off offset:192
	v_lshl_add_u64 v[12:13], v[12:13], 0, v[138:139]
	global_load_dwordx2 v[74:75], v[12:13], off offset:1024
	global_load_dwordx2 v[72:73], v[12:13], off offset:1056
	global_load_dword v70, v112, s[52:53] offset:64
	v_div_scale_f32 v78, vcc, 1.0, v71, 1.0
	v_mul_f32_e32 v12, v78, v77
	v_fma_f32 v13, -v76, v12, v78
	v_fmac_f32_e32 v12, v13, v77
	v_fma_f32 v13, -v76, v12, v78
	v_div_scale_f32 v76, s[6:7], v14, v14, 1.0
	v_rcp_f32_e32 v78, v76
	v_div_fmas_f32 v12, v13, v77, v12
	v_div_fixup_f32 v13, v12, v71, 1.0
	v_fma_f32 v12, -v76, v78, 1.0
	v_fmac_f32_e32 v78, v12, v78
	v_div_scale_f32 v12, vcc, 1.0, v14, 1.0
	v_mul_f32_e32 v71, v12, v78
	v_fma_f32 v77, -v76, v71, v12
	v_fmac_f32_e32 v71, v77, v78
	v_fma_f32 v12, -v76, v71, v12
	v_div_fmas_f32 v12, v12, v78, v71
	s_waitcnt vmcnt(13)
	v_mfma_f32_16x16x32_bf16 v[76:79], v[0:3], v[32:35], 0
	v_div_fixup_f32 v12, v12, v14, 1.0
	v_pk_mul_f32 v[84:85], v[84:85], v[12:13]
	v_lshlrev_b32_e32 v14, 16, v15
	v_mfma_f32_16x16x32_bf16 v[32:35], v[4:7], v[32:35], 0
	v_fma_f32 v84, v132, v84, v134
	v_fma_f32 v85, v132, v85, v134
	v_and_b32_e32 v15, 0xffff0000, v15
	v_cvt_pk_bf16_f32 v23, v84, v85
	s_waitcnt vmcnt(12)
	v_mfma_f32_16x16x32_bf16 v[76:79], v[8:11], v[28:31], v[76:79]
	v_fma_f32 v14, -v80, s50, v14
	v_fma_f32 v15, -v81, s50, v15
	v_cmp_lt_i32_e32 vcc, v204, v203
	v_pk_mul_f32 v[12:13], v[14:15], v[12:13]
	v_mfma_f32_16x16x32_bf16 v[28:31], v[36:39], v[28:31], v[32:35]
	v_fma_f32 v80, v128, v12, v130
	v_fma_f32 v81, v128, v13, v130
	v_cvt_pk_bf16_f32 v12, v64, v65
	v_cvt_pk_bf16_f32 v13, v66, v67
	s_waitcnt vmcnt(11)
	v_mfma_f32_16x16x32_bf16 v[32:35], v[44:47], v[24:27], v[76:79]
	v_cvt_pk_bf16_f32 v14, v82, v83
	v_cvt_pk_bf16_f32 v15, v80, v81
	v_and_b32_e32 v64, 16, v129
	v_mfma_f32_16x16x32_bf16 v[24:27], v[60:63], v[24:27], v[28:31]
	v_cmp_eq_u32_e64 s[12:13], 0, v64
	v_cmp_ne_u32_e64 s[10:11], 0, v64
	v_add_u32_e32 v64, 12, v116
	s_waitcnt vmcnt(10)
	v_mfma_f32_16x16x32_bf16 v[28:31], v[20:23], v[16:19], v[32:35]
	v_ashrrev_i32_e32 v65, 31, v64
	s_nop 1
	v_cndmask_b32_e32 v32, v202, v204, vcc
	v_lshlrev_b32_e32 v82, 2, v32
	v_mfma_f32_16x16x32_bf16 v[32:35], v[12:15], v[16:19], v[24:27]
	s_waitcnt vmcnt(9)
	v_lshlrev_b32_e32 v16, 16, v136
	v_and_b32_e32 v17, 0xffff0000, v136
	s_waitcnt vmcnt(7)
	v_pk_add_f32 v[18:19], v[124:125], v[28:29] op_sel_hi:[0,1]
	v_pk_mul_f32 v[16:17], v[18:19], v[16:17]
	v_lshlrev_b32_e32 v18, 16, v137
	v_and_b32_e32 v19, 0xffff0000, v137
	v_pk_add_f32 v[24:25], v[124:125], v[30:31] op_sel_hi:[0,1]
	v_pk_mul_f32 v[18:19], v[24:25], v[18:19]
	v_cvt_pk_bf16_f32 v16, v16, v17
	v_cvt_pk_bf16_f32 v17, v18, v19
	v_lshlrev_b32_e32 v18, 16, v126
	v_and_b32_e32 v19, 0xffff0000, v126
	v_pk_add_f32 v[24:25], v[124:125], v[32:33] op_sel_hi:[0,1]
	v_pk_mul_f32 v[18:19], v[24:25], v[18:19]
	v_pk_add_f32 v[24:25], v[124:125], v[34:35] op_sel_hi:[0,1]
	v_cvt_pk_bf16_f32 v26, v18, v19
	v_lshlrev_b32_e32 v18, 16, v127
	v_and_b32_e32 v19, 0xffff0000, v127
	v_pk_mul_f32 v[18:19], v[24:25], v[18:19]
	v_mov_b64_e32 v[24:25], v[116:117]
	v_cvt_pk_bf16_f32 v27, v18, v19
	v_cndmask_b32_e64 v18, v16, v26, s[12:13]
	v_cndmask_b32_e64 v19, v17, v27, s[12:13]
	ds_bpermute_b32 v29, v82, v19
	ds_bpermute_b32 v28, v82, v18
	s_waitcnt lgkmcnt(1)
; __device__ __forceinline__ float bflo(unsigned w) { return __uint_as_float(w << 16); }
; __device__ __forceinline__ float bfhi(unsigned w) { return __uint_as_float(w & 0xffff0000u); }
; __device__ __forceinline__ unsigned cvtpk_s(float lo, float hi) { f32x2_t v = {lo, hi}; bf16x2_t b = __builtin_convertvector(v, bf16x2_t); return __builtin_bit_cast(unsigned, b); }
; #define MFMA16(a, b, c) __builtin_amdgcn_mfma_f32_16x16x32_bf16((a), (b), (c), 0, 0, 0)
; template <int NMT> __device__ __forceinline__ void sg_unit(int chunk, int g, int cofs, const bf16_t* VST, const bf16_t* QU, bf16_t* OB, const float* stats, const float* lng, const float* lnb, const bf16_t* WSb, const float* bs, int lane_) {
;     ...
;     for (int nt = 0; nt < 8; ++nt) {
;         const int cur = nt & 1, nxt = cur ^ 1;
;         if (nt < 7) {
; #pragma unroll
;             for (int ks = 0; ks < 4; ++ks) wf[nxt][ks] = *(const bf16x8*)(wp0 + (size_t)(nt + 1) * 16 * 128 + ks * 32);
; #pragma unroll
;             for (int mt = 0; mt < NMT; ++mt) uu[nxt][mt] = *(const u32x2*)(QU + (size_t)(R0 + (nt + 1) * 16 + fr) * 1024 + 512 + ch0 + mt * 16 + 4 * fq);
;             bsv[nxt] = bs[g * 128 + (nt + 1) * 16 + fr];
;         }
;         f32x4 a[NMT];
; #pragma unroll
;         for (int mt = 0; mt < NMT; ++mt) a[mt] = z4;
; #pragma unroll
;         for (int ks = 0; ks < 4; ++ks)
; #pragma unroll
;             for (int mt = 0; mt < NMT; ++mt) a[mt] = MFMA16(af[mt][ks], wf[cur][ks], a[mt]);
;         const float bv = bsv[cur];
;         unsigned q[NMT][2];
; #pragma unroll
;         for (int mt = 0; mt < NMT; ++mt) { const u32x2 u0 = uu[cur][mt];
;             q[mt][0] = cvtpk_s(pg8::bflo(u0.x) * (a[mt][0] + bv), pg8::bfhi(u0.x) * (a[mt][1] + bv)); q[mt][1] = cvtpk_s(pg8::bflo(u0.y) * (a[mt][2] + bv), pg8::bfhi(u0.y) * (a[mt][3] + bv)); }
;         const size_t uo = (size_t)(R0 + nt * 16 + fr) * 1024 + 512 + ch0;
; #pragma unroll
;         for (int mp = 0; mp < NMT / 2; ++mp) { int co; const u32x4 w = pg8::quad_swap(q[2 * mp][0], q[2 * mp][1], q[2 * mp + 1][0], q[2 * mp + 1][1], fq, co); *(u32x4*)(OB + uo + mp * 32 + co) = w; }
	v_mov_b32_e32 v19, v29
	s_waitcnt lgkmcnt(0)
	v_mov_b32_e32 v18, v28
	s_and_saveexec_b64 s[14:15], s[10:11]
	v_mov_b64_e32 v[24:25], v[64:65]
	v_mov_b32_e32 v19, v27
	v_mov_b32_e32 v18, v26
	v_mov_b32_e32 v17, v29
	v_mov_b32_e32 v16, v28
	s_or_b64 exec, exec, s[14:15]
	s_waitcnt vmcnt(6)
	v_mfma_f32_16x16x32_bf16 v[26:29], v[0:3], v[56:59], 0
	s_add_u32 s14, s29, s42
	s_addc_u32 s15, s54, 0
	v_lshl_add_u64 v[30:31], s[14:15], 0, v[122:123]
	v_mfma_f32_16x16x32_bf16 v[56:59], v[4:7], v[56:59], 0
	v_lshl_add_u64 v[24:25], v[24:25], 1, v[30:31]
	global_store_dwordx4 v[24:25], v[16:19], off offset:1024
	v_lshl_add_u64 v[66:67], s[52:53], 0, v[112:113]
	s_waitcnt vmcnt(6)
	v_mfma_f32_16x16x32_bf16 v[76:79], v[8:11], v[52:55], v[26:29]
	v_add_co_u32_e32 v16, vcc, s59, v120
	v_mfma_f32_16x16x32_bf16 v[54:57], v[36:39], v[52:55], v[56:59]
	v_or_b32_e32 v52, 32, v118
	v_ashrrev_i32_e32 v53, 31, v52
	v_lshlrev_b64 v[52:53], 11, v[52:53]
	v_lshl_add_u64 v[58:59], s[26:27], 0, v[52:53]
	v_lshl_add_u64 v[58:59], v[58:59], 0, s[42:43]
	v_addc_co_u32_e32 v17, vcc, 0, v121, vcc
	s_waitcnt vmcnt(5)
	v_mfma_f32_16x16x32_bf16 v[78:81], v[44:47], v[48:51], v[76:79]
	global_load_dwordx4 v[32:35], v[16:17], off
	global_load_dwordx4 v[24:27], v[16:17], off offset:64
	global_load_dwordx4 v[28:31], v[16:17], off offset:128
	s_nop 0
	global_load_dwordx4 v[16:19], v[16:17], off offset:192
	v_mfma_f32_16x16x32_bf16 v[48:51], v[60:63], v[48:51], v[54:57]
	s_nop 2
	v_lshl_add_u64 v[54:55], v[116:117], 1, v[58:59]
	global_load_dwordx2 v[76:77], v[54:55], off offset:1024
	global_load_dwordx2 v[58:59], v[54:55], off offset:1056
	s_waitcnt vmcnt(10)
	v_mfma_f32_16x16x32_bf16 v[78:81], v[20:23], v[40:43], v[78:81]
	global_load_dword v54, v[66:67], off offset:128
	v_mfma_f32_16x16x32_bf16 v[84:87], v[12:15], v[40:43], v[48:51]
	s_waitcnt vmcnt(10)
	v_lshlrev_b32_e32 v40, 16, v74
	v_and_b32_e32 v41, 0xffff0000, v74
	s_waitcnt vmcnt(8)
	s_nop 1
	v_pk_add_f32 v[42:43], v[70:71], v[78:79] op_sel_hi:[0,1]
	v_pk_mul_f32 v[40:41], v[42:43], v[40:41]
	v_lshlrev_b32_e32 v42, 16, v75
	v_and_b32_e32 v43, 0xffff0000, v75
	v_pk_add_f32 v[48:49], v[70:71], v[80:81] op_sel_hi:[0,1]
	v_pk_mul_f32 v[42:43], v[48:49], v[42:43]
	v_cvt_pk_bf16_f32 v40, v40, v41
	v_cvt_pk_bf16_f32 v41, v42, v43
	v_lshlrev_b32_e32 v42, 16, v72
	v_and_b32_e32 v43, 0xffff0000, v72
	v_pk_add_f32 v[48:49], v[70:71], v[84:85] op_sel_hi:[0,1]
	v_pk_mul_f32 v[42:43], v[48:49], v[42:43]
	v_pk_add_f32 v[48:49], v[70:71], v[86:87] op_sel_hi:[0,1]
	v_cvt_pk_bf16_f32 v50, v42, v43
	v_lshlrev_b32_e32 v42, 16, v73
	v_and_b32_e32 v43, 0xffff0000, v73
	v_pk_mul_f32 v[42:43], v[48:49], v[42:43]
	v_mov_b64_e32 v[48:49], v[116:117]
	v_cvt_pk_bf16_f32 v51, v42, v43
	v_cndmask_b32_e64 v42, v40, v50, s[12:13]
	v_cndmask_b32_e64 v43, v41, v51, s[12:13]
	ds_bpermute_b32 v56, v82, v43
	ds_bpermute_b32 v55, v82, v42
	s_waitcnt lgkmcnt(1)
	v_mov_b32_e32 v43, v56
	s_waitcnt lgkmcnt(0)
	v_mov_b32_e32 v42, v55
	s_and_saveexec_b64 s[52:53], s[10:11]
	v_mov_b64_e32 v[48:49], v[64:65]
	v_mov_b32_e32 v43, v51
	v_mov_b32_e32 v42, v50
	v_mov_b32_e32 v41, v56
	v_mov_b32_e32 v40, v55
	s_or_b64 exec, exec, s[52:53]
	s_waitcnt vmcnt(6)
	v_mfma_f32_16x16x32_bf16 v[70:73], v[0:3], v[32:35], 0
	v_lshl_add_u64 v[50:51], s[14:15], 0, v[68:69]
	v_lshl_add_u64 v[48:49], v[48:49], 1, v[50:51]
	v_add_co_u32_e32 v56, vcc, 0x3000, v120
	v_mfma_f32_16x16x32_bf16 v[32:35], v[4:7], v[32:35], 0
	global_store_dwordx4 v[48:49], v[40:43], off offset:1024
	v_addc_co_u32_e32 v57, vcc, 0, v121, vcc
	s_waitcnt vmcnt(6)
	v_mfma_f32_16x16x32_bf16 v[68:71], v[8:11], v[24:27], v[70:73]
	global_load_dwordx4 v[40:43], v[56:57], off
	global_load_dwordx4 v[48:51], v[56:57], off offset:64
	v_mfma_f32_16x16x32_bf16 v[72:75], v[36:39], v[24:27], v[32:35]
	s_nop 2
	global_load_dwordx4 v[32:35], v[56:57], off offset:128
	global_load_dwordx4 v[24:27], v[56:57], off offset:192
	v_or_b32_e32 v56, 48, v118
	v_ashrrev_i32_e32 v57, 31, v56
	s_waitcnt vmcnt(9)
	v_mfma_f32_16x16x32_bf16 v[68:71], v[44:47], v[28:31], v[68:71]
	v_lshlrev_b64 v[56:57], 11, v[56:57]
	v_lshl_add_u64 v[78:79], s[26:27], 0, v[56:57]
	v_lshl_add_u64 v[78:79], v[78:79], 0, s[42:43]
	v_mfma_f32_16x16x32_bf16 v[28:31], v[60:63], v[28:31], v[72:75]
	s_nop 2
	v_lshl_add_u64 v[72:73], v[116:117], 1, v[78:79]
	global_load_dwordx2 v[80:81], v[72:73], off offset:1024
	s_nop 0
	global_load_dwordx2 v[72:73], v[72:73], off offset:1056
	s_waitcnt vmcnt(10)
	v_mfma_f32_16x16x32_bf16 v[84:87], v[20:23], v[16:19], v[68:71]
	s_nop 2
	global_load_dword v68, v[66:67], off offset:192
	v_mfma_f32_16x16x32_bf16 v[88:91], v[12:15], v[16:19], v[28:31]
	s_waitcnt vmcnt(10)
	v_lshlrev_b32_e32 v70, 16, v76
	v_and_b32_e32 v71, 0xffff0000, v76
	s_waitcnt vmcnt(8)
	v_pk_add_f32 v[16:17], v[54:55], v[84:85] op_sel_hi:[0,1]
	v_lshlrev_b32_e32 v18, 16, v77
	v_and_b32_e32 v19, 0xffff0000, v77
	v_pk_add_f32 v[28:29], v[54:55], v[86:87] op_sel_hi:[0,1]
	v_pk_mul_f32 v[16:17], v[16:17], v[70:71]
	v_pk_mul_f32 v[18:19], v[28:29], v[18:19]
	v_cvt_pk_bf16_f32 v16, v16, v17
	v_cvt_pk_bf16_f32 v17, v18, v19
	v_lshlrev_b32_e32 v18, 16, v58
	v_and_b32_e32 v19, 0xffff0000, v58
	v_pk_add_f32 v[28:29], v[54:55], v[88:89] op_sel_hi:[0,1]
	v_pk_mul_f32 v[18:19], v[28:29], v[18:19]
	v_pk_add_f32 v[28:29], v[54:55], v[90:91] op_sel_hi:[0,1]
	v_cvt_pk_bf16_f32 v30, v18, v19
	v_lshlrev_b32_e32 v18, 16, v59
	v_and_b32_e32 v19, 0xffff0000, v59
	v_pk_mul_f32 v[18:19], v[28:29], v[18:19]
	v_mov_b64_e32 v[28:29], v[116:117]
	v_cvt_pk_bf16_f32 v31, v18, v19
	v_cndmask_b32_e64 v18, v16, v30, s[12:13]
	v_cndmask_b32_e64 v19, v17, v31, s[12:13]
	ds_bpermute_b32 v55, v82, v19
	ds_bpermute_b32 v54, v82, v18
	s_waitcnt lgkmcnt(1)
; __device__ __forceinline__ float bflo(unsigned w) { return __uint_as_float(w << 16); }
; __device__ __forceinline__ float bfhi(unsigned w) { return __uint_as_float(w & 0xffff0000u); }
; __device__ __forceinline__ unsigned cvtpk_s(float lo, float hi) { f32x2_t v = {lo, hi}; bf16x2_t b = __builtin_convertvector(v, bf16x2_t); return __builtin_bit_cast(unsigned, b); }
; #define MFMA16(a, b, c) __builtin_amdgcn_mfma_f32_16x16x32_bf16((a), (b), (c), 0, 0, 0)
; template <int NMT> __device__ __forceinline__ void sg_unit(int chunk, int g, int cofs, const bf16_t* VST, const bf16_t* QU, bf16_t* OB, const float* stats, const float* lng, const float* lnb, const bf16_t* WSb, const float* bs, int lane_) {
;     ...
;     for (int nt = 0; nt < 8; ++nt) {
;         const int cur = nt & 1, nxt = cur ^ 1;
;         if (nt < 7) {
; #pragma unroll
;             for (int ks = 0; ks < 4; ++ks) wf[nxt][ks] = *(const bf16x8*)(wp0 + (size_t)(nt + 1) * 16 * 128 + ks * 32);
; #pragma unroll
;             for (int mt = 0; mt < NMT; ++mt) uu[nxt][mt] = *(const u32x2*)(QU + (size_t)(R0 + (nt + 1) * 16 + fr) * 1024 + 512 + ch0 + mt * 16 + 4 * fq);
;             bsv[nxt] = bs[g * 128 + (nt + 1) * 16 + fr];
;         }
;         f32x4 a[NMT];
; #pragma unroll
;         for (int mt = 0; mt < NMT; ++mt) a[mt] = z4;
; #pragma unroll
;         for (int ks = 0; ks < 4; ++ks)
; #pragma unroll
;             for (int mt = 0; mt < NMT; ++mt) a[mt] = MFMA16(af[mt][ks], wf[cur][ks], a[mt]);
;         const float bv = bsv[cur];
;         unsigned q[NMT][2];
; #pragma unroll
;         for (int mt = 0; mt < NMT; ++mt) { const u32x2 u0 = uu[cur][mt];
;             q[mt][0] = cvtpk_s(pg8::bflo(u0.x) * (a[mt][0] + bv), pg8::bfhi(u0.x) * (a[mt][1] + bv)); q[mt][1] = cvtpk_s(pg8::bflo(u0.y) * (a[mt][2] + bv), pg8::bfhi(u0.y) * (a[mt][3] + bv)); }
;         const size_t uo = (size_t)(R0 + nt * 16 + fr) * 1024 + 512 + ch0;
; #pragma unroll
;         for (int mp = 0; mp < NMT / 2; ++mp) { int co; const u32x4 w = pg8::quad_swap(q[2 * mp][0], q[2 * mp][1], q[2 * mp + 1][0], q[2 * mp + 1][1], fq, co); *(u32x4*)(OB + uo + mp * 32 + co) = w; }
	v_mov_b32_e32 v19, v55
	s_waitcnt lgkmcnt(0)
	v_mov_b32_e32 v18, v54
	s_and_saveexec_b64 s[52:53], s[10:11]
	v_mov_b64_e32 v[28:29], v[64:65]
	v_mov_b32_e32 v19, v31
	v_mov_b32_e32 v18, v30
	v_mov_b32_e32 v17, v55
	v_mov_b32_e32 v16, v54
	s_or_b64 exec, exec, s[52:53]
	v_lshl_add_u64 v[30:31], s[14:15], 0, v[52:53]
	s_waitcnt vmcnt(6)
	v_mfma_f32_16x16x32_bf16 v[74:77], v[0:3], v[40:43], 0
	v_lshl_add_u64 v[52:53], v[28:29], 1, v[30:31]
	v_or_b32_e32 v58, 64, v118
	v_ashrrev_i32_e32 v59, 31, v58
	v_mfma_f32_16x16x32_bf16 v[28:31], v[4:7], v[40:43], 0
	v_lshlrev_b64 v[58:59], 11, v[58:59]
	v_lshl_add_u64 v[70:71], s[26:27], 0, v[58:59]
	global_store_dwordx4 v[52:53], v[16:19], off offset:1024
	s_waitcnt vmcnt(6)
	v_mfma_f32_16x16x32_bf16 v[74:77], v[8:11], v[48:51], v[74:77]
	v_lshl_add_u64 v[70:71], v[70:71], 0, s[42:43]
	v_add_co_u32_e32 v16, vcc, 0x4000, v120
	v_mfma_f32_16x16x32_bf16 v[48:51], v[36:39], v[48:51], v[28:31]
	s_nop 0
	v_addc_co_u32_e32 v17, vcc, 0, v121, vcc
	global_load_dwordx4 v[52:55], v[16:17], off
	global_load_dwordx4 v[40:43], v[16:17], off offset:64
	s_waitcnt vmcnt(7)
	v_mfma_f32_16x16x32_bf16 v[84:87], v[44:47], v[32:35], v[74:77]
	global_load_dwordx4 v[28:31], v[16:17], off offset:128
	s_nop 0
	global_load_dwordx4 v[16:19], v[16:17], off offset:192
	s_waitcnt vmcnt(7)
	v_lshlrev_b32_e32 v76, 16, v80
	v_and_b32_e32 v77, 0xffff0000, v80
	v_mfma_f32_16x16x32_bf16 v[32:35], v[60:63], v[32:35], v[48:51]
	s_nop 2
	v_lshl_add_u64 v[48:49], v[116:117], 1, v[70:71]
	global_load_dwordx2 v[78:79], v[48:49], off offset:1024
	global_load_dwordx2 v[74:75], v[48:49], off offset:1056
	global_load_dword v70, v[66:67], off offset:256
	v_mfma_f32_16x16x32_bf16 v[48:51], v[20:23], v[24:27], v[84:87]
	v_mfma_f32_16x16x32_bf16 v[84:87], v[12:15], v[24:27], v[32:35]
	v_lshlrev_b32_e32 v26, 16, v81
	s_waitcnt vmcnt(8)
	s_nop 4
	v_pk_add_f32 v[24:25], v[68:69], v[48:49] op_sel_hi:[0,1]
	v_and_b32_e32 v27, 0xffff0000, v81
	v_pk_add_f32 v[32:33], v[68:69], v[50:51] op_sel_hi:[0,1]
	v_pk_mul_f32 v[24:25], v[24:25], v[76:77]
	v_pk_mul_f32 v[26:27], v[32:33], v[26:27]
	v_cvt_pk_bf16_f32 v24, v24, v25
	v_cvt_pk_bf16_f32 v25, v26, v27
	v_lshlrev_b32_e32 v26, 16, v72
	v_and_b32_e32 v27, 0xffff0000, v72
	v_pk_add_f32 v[32:33], v[68:69], v[84:85] op_sel_hi:[0,1]
	v_pk_mul_f32 v[26:27], v[32:33], v[26:27]
	v_pk_add_f32 v[32:33], v[68:69], v[86:87] op_sel_hi:[0,1]
	v_cvt_pk_bf16_f32 v34, v26, v27
	v_lshlrev_b32_e32 v26, 16, v73
	v_and_b32_e32 v27, 0xffff0000, v73
	v_pk_mul_f32 v[26:27], v[32:33], v[26:27]
	v_mov_b64_e32 v[32:33], v[116:117]
	v_cvt_pk_bf16_f32 v35, v26, v27
	v_cndmask_b32_e64 v26, v24, v34, s[12:13]
	v_cndmask_b32_e64 v27, v25, v35, s[12:13]
	ds_bpermute_b32 v49, v82, v27
	ds_bpermute_b32 v48, v82, v26
	s_waitcnt lgkmcnt(1)
	v_mov_b32_e32 v27, v49
	s_waitcnt lgkmcnt(0)
	v_mov_b32_e32 v26, v48
	s_and_saveexec_b64 s[52:53], s[10:11]
	v_mov_b64_e32 v[32:33], v[64:65]
	v_mov_b32_e32 v27, v35
	v_mov_b32_e32 v26, v34
	v_mov_b32_e32 v25, v49
	v_mov_b32_e32 v24, v48
	s_or_b64 exec, exec, s[52:53]
	v_lshl_add_u64 v[34:35], s[14:15], 0, v[56:57]
	s_waitcnt vmcnt(6)
	v_mfma_f32_16x16x32_bf16 v[48:51], v[0:3], v[52:55], 0
	v_lshl_add_u64 v[56:57], v[32:33], 1, v[34:35]
	global_store_dwordx4 v[56:57], v[24:27], off offset:1024
	v_or_b32_e32 v56, 0x50, v118
	v_mfma_f32_16x16x32_bf16 v[32:35], v[4:7], v[52:55], 0
	v_ashrrev_i32_e32 v57, 31, v56
	v_lshlrev_b64 v[68:69], 11, v[56:57]
	v_lshl_add_u64 v[56:57], s[26:27], 0, v[68:69]
	s_waitcnt vmcnt(6)
	v_mfma_f32_16x16x32_bf16 v[84:87], v[8:11], v[40:43], v[48:51]
	v_add_co_u32_e32 v24, vcc, 0x5000, v120
	v_lshl_add_u64 v[56:57], v[56:57], 0, s[42:43]
	v_mfma_f32_16x16x32_bf16 v[40:43], v[36:39], v[40:43], v[32:35]
	v_addc_co_u32_e32 v25, vcc, 0, v121, vcc
	global_load_dwordx4 v[52:55], v[24:25], off
	global_load_dwordx4 v[48:51], v[24:25], off offset:64
	s_waitcnt vmcnt(7)
	v_mfma_f32_16x16x32_bf16 v[84:87], v[44:47], v[28:31], v[84:87]
	global_load_dwordx4 v[32:35], v[24:25], off offset:128
	s_nop 0
	global_load_dwordx4 v[24:27], v[24:25], off offset:192
	v_mfma_f32_16x16x32_bf16 v[28:31], v[60:63], v[28:31], v[40:43]
	s_nop 2
	v_lshl_add_u64 v[40:41], v[116:117], 1, v[56:57]
	global_load_dwordx2 v[80:81], v[40:41], off offset:1024
	global_load_dwordx2 v[76:77], v[40:41], off offset:1056
	global_load_dword v72, v[66:67], off offset:320
	s_waitcnt vmcnt(11)
	v_mfma_f32_16x16x32_bf16 v[40:43], v[20:23], v[16:19], v[84:87]
	s_waitcnt vmcnt(10)
	v_lshlrev_b32_e32 v56, 16, v78
	v_and_b32_e32 v57, 0xffff0000, v78
	v_mfma_f32_16x16x32_bf16 v[84:87], v[12:15], v[16:19], v[28:31]
	v_lshlrev_b32_e32 v18, 16, v79
	s_waitcnt vmcnt(8)
	s_nop 1
	v_pk_add_f32 v[16:17], v[70:71], v[40:41] op_sel_hi:[0,1]
	v_and_b32_e32 v19, 0xffff0000, v79
	v_pk_add_f32 v[28:29], v[70:71], v[42:43] op_sel_hi:[0,1]
	v_pk_mul_f32 v[16:17], v[16:17], v[56:57]
	v_pk_mul_f32 v[18:19], v[28:29], v[18:19]
	v_cvt_pk_bf16_f32 v16, v16, v17
	v_cvt_pk_bf16_f32 v17, v18, v19
	v_lshlrev_b32_e32 v18, 16, v74
	v_and_b32_e32 v19, 0xffff0000, v74
	v_pk_add_f32 v[28:29], v[70:71], v[84:85] op_sel_hi:[0,1]
	v_pk_mul_f32 v[18:19], v[28:29], v[18:19]
	v_pk_add_f32 v[28:29], v[70:71], v[86:87] op_sel_hi:[0,1]
	v_cvt_pk_bf16_f32 v30, v18, v19
	v_lshlrev_b32_e32 v18, 16, v75
	v_and_b32_e32 v19, 0xffff0000, v75
	v_pk_mul_f32 v[18:19], v[28:29], v[18:19]
	v_mov_b64_e32 v[28:29], v[116:117]
	v_cvt_pk_bf16_f32 v31, v18, v19
	v_cndmask_b32_e64 v18, v16, v30, s[12:13]
	v_cndmask_b32_e64 v19, v17, v31, s[12:13]
	ds_bpermute_b32 v41, v82, v19
	ds_bpermute_b32 v40, v82, v18
	s_waitcnt lgkmcnt(1)
	v_mov_b32_e32 v19, v41
	s_waitcnt lgkmcnt(0)
; __device__ __forceinline__ float bflo(unsigned w) { return __uint_as_float(w << 16); }
; __device__ __forceinline__ float bfhi(unsigned w) { return __uint_as_float(w & 0xffff0000u); }
; __device__ __forceinline__ unsigned cvtpk_s(float lo, float hi) { f32x2_t v = {lo, hi}; bf16x2_t b = __builtin_convertvector(v, bf16x2_t); return __builtin_bit_cast(unsigned, b); }
; #define MFMA16(a, b, c) __builtin_amdgcn_mfma_f32_16x16x32_bf16((a), (b), (c), 0, 0, 0)
; template <int NMT> __device__ __forceinline__ void sg_unit(int chunk, int g, int cofs, const bf16_t* VST, const bf16_t* QU, bf16_t* OB, const float* stats, const float* lng, const float* lnb, const bf16_t* WSb, const float* bs, int lane_) {
;     ...
;     for (int nt = 0; nt < 8; ++nt) {
;         const int cur = nt & 1, nxt = cur ^ 1;
;         if (nt < 7) {
; #pragma unroll
;             for (int ks = 0; ks < 4; ++ks) wf[nxt][ks] = *(const bf16x8*)(wp0 + (size_t)(nt + 1) * 16 * 128 + ks * 32);
; #pragma unroll
;             for (int mt = 0; mt < NMT; ++mt) uu[nxt][mt] = *(const u32x2*)(QU + (size_t)(R0 + (nt + 1) * 16 + fr) * 1024 + 512 + ch0 + mt * 16 + 4 * fq);
;             bsv[nxt] = bs[g * 128 + (nt + 1) * 16 + fr];
;         }
;         f32x4 a[NMT];
; #pragma unroll
;         for (int mt = 0; mt < NMT; ++mt) a[mt] = z4;
; #pragma unroll
;         for (int ks = 0; ks < 4; ++ks)
; #pragma unroll
;             for (int mt = 0; mt < NMT; ++mt) a[mt] = MFMA16(af[mt][ks], wf[cur][ks], a[mt]);
;         const float bv = bsv[cur];
;         unsigned q[NMT][2];
; #pragma unroll
;         for (int mt = 0; mt < NMT; ++mt) { const u32x2 u0 = uu[cur][mt];
;             q[mt][0] = cvtpk_s(pg8::bflo(u0.x) * (a[mt][0] + bv), pg8::bfhi(u0.x) * (a[mt][1] + bv)); q[mt][1] = cvtpk_s(pg8::bflo(u0.y) * (a[mt][2] + bv), pg8::bfhi(u0.y) * (a[mt][3] + bv)); }
;         const size_t uo = (size_t)(R0 + nt * 16 + fr) * 1024 + 512 + ch0;
; #pragma unroll
;         for (int mp = 0; mp < NMT / 2; ++mp) { int co; const u32x4 w = pg8::quad_swap(q[2 * mp][0], q[2 * mp][1], q[2 * mp + 1][0], q[2 * mp + 1][1], fq, co); *(u32x4*)(OB + uo + mp * 32 + co) = w; }
	v_mov_b32_e32 v18, v40
	s_and_saveexec_b64 s[52:53], s[10:11]
	v_mov_b64_e32 v[28:29], v[64:65]
	v_mov_b32_e32 v19, v31
	v_mov_b32_e32 v18, v30
	v_mov_b32_e32 v17, v41
	v_mov_b32_e32 v16, v40
	s_or_b64 exec, exec, s[52:53]
	s_waitcnt vmcnt(6)
	v_mfma_f32_16x16x32_bf16 v[40:43], v[0:3], v[52:55], 0
	v_lshl_add_u64 v[30:31], s[14:15], 0, v[58:59]
	v_lshl_add_u64 v[56:57], v[28:29], 1, v[30:31]
	global_store_dwordx4 v[56:57], v[16:19], off offset:1024
	v_mfma_f32_16x16x32_bf16 v[28:31], v[4:7], v[52:55], 0
	v_or_b32_e32 v70, 0x60, v118
	v_ashrrev_i32_e32 v71, 31, v70
	v_add_co_u32_e32 v16, vcc, 0x6000, v120
	s_waitcnt vmcnt(6)
	v_mfma_f32_16x16x32_bf16 v[56:59], v[8:11], v[48:51], v[40:43]
	v_addc_co_u32_e32 v17, vcc, 0, v121, vcc
	global_load_dwordx4 v[52:55], v[16:17], off
	s_nop 0
	global_load_dwordx4 v[40:43], v[16:17], off offset:64
	v_mfma_f32_16x16x32_bf16 v[48:51], v[36:39], v[48:51], v[28:31]
	s_nop 2
	global_load_dwordx4 v[28:31], v[16:17], off offset:128
	s_nop 0
	global_load_dwordx4 v[16:19], v[16:17], off offset:192
	s_waitcnt vmcnt(7)
	v_lshlrev_b32_e32 v78, 16, v80
	v_and_b32_e32 v79, 0xffff0000, v80
	v_mfma_f32_16x16x32_bf16 v[84:87], v[44:47], v[32:35], v[56:59]
	s_nop 2
	v_lshlrev_b64 v[56:57], 11, v[70:71]
	v_lshl_add_u64 v[58:59], s[26:27], 0, v[56:57]
	v_lshl_add_u64 v[58:59], v[58:59], 0, s[42:43]
	v_mfma_f32_16x16x32_bf16 v[32:35], v[60:63], v[32:35], v[48:51]
	s_nop 2
	v_lshl_add_u64 v[48:49], v[116:117], 1, v[58:59]
	global_load_dwordx2 v[74:75], v[48:49], off offset:1024
	global_load_dwordx2 v[70:71], v[48:49], off offset:1056
	global_load_dword v58, v[66:67], off offset:384
	v_mfma_f32_16x16x32_bf16 v[48:51], v[20:23], v[24:27], v[84:87]
	v_mfma_f32_16x16x32_bf16 v[84:87], v[12:15], v[24:27], v[32:35]
	v_lshlrev_b32_e32 v26, 16, v81
	s_waitcnt vmcnt(8)
	s_nop 4
	v_pk_add_f32 v[24:25], v[72:73], v[48:49] op_sel_hi:[0,1]
	v_and_b32_e32 v27, 0xffff0000, v81
	v_pk_add_f32 v[32:33], v[72:73], v[50:51] op_sel_hi:[0,1]
	v_pk_mul_f32 v[24:25], v[24:25], v[78:79]
	v_pk_mul_f32 v[26:27], v[32:33], v[26:27]
	v_cvt_pk_bf16_f32 v24, v24, v25
	v_cvt_pk_bf16_f32 v25, v26, v27
	v_lshlrev_b32_e32 v26, 16, v76
	v_and_b32_e32 v27, 0xffff0000, v76
	v_pk_add_f32 v[32:33], v[72:73], v[84:85] op_sel_hi:[0,1]
	v_pk_mul_f32 v[26:27], v[32:33], v[26:27]
	v_pk_add_f32 v[32:33], v[72:73], v[86:87] op_sel_hi:[0,1]
	v_cvt_pk_bf16_f32 v34, v26, v27
	v_lshlrev_b32_e32 v26, 16, v77
	v_and_b32_e32 v27, 0xffff0000, v77
	v_pk_mul_f32 v[26:27], v[32:33], v[26:27]
	v_mov_b64_e32 v[32:33], v[116:117]
	v_cvt_pk_bf16_f32 v35, v26, v27
	v_cndmask_b32_e64 v26, v24, v34, s[12:13]
	v_cndmask_b32_e64 v27, v25, v35, s[12:13]
	ds_bpermute_b32 v49, v82, v27
	ds_bpermute_b32 v48, v82, v26
	s_waitcnt lgkmcnt(1)
	v_mov_b32_e32 v27, v49
	s_waitcnt lgkmcnt(0)
	v_mov_b32_e32 v26, v48
	s_and_saveexec_b64 s[52:53], s[10:11]
	v_mov_b64_e32 v[32:33], v[64:65]
	v_mov_b32_e32 v27, v35
	v_mov_b32_e32 v26, v34
	v_mov_b32_e32 v25, v49
	v_mov_b32_e32 v24, v48
	s_or_b64 exec, exec, s[52:53]
	v_lshl_add_u64 v[34:35], s[14:15], 0, v[68:69]
	s_waitcnt vmcnt(6)
	v_mfma_f32_16x16x32_bf16 v[48:51], v[0:3], v[52:55], 0
	v_lshl_add_u64 v[68:69], v[32:33], 1, v[34:35]
	global_store_dwordx4 v[68:69], v[24:27], off offset:1024
	s_waitcnt vmcnt(3)
; __device__ __forceinline__ float bflo(unsigned w) { return __uint_as_float(w << 16); }
; __device__ __forceinline__ float bfhi(unsigned w) { return __uint_as_float(w & 0xffff0000u); }
; __device__ __forceinline__ unsigned cvtpk_s(float lo, float hi) { f32x2_t v = {lo, hi}; bf16x2_t b = __builtin_convertvector(v, bf16x2_t); return __builtin_bit_cast(unsigned, b); }
; #define MFMA16(a, b, c) __builtin_amdgcn_mfma_f32_16x16x32_bf16((a), (b), (c), 0, 0, 0)
; template <int NMT> __device__ __forceinline__ void sg_unit(int chunk, int g, int cofs, const bf16_t* VST, const bf16_t* QU, bf16_t* OB, const float* stats, const float* lng, const float* lnb, const bf16_t* WSb, const float* bs, int lane_) {
;     ...
;     for (int nt = 0; nt < 8; ++nt) {
;         const int cur = nt & 1, nxt = cur ^ 1;
;         if (nt < 7) {
; #pragma unroll
;             for (int ks = 0; ks < 4; ++ks) wf[nxt][ks] = *(const bf16x8*)(wp0 + (size_t)(nt + 1) * 16 * 128 + ks * 32);
; #pragma unroll
;             for (int mt = 0; mt < NMT; ++mt) uu[nxt][mt] = *(const u32x2*)(QU + (size_t)(R0 + (nt + 1) * 16 + fr) * 1024 + 512 + ch0 + mt * 16 + 4 * fq);
;             bsv[nxt] = bs[g * 128 + (nt + 1) * 16 + fr];
;         }
;         f32x4 a[NMT];
; #pragma unroll
;         for (int mt = 0; mt < NMT; ++mt) a[mt] = z4;
; #pragma unroll
;         for (int ks = 0; ks < 4; ++ks)
; #pragma unroll
;             for (int mt = 0; mt < NMT; ++mt) a[mt] = MFMA16(af[mt][ks], wf[cur][ks], a[mt]);
;         const float bv = bsv[cur];
;         unsigned q[NMT][2];
; #pragma unroll
;         for (int mt = 0; mt < NMT; ++mt) { const u32x2 u0 = uu[cur][mt];
;             q[mt][0] = cvtpk_s(pg8::bflo(u0.x) * (a[mt][0] + bv), pg8::bfhi(u0.x) * (a[mt][1] + bv)); q[mt][1] = cvtpk_s(pg8::bflo(u0.y) * (a[mt][2] + bv), pg8::bfhi(u0.y) * (a[mt][3] + bv)); }
;         const size_t uo = (size_t)(R0 + nt * 16 + fr) * 1024 + 512 + ch0;
; #pragma unroll
;         for (int mp = 0; mp < NMT / 2; ++mp) { int co; const u32x4 w = pg8::quad_swap(q[2 * mp][0], q[2 * mp][1], q[2 * mp + 1][0], q[2 * mp + 1][1], fq, co); *(u32x4*)(OB + uo + mp * 32 + co) = w; }
	v_lshlrev_b32_e32 v72, 16, v74
	v_mfma_f32_16x16x32_bf16 v[32:35], v[4:7], v[52:55], 0
	v_add_co_u32_e32 v24, vcc, 0x7000, v120
	v_and_b32_e32 v73, 0xffff0000, v74
	v_mfma_f32_16x16x32_bf16 v[76:79], v[8:11], v[40:43], v[48:51]
	v_addc_co_u32_e32 v25, vcc, 0, v121, vcc
	global_load_dwordx4 v[52:55], v[24:25], off
	s_nop 0
	global_load_dwordx4 v[48:51], v[24:25], off offset:64
	v_mfma_f32_16x16x32_bf16 v[84:87], v[36:39], v[40:43], v[32:35]
	v_or_b32_e32 v40, 0x70, v118
	v_ashrrev_i32_e32 v41, 31, v40
	v_lshlrev_b64 v[40:41], 11, v[40:41]
	v_lshl_add_u64 v[42:43], s[26:27], 0, v[40:41]
	v_lshl_add_u64 v[42:43], v[42:43], 0, s[42:43]
	v_mfma_f32_16x16x32_bf16 v[76:79], v[44:47], v[28:31], v[76:79]
	global_load_dwordx4 v[32:35], v[24:25], off offset:128
	s_nop 0
	global_load_dwordx4 v[24:27], v[24:25], off offset:192
	v_mfma_f32_16x16x32_bf16 v[84:87], v[60:63], v[28:31], v[84:87]
	v_lshl_add_u64 v[28:29], v[116:117], 1, v[42:43]
	global_load_dwordx2 v[42:43], v[28:29], off offset:1024
	global_load_dwordx2 v[30:31], v[28:29], off offset:1056
	s_nop 0
	global_load_dword v28, v[66:67], off offset:448
	v_mfma_f32_16x16x32_bf16 v[76:79], v[20:23], v[16:19], v[76:79]
	v_mfma_f32_16x16x32_bf16 v[66:69], v[12:15], v[16:19], v[84:87]
	v_lshlrev_b32_e32 v18, 16, v75
	s_waitcnt vmcnt(8)
	s_nop 4
	v_pk_add_f32 v[16:17], v[58:59], v[76:77] op_sel_hi:[0,1]
	v_pk_mul_f32 v[16:17], v[16:17], v[72:73]
	v_and_b32_e32 v19, 0xffff0000, v75
	v_pk_add_f32 v[72:73], v[58:59], v[78:79] op_sel_hi:[0,1]
	v_pk_mul_f32 v[18:19], v[72:73], v[18:19]
	v_cvt_pk_bf16_f32 v16, v16, v17
	v_cvt_pk_bf16_f32 v17, v18, v19
	v_lshlrev_b32_e32 v18, 16, v70
	v_and_b32_e32 v19, 0xffff0000, v70
	v_pk_add_f32 v[66:67], v[58:59], v[66:67] op_sel_hi:[0,1]
	v_pk_mul_f32 v[18:19], v[66:67], v[18:19]
	v_pk_add_f32 v[58:59], v[58:59], v[68:69] op_sel_hi:[0,1]
	v_cvt_pk_bf16_f32 v29, v18, v19
	v_lshlrev_b32_e32 v18, 16, v71
	v_and_b32_e32 v19, 0xffff0000, v71
	v_pk_mul_f32 v[18:19], v[58:59], v[18:19]
	v_mov_b64_e32 v[58:59], v[116:117]
	v_cvt_pk_bf16_f32 v66, v18, v19
	v_cndmask_b32_e64 v18, v16, v29, s[12:13]
	v_cndmask_b32_e64 v19, v17, v66, s[12:13]
	ds_bpermute_b32 v68, v82, v19
	ds_bpermute_b32 v67, v82, v18
	s_waitcnt lgkmcnt(1)
	v_mov_b32_e32 v19, v68
	s_waitcnt lgkmcnt(0)
	v_mov_b32_e32 v18, v67
	s_and_saveexec_b64 s[52:53], s[10:11]
	v_mov_b64_e32 v[58:59], v[64:65]
	v_mov_b32_e32 v19, v66
	v_mov_b32_e32 v18, v29
	v_mov_b32_e32 v17, v68
	v_mov_b32_e32 v16, v67
	s_or_b64 exec, exec, s[52:53]
	s_waitcnt vmcnt(6)
	v_mfma_f32_16x16x32_bf16 v[0:3], v[0:3], v[52:55], 0
	s_waitcnt vmcnt(5)
	v_mfma_f32_16x16x32_bf16 v[0:3], v[8:11], v[48:51], v[0:3]
	s_waitcnt vmcnt(2)
	v_lshlrev_b32_e32 v8, 16, v42
	v_and_b32_e32 v9, 0xffff0000, v42
	v_mfma_f32_16x16x32_bf16 v[0:3], v[44:47], v[32:35], v[0:3]
	v_mfma_f32_16x16x32_bf16 v[4:7], v[4:7], v[52:55], 0
	v_mfma_f32_16x16x32_bf16 v[0:3], v[20:23], v[24:27], v[0:3]
	v_mfma_f32_16x16x32_bf16 v[4:7], v[36:39], v[48:51], v[4:7]
	s_waitcnt vmcnt(0)
	s_nop 5
	v_pk_add_f32 v[0:1], v[28:29], v[0:1] op_sel_hi:[0,1]
	v_pk_mul_f32 v[0:1], v[0:1], v[8:9]
	v_lshlrev_b32_e32 v8, 16, v43
	v_and_b32_e32 v9, 0xffff0000, v43
	v_pk_add_f32 v[2:3], v[28:29], v[2:3] op_sel_hi:[0,1]
	v_pk_mul_f32 v[8:9], v[2:3], v[8:9]
	v_mfma_f32_16x16x32_bf16 v[2:5], v[60:63], v[32:35], v[4:7]
	v_cvt_pk_bf16_f32 v0, v0, v1
	v_cvt_pk_bf16_f32 v1, v8, v9
	v_lshlrev_b32_e32 v8, 16, v30
	v_mfma_f32_16x16x32_bf16 v[4:7], v[12:15], v[24:27], v[2:5]
	v_and_b32_e32 v9, 0xffff0000, v30
	s_nop 6
	v_pk_add_f32 v[2:3], v[28:29], v[4:5] op_sel_hi:[0,1]
	v_pk_mul_f32 v[2:3], v[2:3], v[8:9]
	v_pk_add_f32 v[6:7], v[28:29], v[6:7] op_sel_hi:[0,1]
	v_cvt_pk_bf16_f32 v4, v2, v3
	v_lshlrev_b32_e32 v2, 16, v31
	v_and_b32_e32 v3, 0xffff0000, v31
	v_pk_mul_f32 v[2:3], v[6:7], v[2:3]
	s_nop 0
	v_cvt_pk_bf16_f32 v5, v2, v3
	v_cndmask_b32_e64 v2, v0, v4, s[12:13]
	v_cndmask_b32_e64 v3, v1, v5, s[12:13]
	ds_bpermute_b32 v7, v82, v3
	ds_bpermute_b32 v6, v82, v2
	v_lshl_add_u64 v[2:3], s[14:15], 0, v[56:57]
	v_lshl_add_u64 v[2:3], v[58:59], 1, v[2:3]
	global_store_dwordx4 v[2:3], v[16:19], off offset:1024
	s_waitcnt lgkmcnt(1)
	v_mov_b32_e32 v3, v7
	s_waitcnt lgkmcnt(0)
	v_mov_b32_e32 v2, v6
	s_and_saveexec_b64 s[12:13], s[10:11]
	s_cbranch_execz .LBB0_965
	v_mov_b64_e32 v[116:117], v[64:65]
	v_mov_b32_e32 v3, v5
	v_mov_b32_e32 v2, v4
	v_mov_b32_e32 v1, v7
	v_mov_b32_e32 v0, v6
	s_branch .LBB0_965

;     __device__ __forceinline__ void operator()(const f32x4 (&acc)[2][2][4][2], const Unit& u, int wr, int wc, int fr, int fq) const {
;         const int cond = u.pm < 64 ? 0 : (u.pm < 128 ? 1 : 2);
;         const float* gate = gate_l + cond * 9216;
;         const int col0 = u.pn * BM + wc * 32 + 4 * fq;
;         f32x4 gv[2][2];
; #pragma unroll
;         for (int bj = 0; bj < 2; ++bj)
; #pragma unroll
;             for (int n = 0; n < 2; ++n) gv[bj][n] = *(const f32x4*)(gate + col0 + bj * HALF + n * 16) * coef;
; #pragma unroll
;         for (int ai = 0; ai < 2; ++ai)
; #pragma unroll
;             for (int m = 0; m < 4; ++m) {
;                 const int row = u.pm * BM + ai * HALF + wr * 64 + m * 16 + fr;
;                 const float* s = row < MX_ ? src_main + (size_t)row * D_ : src_ctx + (size_t)(row - MX_) * D_;
;                 float* d = row < MX_ ? dst_main + (size_t)row * D_ : dst_ctx + (size_t)(row - MX_) * D_;
; #pragma unroll
;                 for (int bj = 0; bj < 2; ++bj)
; #pragma unroll
;                     for (int n = 0; n < 2; ++n) { const int off = col0 + bj * HALF + n * 16; const f32x4 xo = *(const f32x4*)(s + off); *(f32x4*)(d + off) = xo + gv[bj][n] * acc[ai][bj][m][n]; }
; __device__ __forceinline__ void final_norm(float* out, const float* g, int gw, int NGW, int lane) {
;     ...
;         float ss = 0.f;
; #pragma unroll
;         for (int j = 0; j < 4; ++j) ss += (v[j][0] * v[j][0] + v[j][1] * v[j][1]) + (v[j][2] * v[j][2] + v[j][3] * v[j][3]);
;         const float rstd = 1.0f / sqrtf(wave_sum(ss) * (1.0f / D) + EPS);
; #pragma unroll
;         for (int j = 0; j < 4; ++j) *(f32x4*)(out + (size_t)row * D + 4 * lane + 256 * j) = v[j] * rstd * gg[j];
.LBB0_2544:
	s_cmpk_lt_i32 s57, 0x80
	s_cselect_b32 s18, s54, 0x4800
	s_cmp_gt_i32 s57, 63
	s_cselect_b32 s18, s18, 0
	s_lshl_b32 s18, s18, 2
	s_add_u32 s18, s46, s18
	s_addc_u32 s19, s47, 0
	s_load_dwordx2 s[74:75], s[0:1], 0xa8
	s_load_dwordx2 s[76:77], s[0:1], 0xb8
	v_lshl_add_u32 v156, s57, 8, v158
	v_lshl_or_b32 v157, s58, 8, v160
	v_lshlrev_b32_e32 v200, 2, v157
	v_lshl_add_u32 v201, v156, 12, v200
	global_load_dwordx4 v[196:199], v200, s[18:19]
	global_load_dwordx4 v[208:211], v200, s[18:19] offset:64
	global_load_dwordx4 v[212:215], v200, s[18:19] offset:512
	global_load_dwordx4 v[216:219], v200, s[18:19] offset:576
	v_add_u32_e32 v205, 0x10000, v201
	v_add_u32_e32 v207, 0x20000, v201
	v_add_u32_e32 v252, 0x30000, v201
	v_add_u32_e32 v220, 0x80000, v201
	v_add_u32_e32 v221, 0x90000, v201
	v_add_u32_e32 v222, 0xa0000, v201
	v_add_u32_e32 v223, 0xb0000, v201
	global_load_dwordx4 v[140:143], v201, s[8:9]
	global_load_dwordx4 v[144:147], v201, s[8:9] offset:64
	global_load_dwordx4 v[148:151], v201, s[8:9] offset:512
	global_load_dwordx4 v[152:155], v201, s[8:9] offset:576
	global_load_dwordx4 v[164:167], v205, s[8:9]
	global_load_dwordx4 v[168:171], v205, s[8:9] offset:64
	global_load_dwordx4 v[172:175], v205, s[8:9] offset:512
	global_load_dwordx4 v[176:179], v205, s[8:9] offset:576
	global_load_dwordx4 v[180:183], v207, s[8:9]
	global_load_dwordx4 v[184:187], v207, s[8:9] offset:64
	global_load_dwordx4 v[188:191], v207, s[8:9] offset:512
	global_load_dwordx4 v[192:195], v207, s[8:9] offset:576
	s_waitcnt vmcnt(12)
	v_pk_mul_f32 v[196:197], v[196:197], 0.5 op_sel_hi:[1,0]
	v_pk_mul_f32 v[198:199], v[198:199], 0.5 op_sel_hi:[1,0]
	v_pk_mul_f32 v[208:209], v[208:209], 0.5 op_sel_hi:[1,0]
	v_pk_mul_f32 v[210:211], v[210:211], 0.5 op_sel_hi:[1,0]
	v_pk_mul_f32 v[212:213], v[212:213], 0.5 op_sel_hi:[1,0]
	v_pk_mul_f32 v[214:215], v[214:215], 0.5 op_sel_hi:[1,0]
	v_pk_mul_f32 v[216:217], v[216:217], 0.5 op_sel_hi:[1,0]
	v_pk_mul_f32 v[218:219], v[218:219], 0.5 op_sel_hi:[1,0]
	s_waitcnt vmcnt(11)
	v_pk_fma_f32 v[124:125], v[124:125], v[196:197], v[140:141]
	v_pk_fma_f32 v[126:127], v[126:127], v[198:199], v[142:143]
	v_mul_f32_e32 v224, v124, v124
	v_fmac_f32_e32 v224, v125, v125
	v_fmac_f32_e32 v224, v126, v126
	v_fmac_f32_e32 v224, v127, v127
	s_waitcnt vmcnt(10)
	v_pk_fma_f32 v[120:121], v[120:121], v[208:209], v[144:145]
	v_pk_fma_f32 v[122:123], v[122:123], v[210:211], v[146:147]
	v_fmac_f32_e32 v224, v120, v120
	v_fmac_f32_e32 v224, v121, v121
	v_fmac_f32_e32 v224, v122, v122
	v_fmac_f32_e32 v224, v123, v123
	s_waitcnt vmcnt(9)
	v_pk_fma_f32 v[116:117], v[116:117], v[212:213], v[148:149]
	v_pk_fma_f32 v[118:119], v[118:119], v[214:215], v[150:151]
	v_fmac_f32_e32 v224, v116, v116
	v_fmac_f32_e32 v224, v117, v117
	v_fmac_f32_e32 v224, v118, v118
	v_fmac_f32_e32 v224, v119, v119
	s_waitcnt vmcnt(8)
	v_pk_fma_f32 v[112:113], v[112:113], v[216:217], v[152:153]
	v_pk_fma_f32 v[114:115], v[114:115], v[218:219], v[154:155]
	v_fmac_f32_e32 v224, v112, v112
	v_fmac_f32_e32 v224, v113, v113
	v_fmac_f32_e32 v224, v114, v114
	v_fmac_f32_e32 v224, v115, v115
	global_load_dwordx4 v[140:143], v252, s[8:9]
	global_load_dwordx4 v[144:147], v252, s[8:9] offset:64
	global_load_dwordx4 v[148:151], v252, s[8:9] offset:512
	global_load_dwordx4 v[152:155], v252, s[8:9] offset:576
	s_waitcnt vmcnt(11)
	v_pk_fma_f32 v[108:109], v[108:109], v[196:197], v[164:165]
	v_pk_fma_f32 v[110:111], v[110:111], v[198:199], v[166:167]
	v_mul_f32_e32 v225, v108, v108
	v_fmac_f32_e32 v225, v109, v109
	v_fmac_f32_e32 v225, v110, v110
	v_fmac_f32_e32 v225, v111, v111
	s_waitcnt vmcnt(10)
	v_pk_fma_f32 v[104:105], v[104:105], v[208:209], v[168:169]
	v_pk_fma_f32 v[106:107], v[106:107], v[210:211], v[170:171]
	v_fmac_f32_e32 v225, v104, v104
	v_fmac_f32_e32 v225, v105, v105
	v_fmac_f32_e32 v225, v106, v106
	v_fmac_f32_e32 v225, v107, v107
	s_waitcnt vmcnt(9)
	v_pk_fma_f32 v[100:101], v[100:101], v[212:213], v[172:173]
	v_pk_fma_f32 v[102:103], v[102:103], v[214:215], v[174:175]
	v_fmac_f32_e32 v225, v100, v100
	v_fmac_f32_e32 v225, v101, v101
	v_fmac_f32_e32 v225, v102, v102
	v_fmac_f32_e32 v225, v103, v103
	s_waitcnt vmcnt(8)
	v_pk_fma_f32 v[96:97], v[96:97], v[216:217], v[176:177]
	v_pk_fma_f32 v[98:99], v[98:99], v[218:219], v[178:179]
	v_fmac_f32_e32 v225, v96, v96
	v_fmac_f32_e32 v225, v97, v97
	v_fmac_f32_e32 v225, v98, v98
	v_fmac_f32_e32 v225, v99, v99
	global_load_dwordx4 v[164:167], v220, s[8:9]
	global_load_dwordx4 v[168:171], v220, s[8:9] offset:64
	global_load_dwordx4 v[172:175], v220, s[8:9] offset:512
	global_load_dwordx4 v[176:179], v220, s[8:9] offset:576
	s_waitcnt vmcnt(11)
	v_pk_fma_f32 v[92:93], v[92:93], v[196:197], v[180:181]
	v_pk_fma_f32 v[94:95], v[94:95], v[198:199], v[182:183]
	v_mul_f32_e32 v226, v92, v92
	v_fmac_f32_e32 v226, v93, v93
	v_fmac_f32_e32 v226, v94, v94
	v_fmac_f32_e32 v226, v95, v95
	s_waitcnt vmcnt(10)
	v_pk_fma_f32 v[88:89], v[88:89], v[208:209], v[184:185]
	v_pk_fma_f32 v[90:91], v[90:91], v[210:211], v[186:187]
	v_fmac_f32_e32 v226, v88, v88
	v_fmac_f32_e32 v226, v89, v89
	v_fmac_f32_e32 v226, v90, v90
	v_fmac_f32_e32 v226, v91, v91
	s_waitcnt vmcnt(9)
	v_pk_fma_f32 v[84:85], v[84:85], v[212:213], v[188:189]
	v_pk_fma_f32 v[86:87], v[86:87], v[214:215], v[190:191]
	v_fmac_f32_e32 v226, v84, v84
	v_fmac_f32_e32 v226, v85, v85
	v_fmac_f32_e32 v226, v86, v86
	v_fmac_f32_e32 v226, v87, v87
	s_waitcnt vmcnt(8)
;     __device__ __forceinline__ void operator()(const f32x4 (&acc)[2][2][4][2], const Unit& u, int wr, int wc, int fr, int fq) const {
;     ...
;         for (int ai = 0; ai < 2; ++ai)
; #pragma unroll
;             for (int m = 0; m < 4; ++m) {
;                 const int row = u.pm * BM + ai * HALF + wr * 64 + m * 16 + fr;
;                 const float* s = row < MX_ ? src_main + (size_t)row * D_ : src_ctx + (size_t)(row - MX_) * D_;
;                 float* d = row < MX_ ? dst_main + (size_t)row * D_ : dst_ctx + (size_t)(row - MX_) * D_;
; #pragma unroll
;                 for (int bj = 0; bj < 2; ++bj)
; #pragma unroll
;                     for (int n = 0; n < 2; ++n) { const int off = col0 + bj * HALF + n * 16; const f32x4 xo = *(const f32x4*)(s + off); *(f32x4*)(d + off) = xo + gv[bj][n] * acc[ai][bj][m][n]; }
; __device__ __forceinline__ void final_norm(float* out, const float* g, int gw, int NGW, int lane) {
;     ...
;         float ss = 0.f;
; #pragma unroll
;         for (int j = 0; j < 4; ++j) ss += (v[j][0] * v[j][0] + v[j][1] * v[j][1]) + (v[j][2] * v[j][2] + v[j][3] * v[j][3]);
	v_pk_fma_f32 v[80:81], v[80:81], v[216:217], v[192:193]
	v_pk_fma_f32 v[82:83], v[82:83], v[218:219], v[194:195]
	v_fmac_f32_e32 v226, v80, v80
	v_fmac_f32_e32 v226, v81, v81
	v_fmac_f32_e32 v226, v82, v82
	v_fmac_f32_e32 v226, v83, v83
	global_load_dwordx4 v[180:183], v221, s[8:9]
	global_load_dwordx4 v[184:187], v221, s[8:9] offset:64
	global_load_dwordx4 v[188:191], v221, s[8:9] offset:512
	global_load_dwordx4 v[192:195], v221, s[8:9] offset:576
	s_waitcnt vmcnt(11)
	v_pk_fma_f32 v[76:77], v[76:77], v[196:197], v[140:141]
	v_pk_fma_f32 v[78:79], v[78:79], v[198:199], v[142:143]
	v_mul_f32_e32 v227, v76, v76
	v_fmac_f32_e32 v227, v77, v77
	v_fmac_f32_e32 v227, v78, v78
	v_fmac_f32_e32 v227, v79, v79
	s_waitcnt vmcnt(10)
	v_pk_fma_f32 v[72:73], v[72:73], v[208:209], v[144:145]
	v_pk_fma_f32 v[74:75], v[74:75], v[210:211], v[146:147]
	v_fmac_f32_e32 v227, v72, v72
	v_fmac_f32_e32 v227, v73, v73
	v_fmac_f32_e32 v227, v74, v74
	v_fmac_f32_e32 v227, v75, v75
	s_waitcnt vmcnt(9)
	v_pk_fma_f32 v[68:69], v[68:69], v[212:213], v[148:149]
	v_pk_fma_f32 v[70:71], v[70:71], v[214:215], v[150:151]
	v_fmac_f32_e32 v227, v68, v68
	v_fmac_f32_e32 v227, v69, v69
	v_fmac_f32_e32 v227, v70, v70
	v_fmac_f32_e32 v227, v71, v71
	s_waitcnt vmcnt(8)
	v_pk_fma_f32 v[64:65], v[64:65], v[216:217], v[152:153]
	v_pk_fma_f32 v[66:67], v[66:67], v[218:219], v[154:155]
	v_fmac_f32_e32 v227, v64, v64
	v_fmac_f32_e32 v227, v65, v65
	v_fmac_f32_e32 v227, v66, v66
	v_fmac_f32_e32 v227, v67, v67
	global_load_dwordx4 v[140:143], v222, s[8:9]
	global_load_dwordx4 v[144:147], v222, s[8:9] offset:64
	global_load_dwordx4 v[148:151], v222, s[8:9] offset:512
	global_load_dwordx4 v[152:155], v222, s[8:9] offset:576
	s_waitcnt vmcnt(11)
	v_pk_fma_f32 v[60:61], v[60:61], v[196:197], v[164:165]
	v_pk_fma_f32 v[62:63], v[62:63], v[198:199], v[166:167]
	v_mul_f32_e32 v228, v60, v60
	v_fmac_f32_e32 v228, v61, v61
	v_fmac_f32_e32 v228, v62, v62
	v_fmac_f32_e32 v228, v63, v63
	s_waitcnt vmcnt(10)
	v_pk_fma_f32 v[56:57], v[56:57], v[208:209], v[168:169]
	v_pk_fma_f32 v[58:59], v[58:59], v[210:211], v[170:171]
	v_fmac_f32_e32 v228, v56, v56
	v_fmac_f32_e32 v228, v57, v57
	v_fmac_f32_e32 v228, v58, v58
	v_fmac_f32_e32 v228, v59, v59
	s_waitcnt vmcnt(9)
	v_pk_fma_f32 v[52:53], v[52:53], v[212:213], v[172:173]
	v_pk_fma_f32 v[54:55], v[54:55], v[214:215], v[174:175]
	v_fmac_f32_e32 v228, v52, v52
	v_fmac_f32_e32 v228, v53, v53
	v_fmac_f32_e32 v228, v54, v54
	v_fmac_f32_e32 v228, v55, v55
	s_waitcnt vmcnt(8)
	v_pk_fma_f32 v[48:49], v[48:49], v[216:217], v[176:177]
	v_pk_fma_f32 v[50:51], v[50:51], v[218:219], v[178:179]
	v_fmac_f32_e32 v228, v48, v48
	v_fmac_f32_e32 v228, v49, v49
	v_fmac_f32_e32 v228, v50, v50
	v_fmac_f32_e32 v228, v51, v51
	global_load_dwordx4 v[164:167], v223, s[8:9]
	global_load_dwordx4 v[168:171], v223, s[8:9] offset:64
	global_load_dwordx4 v[172:175], v223, s[8:9] offset:512
	global_load_dwordx4 v[176:179], v223, s[8:9] offset:576
	s_waitcnt vmcnt(11)
	v_pk_fma_f32 v[44:45], v[44:45], v[196:197], v[180:181]
	v_pk_fma_f32 v[46:47], v[46:47], v[198:199], v[182:183]
	v_mul_f32_e32 v229, v44, v44
	v_fmac_f32_e32 v229, v45, v45
	v_fmac_f32_e32 v229, v46, v46
	v_fmac_f32_e32 v229, v47, v47
	s_waitcnt vmcnt(10)
	v_pk_fma_f32 v[40:41], v[40:41], v[208:209], v[184:185]
	v_pk_fma_f32 v[42:43], v[42:43], v[210:211], v[186:187]
	v_fmac_f32_e32 v229, v40, v40
	v_fmac_f32_e32 v229, v41, v41
	v_fmac_f32_e32 v229, v42, v42
	v_fmac_f32_e32 v229, v43, v43
	s_waitcnt vmcnt(9)
	v_pk_fma_f32 v[36:37], v[36:37], v[212:213], v[188:189]
	v_pk_fma_f32 v[38:39], v[38:39], v[214:215], v[190:191]
	v_fmac_f32_e32 v229, v36, v36
	v_fmac_f32_e32 v229, v37, v37
	v_fmac_f32_e32 v229, v38, v38
	v_fmac_f32_e32 v229, v39, v39
	s_waitcnt vmcnt(8)
	v_pk_fma_f32 v[32:33], v[32:33], v[216:217], v[192:193]
	v_pk_fma_f32 v[34:35], v[34:35], v[218:219], v[194:195]
	v_fmac_f32_e32 v229, v32, v32
	v_fmac_f32_e32 v229, v33, v33
	v_fmac_f32_e32 v229, v34, v34
	v_fmac_f32_e32 v229, v35, v35
	s_waitcnt vmcnt(7)
	v_pk_fma_f32 v[28:29], v[28:29], v[196:197], v[140:141]
	v_pk_fma_f32 v[30:31], v[30:31], v[198:199], v[142:143]
	v_mul_f32_e32 v230, v28, v28
	v_fmac_f32_e32 v230, v29, v29
	v_fmac_f32_e32 v230, v30, v30
	v_fmac_f32_e32 v230, v31, v31
	s_waitcnt vmcnt(6)
	v_pk_fma_f32 v[24:25], v[24:25], v[208:209], v[144:145]
	v_pk_fma_f32 v[26:27], v[26:27], v[210:211], v[146:147]
	v_fmac_f32_e32 v230, v24, v24
	v_fmac_f32_e32 v230, v25, v25
	v_fmac_f32_e32 v230, v26, v26
	v_fmac_f32_e32 v230, v27, v27
	s_waitcnt vmcnt(5)
	v_pk_fma_f32 v[20:21], v[20:21], v[212:213], v[148:149]
	v_pk_fma_f32 v[22:23], v[22:23], v[214:215], v[150:151]
	v_fmac_f32_e32 v230, v20, v20
	v_fmac_f32_e32 v230, v21, v21
	v_fmac_f32_e32 v230, v22, v22
	v_fmac_f32_e32 v230, v23, v23
	s_waitcnt vmcnt(4)
	v_pk_fma_f32 v[16:17], v[16:17], v[216:217], v[152:153]
	v_pk_fma_f32 v[18:19], v[18:19], v[218:219], v[154:155]
	v_fmac_f32_e32 v230, v16, v16
	v_fmac_f32_e32 v230, v17, v17
	v_fmac_f32_e32 v230, v18, v18
	v_fmac_f32_e32 v230, v19, v19
	s_waitcnt vmcnt(3)
	v_pk_fma_f32 v[12:13], v[12:13], v[196:197], v[164:165]
	v_pk_fma_f32 v[14:15], v[14:15], v[198:199], v[166:167]
	v_mul_f32_e32 v231, v12, v12
	v_fmac_f32_e32 v231, v13, v13
	v_fmac_f32_e32 v231, v14, v14
	v_fmac_f32_e32 v231, v15, v15
	s_waitcnt vmcnt(2)
	v_pk_fma_f32 v[8:9], v[8:9], v[208:209], v[168:169]
	v_pk_fma_f32 v[10:11], v[10:11], v[210:211], v[170:171]
	v_fmac_f32_e32 v231, v8, v8
	v_fmac_f32_e32 v231, v9, v9
	v_fmac_f32_e32 v231, v10, v10
	v_fmac_f32_e32 v231, v11, v11
	s_waitcnt vmcnt(1)
;     __device__ __forceinline__ void operator()(const f32x4 (&acc)[2][2][4][2], const Unit& u, int wr, int wc, int fr, int fq) const {
;     ...
;                     for (int n = 0; n < 2; ++n) { const int off = col0 + bj * HALF + n * 16; const f32x4 xo = *(const f32x4*)(s + off); *(f32x4*)(d + off) = xo + gv[bj][n] * acc[ai][bj][m][n]; }
; __device__ __forceinline__ void final_norm(float* out, const float* g, int gw, int NGW, int lane) {
;     ...
;         const float rstd = 1.0f / sqrtf(wave_sum(ss) * (1.0f / D) + EPS);
; #pragma unroll
;         for (int j = 0; j < 4; ++j) *(f32x4*)(out + (size_t)row * D + 4 * lane + 256 * j) = v[j] * rstd * gg[j];
	v_pk_fma_f32 v[4:5], v[4:5], v[212:213], v[172:173]
	v_pk_fma_f32 v[6:7], v[6:7], v[214:215], v[174:175]
	v_fmac_f32_e32 v231, v4, v4
	v_fmac_f32_e32 v231, v5, v5
	v_fmac_f32_e32 v231, v6, v6
	v_fmac_f32_e32 v231, v7, v7
	s_waitcnt vmcnt(0)
	v_pk_fma_f32 v[0:1], v[0:1], v[216:217], v[176:177]
	v_pk_fma_f32 v[2:3], v[2:3], v[218:219], v[178:179]
	v_fmac_f32_e32 v231, v0, v0
	v_fmac_f32_e32 v231, v1, v1
	v_fmac_f32_e32 v231, v2, v2
	v_fmac_f32_e32 v231, v3, v3
	v_mbcnt_lo_u32_b32 v232, -1, 0
	v_mbcnt_hi_u32_b32 v232, -1, v232
	v_xor_b32_e32 v233, 16, v232
	v_xor_b32_e32 v234, 32, v232
	v_lshlrev_b32_e32 v233, 2, v233
	v_lshlrev_b32_e32 v234, 2, v234
	s_waitcnt lgkmcnt(0)
	ds_bpermute_b32 v140, v233, v224
	ds_bpermute_b32 v141, v233, v225
	ds_bpermute_b32 v142, v233, v226
	ds_bpermute_b32 v143, v233, v227
	ds_bpermute_b32 v144, v233, v228
	ds_bpermute_b32 v145, v233, v229
	ds_bpermute_b32 v146, v233, v230
	ds_bpermute_b32 v147, v233, v231
	s_waitcnt lgkmcnt(7)
	v_add_f32_e32 v224, v224, v140
	s_waitcnt lgkmcnt(6)
	v_add_f32_e32 v225, v225, v141
	s_waitcnt lgkmcnt(5)
	v_add_f32_e32 v226, v226, v142
	s_waitcnt lgkmcnt(4)
	v_add_f32_e32 v227, v227, v143
	s_waitcnt lgkmcnt(3)
	v_add_f32_e32 v228, v228, v144
	s_waitcnt lgkmcnt(2)
	v_add_f32_e32 v229, v229, v145
	s_waitcnt lgkmcnt(1)
	v_add_f32_e32 v230, v230, v146
	s_waitcnt lgkmcnt(0)
	v_add_f32_e32 v231, v231, v147
	ds_bpermute_b32 v140, v234, v224
	ds_bpermute_b32 v141, v234, v225
	ds_bpermute_b32 v142, v234, v226
	ds_bpermute_b32 v143, v234, v227
	ds_bpermute_b32 v144, v234, v228
	ds_bpermute_b32 v145, v234, v229
	ds_bpermute_b32 v146, v234, v230
	ds_bpermute_b32 v147, v234, v231
	s_waitcnt lgkmcnt(7)
	v_add_f32_e32 v224, v224, v140
	s_waitcnt lgkmcnt(6)
	v_add_f32_e32 v225, v225, v141
	s_waitcnt lgkmcnt(5)
	v_add_f32_e32 v226, v226, v142
	s_waitcnt lgkmcnt(4)
	v_add_f32_e32 v227, v227, v143
	s_waitcnt lgkmcnt(3)
	v_add_f32_e32 v228, v228, v144
	s_waitcnt lgkmcnt(2)
	v_add_f32_e32 v229, v229, v145
	s_waitcnt lgkmcnt(1)
	v_add_f32_e32 v230, v230, v146
	s_waitcnt lgkmcnt(0)
	v_add_f32_e32 v231, v231, v147
	v_lshlrev_b32_e32 v235, 2, v156
	s_add_u32 s76, s76, 0xd0000
	s_addc_u32 s77, s77, 0
	s_lshl_b32 s83, s57, 6
	s_add_u32 s78, s76, s83
	s_addc_u32 s79, s77, 0
	s_add_u32 s78, s78, 0x20000
	s_addc_u32 s79, s79, 0
	s_mov_b64 s[80:81], exec
	s_mov_b64 exec, 0xffff
	global_atomic_add_f32 v235, v224, s[76:77]
	global_atomic_add_f32 v235, v225, s[76:77] offset:64
	global_atomic_add_f32 v235, v226, s[76:77] offset:128
	global_atomic_add_f32 v235, v227, s[76:77] offset:192
	global_atomic_add_f32 v235, v228, s[76:77] offset:512
	global_atomic_add_f32 v235, v229, s[76:77] offset:576
	global_atomic_add_f32 v235, v230, s[76:77] offset:640
	global_atomic_add_f32 v235, v231, s[76:77] offset:704
	s_mov_b64 exec, s[80:81]
	s_waitcnt vmcnt(0)
	s_barrier
	v_readfirstlane_b32 s83, v206
	v_mov_b32_e32 v236, 0
	v_mov_b32_e32 v237, 1
	s_cmp_lg_u32 s83, 0
	s_cbranch_scc1 .Lfn_wait_done
	s_mov_b64 exec, 1
	global_atomic_add v236, v237, s[78:79]
	s_mov_b32 s82, 0
.Lfn_spin:
	global_load_dword v238, v236, s[78:79] sc1
	s_waitcnt vmcnt(0)
	v_readfirstlane_b32 s83, v238
	s_cmp_ge_u32 s83, 4
	s_cbranch_scc1 .Lfn_spin_done
	s_sleep 1
	s_add_u32 s82, s82, 1
	s_cmp_lt_u32 s82, 0x4000
	s_cbranch_scc1 .Lfn_spin
.Lfn_spin_done:
	s_mov_b64 exec, s[80:81]
.Lfn_wait_done:
	s_barrier
	global_load_dword v144, v235, s[76:77] sc1
	global_load_dword v145, v235, s[76:77] offset:64 sc1
	global_load_dword v146, v235, s[76:77] offset:128 sc1
	global_load_dword v147, v235, s[76:77] offset:192 sc1
	global_load_dword v148, v235, s[76:77] offset:512 sc1
	global_load_dword v149, v235, s[76:77] offset:576 sc1
	global_load_dword v150, v235, s[76:77] offset:640 sc1
	global_load_dword v151, v235, s[76:77] offset:704 sc1
	global_load_dwordx4 v[196:199], v200, s[74:75]
	global_load_dwordx4 v[208:211], v200, s[74:75] offset:64
	global_load_dwordx4 v[212:215], v200, s[74:75] offset:512
	global_load_dwordx4 v[216:219], v200, s[74:75] offset:576
	v_mov_b32_e32 v232, 0x358637bd
	s_waitcnt vmcnt(0)
	v_fmamk_f32 v144, v144, 0x3a800000, v232
	v_fmamk_f32 v145, v145, 0x3a800000, v232
	v_fmamk_f32 v146, v146, 0x3a800000, v232
	v_fmamk_f32 v147, v147, 0x3a800000, v232
	v_fmamk_f32 v148, v148, 0x3a800000, v232
	v_fmamk_f32 v149, v149, 0x3a800000, v232
	v_fmamk_f32 v150, v150, 0x3a800000, v232
	v_fmamk_f32 v151, v151, 0x3a800000, v232
	v_rsq_f32_e32 v144, v144
	v_rsq_f32_e32 v145, v145
	v_rsq_f32_e32 v146, v146
	v_rsq_f32_e32 v147, v147
	v_rsq_f32_e32 v148, v148
	v_rsq_f32_e32 v149, v149
	v_rsq_f32_e32 v150, v150
	v_rsq_f32_e32 v151, v151
	s_nop 0
	v_mul_f32_e32 v124, v124, v144
	v_mul_f32_e32 v125, v125, v144
	v_pk_mul_f32 v[124:125], v[124:125], v[196:197]
	v_mul_f32_e32 v126, v126, v144
	v_mul_f32_e32 v127, v127, v144
	v_pk_mul_f32 v[126:127], v[126:127], v[198:199]
	v_mul_f32_e32 v120, v120, v144
	v_mul_f32_e32 v121, v121, v144
	v_pk_mul_f32 v[120:121], v[120:121], v[208:209]
	v_mul_f32_e32 v122, v122, v144
	v_mul_f32_e32 v123, v123, v144
	v_pk_mul_f32 v[122:123], v[122:123], v[210:211]
	v_mul_f32_e32 v116, v116, v144
	v_mul_f32_e32 v117, v117, v144
	v_pk_mul_f32 v[116:117], v[116:117], v[212:213]
	v_mul_f32_e32 v118, v118, v144
	v_mul_f32_e32 v119, v119, v144
	v_pk_mul_f32 v[118:119], v[118:119], v[214:215]
	v_mul_f32_e32 v112, v112, v144
	v_mul_f32_e32 v113, v113, v144
	v_pk_mul_f32 v[112:113], v[112:113], v[216:217]
	v_mul_f32_e32 v114, v114, v144
	v_mul_f32_e32 v115, v115, v144
	v_pk_mul_f32 v[114:115], v[114:115], v[218:219]
	global_store_dwordx4 v201, v[124:127], s[8:9]
	global_store_dwordx4 v201, v[120:123], s[8:9] offset:64
; __device__ __forceinline__ void final_norm(float* out, const float* g, int gw, int NGW, int lane) {
;     ...
;         for (int j = 0; j < 4; ++j) *(f32x4*)(out + (size_t)row * D + 4 * lane + 256 * j) = v[j] * rstd * gg[j];
	global_store_dwordx4 v201, v[116:119], s[8:9] offset:512
	global_store_dwordx4 v201, v[112:115], s[8:9] offset:576
	v_mul_f32_e32 v108, v108, v145
	v_mul_f32_e32 v109, v109, v145
	v_pk_mul_f32 v[108:109], v[108:109], v[196:197]
	v_mul_f32_e32 v110, v110, v145
	v_mul_f32_e32 v111, v111, v145
	v_pk_mul_f32 v[110:111], v[110:111], v[198:199]
	v_mul_f32_e32 v104, v104, v145
	v_mul_f32_e32 v105, v105, v145
	v_pk_mul_f32 v[104:105], v[104:105], v[208:209]
	v_mul_f32_e32 v106, v106, v145
	v_mul_f32_e32 v107, v107, v145
	v_pk_mul_f32 v[106:107], v[106:107], v[210:211]
	v_mul_f32_e32 v100, v100, v145
	v_mul_f32_e32 v101, v101, v145
	v_pk_mul_f32 v[100:101], v[100:101], v[212:213]
	v_mul_f32_e32 v102, v102, v145
	v_mul_f32_e32 v103, v103, v145
	v_pk_mul_f32 v[102:103], v[102:103], v[214:215]
	v_mul_f32_e32 v96, v96, v145
	v_mul_f32_e32 v97, v97, v145
	v_pk_mul_f32 v[96:97], v[96:97], v[216:217]
	v_mul_f32_e32 v98, v98, v145
	v_mul_f32_e32 v99, v99, v145
	v_pk_mul_f32 v[98:99], v[98:99], v[218:219]
	global_store_dwordx4 v205, v[108:111], s[8:9]
	global_store_dwordx4 v205, v[104:107], s[8:9] offset:64
	global_store_dwordx4 v205, v[100:103], s[8:9] offset:512
	global_store_dwordx4 v205, v[96:99], s[8:9] offset:576
	v_mul_f32_e32 v92, v92, v146
	v_mul_f32_e32 v93, v93, v146
	v_pk_mul_f32 v[92:93], v[92:93], v[196:197]
	v_mul_f32_e32 v94, v94, v146
	v_mul_f32_e32 v95, v95, v146
	v_pk_mul_f32 v[94:95], v[94:95], v[198:199]
	v_mul_f32_e32 v88, v88, v146
	v_mul_f32_e32 v89, v89, v146
	v_pk_mul_f32 v[88:89], v[88:89], v[208:209]
	v_mul_f32_e32 v90, v90, v146
	v_mul_f32_e32 v91, v91, v146
	v_pk_mul_f32 v[90:91], v[90:91], v[210:211]
	v_mul_f32_e32 v84, v84, v146
	v_mul_f32_e32 v85, v85, v146
	v_pk_mul_f32 v[84:85], v[84:85], v[212:213]
	v_mul_f32_e32 v86, v86, v146
	v_mul_f32_e32 v87, v87, v146
	v_pk_mul_f32 v[86:87], v[86:87], v[214:215]
	v_mul_f32_e32 v80, v80, v146
	v_mul_f32_e32 v81, v81, v146
	v_pk_mul_f32 v[80:81], v[80:81], v[216:217]
	v_mul_f32_e32 v82, v82, v146
	v_mul_f32_e32 v83, v83, v146
	v_pk_mul_f32 v[82:83], v[82:83], v[218:219]
	global_store_dwordx4 v207, v[92:95], s[8:9]
	global_store_dwordx4 v207, v[88:91], s[8:9] offset:64
	global_store_dwordx4 v207, v[84:87], s[8:9] offset:512
	global_store_dwordx4 v207, v[80:83], s[8:9] offset:576
	v_mul_f32_e32 v76, v76, v147
	v_mul_f32_e32 v77, v77, v147
	v_pk_mul_f32 v[76:77], v[76:77], v[196:197]
	v_mul_f32_e32 v78, v78, v147
	v_mul_f32_e32 v79, v79, v147
	v_pk_mul_f32 v[78:79], v[78:79], v[198:199]
	v_mul_f32_e32 v72, v72, v147
	v_mul_f32_e32 v73, v73, v147
	v_pk_mul_f32 v[72:73], v[72:73], v[208:209]
	v_mul_f32_e32 v74, v74, v147
	v_mul_f32_e32 v75, v75, v147
	v_pk_mul_f32 v[74:75], v[74:75], v[210:211]
	v_mul_f32_e32 v68, v68, v147
	v_mul_f32_e32 v69, v69, v147
	v_pk_mul_f32 v[68:69], v[68:69], v[212:213]
	v_mul_f32_e32 v70, v70, v147
	v_mul_f32_e32 v71, v71, v147
	v_pk_mul_f32 v[70:71], v[70:71], v[214:215]
	v_mul_f32_e32 v64, v64, v147
	v_mul_f32_e32 v65, v65, v147
	v_pk_mul_f32 v[64:65], v[64:65], v[216:217]
	v_mul_f32_e32 v66, v66, v147
	v_mul_f32_e32 v67, v67, v147
	v_pk_mul_f32 v[66:67], v[66:67], v[218:219]
	global_store_dwordx4 v252, v[76:79], s[8:9]
	global_store_dwordx4 v252, v[72:75], s[8:9] offset:64
	global_store_dwordx4 v252, v[68:71], s[8:9] offset:512
	global_store_dwordx4 v252, v[64:67], s[8:9] offset:576
	v_mul_f32_e32 v60, v60, v148
	v_mul_f32_e32 v61, v61, v148
	v_pk_mul_f32 v[60:61], v[60:61], v[196:197]
	v_mul_f32_e32 v62, v62, v148
	v_mul_f32_e32 v63, v63, v148
	v_pk_mul_f32 v[62:63], v[62:63], v[198:199]
	v_mul_f32_e32 v56, v56, v148
	v_mul_f32_e32 v57, v57, v148
	v_pk_mul_f32 v[56:57], v[56:57], v[208:209]
	v_mul_f32_e32 v58, v58, v148
	v_mul_f32_e32 v59, v59, v148
	v_pk_mul_f32 v[58:59], v[58:59], v[210:211]
	v_mul_f32_e32 v52, v52, v148
	v_mul_f32_e32 v53, v53, v148
	v_pk_mul_f32 v[52:53], v[52:53], v[212:213]
; #define PG8_BAR __builtin_amdgcn_s_barrier()
;     ...
;     if constexpr (!ALIGN_EPI) { if (wr == 0) PG8_BAR; }
;     PG8_BAR;
; __device__ __forceinline__ void final_norm(float* out, const float* g, int gw, int NGW, int lane) {
;     ...
;         for (int j = 0; j < 4; ++j) *(f32x4*)(out + (size_t)row * D + 4 * lane + 256 * j) = v[j] * rstd * gg[j];
	v_mul_f32_e32 v54, v54, v148
	v_mul_f32_e32 v55, v55, v148
	v_pk_mul_f32 v[54:55], v[54:55], v[214:215]
	v_mul_f32_e32 v48, v48, v148
	v_mul_f32_e32 v49, v49, v148
	v_pk_mul_f32 v[48:49], v[48:49], v[216:217]
	v_mul_f32_e32 v50, v50, v148
	v_mul_f32_e32 v51, v51, v148
	v_pk_mul_f32 v[50:51], v[50:51], v[218:219]
	global_store_dwordx4 v220, v[60:63], s[8:9]
	global_store_dwordx4 v220, v[56:59], s[8:9] offset:64
	global_store_dwordx4 v220, v[52:55], s[8:9] offset:512
	global_store_dwordx4 v220, v[48:51], s[8:9] offset:576
	v_mul_f32_e32 v44, v44, v149
	v_mul_f32_e32 v45, v45, v149
	v_pk_mul_f32 v[44:45], v[44:45], v[196:197]
	v_mul_f32_e32 v46, v46, v149
	v_mul_f32_e32 v47, v47, v149
	v_pk_mul_f32 v[46:47], v[46:47], v[198:199]
	v_mul_f32_e32 v40, v40, v149
	v_mul_f32_e32 v41, v41, v149
	v_pk_mul_f32 v[40:41], v[40:41], v[208:209]
	v_mul_f32_e32 v42, v42, v149
	v_mul_f32_e32 v43, v43, v149
	v_pk_mul_f32 v[42:43], v[42:43], v[210:211]
	v_mul_f32_e32 v36, v36, v149
	v_mul_f32_e32 v37, v37, v149
	v_pk_mul_f32 v[36:37], v[36:37], v[212:213]
	v_mul_f32_e32 v38, v38, v149
	v_mul_f32_e32 v39, v39, v149
	v_pk_mul_f32 v[38:39], v[38:39], v[214:215]
	v_mul_f32_e32 v32, v32, v149
	v_mul_f32_e32 v33, v33, v149
	v_pk_mul_f32 v[32:33], v[32:33], v[216:217]
	v_mul_f32_e32 v34, v34, v149
	v_mul_f32_e32 v35, v35, v149
	v_pk_mul_f32 v[34:35], v[34:35], v[218:219]
	global_store_dwordx4 v221, v[44:47], s[8:9]
	global_store_dwordx4 v221, v[40:43], s[8:9] offset:64
	global_store_dwordx4 v221, v[36:39], s[8:9] offset:512
	global_store_dwordx4 v221, v[32:35], s[8:9] offset:576
	v_mul_f32_e32 v28, v28, v150
	v_mul_f32_e32 v29, v29, v150
	v_pk_mul_f32 v[28:29], v[28:29], v[196:197]
	v_mul_f32_e32 v30, v30, v150
	v_mul_f32_e32 v31, v31, v150
	v_pk_mul_f32 v[30:31], v[30:31], v[198:199]
	v_mul_f32_e32 v24, v24, v150
	v_mul_f32_e32 v25, v25, v150
	v_pk_mul_f32 v[24:25], v[24:25], v[208:209]
	v_mul_f32_e32 v26, v26, v150
	v_mul_f32_e32 v27, v27, v150
	v_pk_mul_f32 v[26:27], v[26:27], v[210:211]
	v_mul_f32_e32 v20, v20, v150
	v_mul_f32_e32 v21, v21, v150
	v_pk_mul_f32 v[20:21], v[20:21], v[212:213]
	v_mul_f32_e32 v22, v22, v150
	v_mul_f32_e32 v23, v23, v150
	v_pk_mul_f32 v[22:23], v[22:23], v[214:215]
	v_mul_f32_e32 v16, v16, v150
	v_mul_f32_e32 v17, v17, v150
	v_pk_mul_f32 v[16:17], v[16:17], v[216:217]
	v_mul_f32_e32 v18, v18, v150
	v_mul_f32_e32 v19, v19, v150
	v_pk_mul_f32 v[18:19], v[18:19], v[218:219]
	global_store_dwordx4 v222, v[28:31], s[8:9]
	global_store_dwordx4 v222, v[24:27], s[8:9] offset:64
	global_store_dwordx4 v222, v[20:23], s[8:9] offset:512
	global_store_dwordx4 v222, v[16:19], s[8:9] offset:576
	v_mul_f32_e32 v12, v12, v151
	v_mul_f32_e32 v13, v13, v151
	v_pk_mul_f32 v[12:13], v[12:13], v[196:197]
	v_mul_f32_e32 v14, v14, v151
	v_mul_f32_e32 v15, v15, v151
	v_pk_mul_f32 v[14:15], v[14:15], v[198:199]
	v_mul_f32_e32 v8, v8, v151
	v_mul_f32_e32 v9, v9, v151
	v_pk_mul_f32 v[8:9], v[8:9], v[208:209]
	v_mul_f32_e32 v10, v10, v151
	v_mul_f32_e32 v11, v11, v151
	v_pk_mul_f32 v[10:11], v[10:11], v[210:211]
	v_mul_f32_e32 v4, v4, v151
	v_mul_f32_e32 v5, v5, v151
	v_pk_mul_f32 v[4:5], v[4:5], v[212:213]
	v_mul_f32_e32 v6, v6, v151
	v_mul_f32_e32 v7, v7, v151
	v_pk_mul_f32 v[6:7], v[6:7], v[214:215]
	v_mul_f32_e32 v0, v0, v151
	v_mul_f32_e32 v1, v1, v151
	v_pk_mul_f32 v[0:1], v[0:1], v[216:217]
	v_mul_f32_e32 v2, v2, v151
	v_mul_f32_e32 v3, v3, v151
	v_pk_mul_f32 v[2:3], v[2:3], v[218:219]
	global_store_dwordx4 v223, v[12:15], s[8:9]
	global_store_dwordx4 v223, v[8:11], s[8:9] offset:64
	global_store_dwordx4 v223, v[4:7], s[8:9] offset:512
	global_store_dwordx4 v223, v[0:3], s[8:9] offset:576
	s_and_b64 vcc, exec, s[4:5]
	s_mov_b64 s[4:5], -1
	s_cbranch_vccnz .LBB0_2529
	s_andn2_b64 vcc, exec, s[10:11]
	s_cbranch_vccnz .LBB0_2528
	s_barrier
	s_branch .LBB0_2528
.LBB0_2547:
	s_waitcnt vmcnt(0)
	s_barrier
.LBB0_2548:
	s_endpgm

; __global__ void __launch_bounds__(NTHREADS, 2) mega_fwd(Args a) {
	.amdhsa_kernel _Z8mega_fwd4Args
		.amdhsa_group_segment_fixed_size 0
		.amdhsa_private_segment_fixed_size 0
		.amdhsa_kernarg_size 448
		.amdhsa_user_sgpr_count 2
		.amdhsa_user_sgpr_dispatch_ptr 0
		.amdhsa_user_sgpr_queue_ptr 0
		.amdhsa_user_sgpr_kernarg_segment_ptr 1
		.amdhsa_user_sgpr_dispatch_id 0
		.amdhsa_user_sgpr_kernarg_preload_length 0
		.amdhsa_user_sgpr_kernarg_preload_offset 0
		.amdhsa_user_sgpr_private_segment_size 0
		.amdhsa_uses_dynamic_stack 0
		.amdhsa_enable_private_segment 0
		.amdhsa_system_sgpr_workgroup_id_x 1
		.amdhsa_system_sgpr_workgroup_id_y 0
		.amdhsa_system_sgpr_workgroup_id_z 0
		.amdhsa_system_sgpr_workgroup_info 0
		.amdhsa_system_vgpr_workitem_id 2
		.amdhsa_next_free_vgpr 253
		.amdhsa_next_free_sgpr 101
		.amdhsa_accum_offset 256
		.amdhsa_reserve_vcc 1
		.amdhsa_float_round_mode_32 0
		.amdhsa_float_round_mode_16_64 0
		.amdhsa_float_denorm_mode_32 3
		.amdhsa_float_denorm_mode_16_64 3
		.amdhsa_dx10_clamp 1
		.amdhsa_ieee_mode 1
		.amdhsa_fp16_overflow 0
		.amdhsa_tg_split 0
		.amdhsa_exception_fp_ieee_invalid_op 0
		.amdhsa_exception_fp_denorm_src 0
		.amdhsa_exception_fp_ieee_div_zero 0
		.amdhsa_exception_fp_ieee_overflow 0
		.amdhsa_exception_fp_ieee_underflow 0
		.amdhsa_exception_fp_ieee_inexact 0
		.amdhsa_exception_int_div_zero 0
	.end_amdhsa_kernel

; __global__ void __launch_bounds__(NTHREADS, 2) mega_fwd(Args a) {
amdhsa.kernels:
  - .agpr_count:     0
    .args:
      - .offset:         0
        .size:           192
        .value_kind:     by_value
      - .offset:         192
        .size:           4
        .value_kind:     hidden_block_count_x
      - .offset:         196
        .size:           4
        .value_kind:     hidden_block_count_y
      - .offset:         200
        .size:           4
        .value_kind:     hidden_block_count_z
      - .offset:         204
        .size:           2
        .value_kind:     hidden_group_size_x
      - .offset:         206
        .size:           2
        .value_kind:     hidden_group_size_y
      - .offset:         208
        .size:           2
        .value_kind:     hidden_group_size_z
      - .offset:         210
        .size:           2
        .value_kind:     hidden_remainder_x
      - .offset:         212
        .size:           2
        .value_kind:     hidden_remainder_y
      - .offset:         214
        .size:           2
        .value_kind:     hidden_remainder_z
      - .offset:         232
        .size:           8
        .value_kind:     hidden_global_offset_x
      - .offset:         240
        .size:           8
        .value_kind:     hidden_global_offset_y
      - .offset:         248
        .size:           8
        .value_kind:     hidden_global_offset_z
      - .offset:         256
        .size:           2
        .value_kind:     hidden_grid_dims
      - .offset:         280
        .size:           8
        .value_kind:     hidden_multigrid_sync_arg
      - .offset:         312
        .size:           4
        .value_kind:     hidden_dynamic_lds_size
    .group_segment_fixed_size: 0
    .kernarg_segment_align: 8
    .kernarg_segment_size: 448
    .language:       OpenCL C
    .language_version:
      - 2
      - 0
    .max_flat_workgroup_size: 512
    .name:           _Z8mega_fwd4Args
    .private_segment_fixed_size: 0
    .sgpr_count:     107
    .sgpr_spill_count: 9
    .symbol:         _Z8mega_fwd4Args.kd
    .uniform_work_group_size: 1
    .uses_dynamic_stack: false
    .vgpr_count:     253
    .vgpr_spill_count: 0
    .wavefront_size: 64
